# norm phases A-D: wave-wide sum of squares via permlane32/16 swaps + DPP row mirrors/quad permutes (no LDS round trips) instead of six serialized ds_bpermute steps
# baseline (speedup 1.0000x reference)
.LBB0_198:
	s_or_b64 exec, exec, s[0:1]
	s_add_u32 s0, s90, 0xb171900
	s_addc_u32 s1, s91, 0
	v_writelane_b32 v250, s0, 19
	v_lshrrev_b32_e32 v174, 6, v128
	v_lshl_add_u32 v148, s33, 2, v174
	v_writelane_b32 v250, s1, 20
	s_movk_i32 s0, 0x3000
	v_mbcnt_lo_u32_b32 v182, -1, 0
	s_waitcnt lgkmcnt(0)
	s_barrier
	v_cmp_gt_i32_e64 s[0:1], s0, v148
	s_mov_b64 s[2:3], exec
	s_nop 0
	v_writelane_b32 v250, s0, 21
	s_nop 1
	v_writelane_b32 v250, s1, 22
	s_and_b64 s[0:1], s[2:3], s[0:1]
	s_mov_b64 exec, s[0:1]
	s_cbranch_execz .LBB0_205
	s_waitcnt vmcnt(5)
	v_mbcnt_hi_u32_b32 v0, -1, v182
	v_and_b32_e32 v2, 64, v0
	v_add_u32_e32 v2, 64, v2
	v_xor_b32_e32 v3, 32, v0
	v_cmp_lt_i32_e32 vcc, v3, v2
	s_waitcnt vmcnt(4)
	v_and_b32_e32 v6, 0xfc, v149
	v_readlane_b32 s12, v250, 3
	v_cndmask_b32_e32 v3, v0, v3, vcc
	v_lshlrev_b32_e32 v18, 2, v3
	v_xor_b32_e32 v3, 16, v0
	v_cmp_lt_i32_e32 vcc, v3, v2
	v_mov_b32_e32 v1, 0
	v_readlane_b32 s20, v250, 11
	v_cndmask_b32_e32 v3, v0, v3, vcc
	v_lshlrev_b32_e32 v19, 2, v3
	v_xor_b32_e32 v3, 8, v0
	v_cmp_lt_i32_e32 vcc, v3, v2
	v_readlane_b32 s21, v250, 12
	v_readlane_b32 s0, v250, 19
	v_cndmask_b32_e32 v3, v0, v3, vcc
	v_lshlrev_b32_e32 v20, 2, v3
	v_xor_b32_e32 v3, 4, v0
	v_cmp_lt_i32_e32 vcc, v3, v2
	v_readlane_b32 s13, v250, 4
	s_waitcnt vmcnt(3)
	v_or_b32_e32 v8, 0x100, v6
	v_cndmask_b32_e32 v3, v0, v3, vcc
	v_lshlrev_b32_e32 v21, 2, v3
	v_xor_b32_e32 v3, 2, v0
	v_cmp_lt_i32_e32 vcc, v3, v2
	v_or_b32_e32 v10, 0x200, v6
	s_waitcnt vmcnt(2)
	v_or_b32_e32 v12, 0x300, v6
	v_cndmask_b32_e32 v3, v0, v3, vcc
	v_lshlrev_b32_e32 v22, 2, v3
	v_xor_b32_e32 v3, 1, v0
	v_cmp_lt_i32_e32 vcc, v3, v2
	v_readlane_b32 s1, v250, 20
	s_lshl_b32 s8, s92, 2
	v_cndmask_b32_e32 v0, v0, v3, vcc
	v_lshlrev_b32_e32 v23, 2, v0
	v_lshlrev_b32_e32 v0, 2, v6
	v_lshl_add_u64 v[2:3], s[20:21], 0, v[0:1]
	v_lshlrev_b32_e32 v0, 1, v6
	v_lshl_add_u64 v[4:5], s[0:1], 0, v[0:1]
	s_mov_b64 s[4:5], 0
	s_movk_i32 s9, 0x2000
	s_movk_i32 s10, 0x1fff
	v_lshlrev_b32_e32 v6, 2, v6
	v_mov_b32_e32 v7, v1
	s_movk_i32 s11, 0x1800
	s_mov_b64 s[6:7], 0x1000
	v_lshlrev_b32_e32 v8, 2, v8
	v_mov_b32_e32 v9, v1
	v_lshlrev_b32_e32 v10, 2, v10
	v_mov_b32_e32 v11, v1
	v_lshlrev_b32_e32 v12, 2, v12
	v_mov_b32_e32 v13, v1
	v_mov_b32_e32 v24, 0x358637bd
	s_mov_b32 s12, 0x800000
	s_movk_i32 s13, 0x2fff
	v_mov_b32_e32 v14, v148
	v_readlane_b32 s14, v250, 5
	v_readlane_b32 s15, v250, 6
	v_readlane_b32 s16, v250, 7
	v_readlane_b32 s17, v250, 8
	v_readlane_b32 s18, v250, 9
	v_readlane_b32 s19, v250, 10
	v_readlane_b32 s22, v250, 13
	v_readlane_b32 s23, v250, 14
	v_readlane_b32 s24, v250, 15
	v_readlane_b32 s25, v250, 16
	v_readlane_b32 s26, v250, 17
	v_readlane_b32 s27, v250, 18
	v_mbcnt_lo_u32_b32 v80, -1, 0
	v_mbcnt_hi_u32_b32 v80, -1, v80
	v_lshlrev_b32_e32 v96, 4, v80
	v_lshlrev_b32_e32 v97, 3, v80
	v_xor_b32_e32 v98, 32, v80
	v_lshlrev_b32_e32 v98, 2, v98
	v_xor_b32_e32 v99, 16, v80
	v_lshlrev_b32_e32 v99, 2, v99
	v_xor_b32_e32 v100, 8, v80
	v_lshlrev_b32_e32 v100, 2, v100
	v_xor_b32_e32 v101, 4, v80
	v_lshlrev_b32_e32 v101, 2, v101
	v_xor_b32_e32 v102, 2, v80
	v_lshlrev_b32_e32 v102, 2, v102
	v_xor_b32_e32 v103, 1, v80
	v_lshlrev_b32_e32 v103, 2, v103
	v_mov_b32_e32 v104, 0x358637bd
	v_mov_b32_e32 v107, 0
	v_readlane_b32 s100, v250, 11
	v_readlane_b32 s101, v250, 12
	s_nop 5
	global_load_dwordx4 v[32:35], v96, s[100:101] offset:0
	global_load_dwordx4 v[36:39], v96, s[100:101] offset:1024
	global_load_dwordx4 v[40:43], v96, s[100:101] offset:2048
	global_load_dwordx4 v[44:47], v96, s[100:101] offset:3072
	v_readfirstlane_b32 s98, v148
	s_nop 3
	s_lshl_b32 s99, s98, 12
	s_sub_u32 vcc_lo, s99, 0x2000000
	s_cmp_lt_u32 s98, 0x2000
	s_cselect_b32 s99, s99, vcc_lo
	s_cselect_b32 s100, s72, s74
	s_cselect_b32 s101, s73, s75
	s_add_u32 s100, s100, s99
	s_addc_u32 s101, s101, 0
	global_load_dwordx4 v[0:3], v96, s[100:101] offset:0
	global_load_dwordx4 v[4:7], v96, s[100:101] offset:1024
	global_load_dwordx4 v[8:11], v96, s[100:101] offset:2048
	global_load_dwordx4 v[12:15], v96, s[100:101] offset:3072
	s_sub_u32 s99, s98, 0x2000
	s_lshr_b32 s99, s99, 11
	s_add_u32 s99, s99, 1
	s_cmp_lt_u32 s98, 0x2000
	s_cmov_b32 s99, 0
	s_mul_i32 s99, s99, 0x6000
	s_add_u32 s99, s99, 0x3441000
	s_add_u32 s100, s90, s99
	s_addc_u32 s101, s91, 0
	global_load_dwordx4 v[48:51], v96, s[100:101] offset:0
	global_load_dwordx4 v[52:55], v96, s[100:101] offset:1024
	global_load_dwordx4 v[56:59], v96, s[100:101] offset:2048
	global_load_dwordx4 v[60:63], v96, s[100:101] offset:3072
	s_sub_u32 s99, s98, 0x2000
	s_lshr_b32 s99, s99, 11
	s_add_u32 s99, s99, 1
	s_cmp_lt_u32 s98, 0x2000
	s_cmov_b32 s99, 0
	s_mul_i32 s99, s99, 0x6000
	s_add_u32 s99, s99, 0x3440000
	s_add_u32 s100, s90, s99
	s_addc_u32 s101, s91, 0
	global_load_dwordx4 v[64:67], v96, s[100:101] offset:0
	global_load_dwordx4 v[68:71], v96, s[100:101] offset:1024
	global_load_dwordx4 v[72:75], v96, s[100:101] offset:2048
	global_load_dwordx4 v[76:79], v96, s[100:101] offset:3072
	s_add_u32 s98, s98, 0x800
	s_lshl_b32 s99, s98, 12
	s_sub_u32 vcc_lo, s99, 0x2000000
	s_cmp_lt_u32 s98, 0x2000
	s_cselect_b32 s99, s99, vcc_lo
	s_cselect_b32 s100, s72, s74
	s_cselect_b32 s101, s73, s75
	s_add_u32 s100, s100, s99
	s_addc_u32 s101, s101, 0
	global_load_dwordx4 v[16:19], v96, s[100:101] offset:0
	global_load_dwordx4 v[20:23], v96, s[100:101] offset:1024
	global_load_dwordx4 v[24:27], v96, s[100:101] offset:2048
	global_load_dwordx4 v[28:31], v96, s[100:101] offset:3072
	s_sub_u32 s98, s98, 0x800
	s_waitcnt vmcnt(12)
	v_mul_f32_e32 v80, v1, v1
	v_mul_f32_e32 v81, v5, v5
	v_mul_f32_e32 v82, v9, v9
	v_mul_f32_e32 v83, v13, v13
	v_fmac_f32_e32 v80, v0, v0
	v_fmac_f32_e32 v81, v4, v4
	v_fmac_f32_e32 v82, v8, v8
	v_fmac_f32_e32 v83, v12, v12
	v_fmac_f32_e32 v80, v2, v2
	v_fmac_f32_e32 v81, v6, v6
	v_fmac_f32_e32 v82, v10, v10
	v_fmac_f32_e32 v83, v14, v14
	v_fmac_f32_e32 v80, v3, v3
	v_fmac_f32_e32 v81, v7, v7
	v_fmac_f32_e32 v82, v11, v11
	v_fmac_f32_e32 v83, v15, v15
	v_add_f32_e32 v84, v80, v81
	v_add_f32_e32 v84, v84, v82
	v_add_f32_e32 v84, v84, v83
	v_mov_b32_e32 v85, v84
	s_nop 1
	v_permlane32_swap_b32_e32 v84, v85
	s_nop 1
	v_add_f32_e32 v84, v84, v85
	v_mov_b32_e32 v85, v84
	s_nop 1
	v_permlane16_swap_b32_e32 v84, v85
	s_nop 1
	v_add_f32_e32 v84, v84, v85
	s_nop 1
	v_add_f32_dpp v84, v84, v84 row_mirror row_mask:0xf bank_mask:0xf
	s_nop 1
	v_add_f32_dpp v84, v84, v84 row_half_mirror row_mask:0xf bank_mask:0xf
	s_nop 1
	v_add_f32_dpp v84, v84, v84 quad_perm:[2,3,0,1] row_mask:0xf bank_mask:0xf
	s_nop 1
	v_add_f32_dpp v84, v84, v84 quad_perm:[1,0,3,2] row_mask:0xf bank_mask:0xf
	s_nop 1
	v_fmamk_f32 v84, v84, 0x3a800000, v104
	v_mul_f32_e32 v85, 0x4b800000, v84
	v_cmp_gt_f32_e32 vcc, 0x800000, v84
	s_nop 1
	v_cndmask_b32_e32 v84, v84, v85, vcc
	v_rsq_f32_e32 v84, v84
	s_nop 0
	v_mul_f32_e32 v85, 0x45800000, v84
	v_cndmask_b32_e32 v106, v84, v85, vcc
	s_waitcnt vmcnt(4)
	s_lshl_b32 s99, s98, 11
	s_add_u32 s99, s99, 0xb171900
	s_add_u32 s100, s90, s99
	s_addc_u32 s101, s91, 0
	v_pk_mul_f32 v[0:1], v[0:1], v[106:107] op_sel_hi:[1,0]
	v_pk_mul_f32 v[2:3], v[2:3], v[106:107] op_sel_hi:[1,0]
	v_pk_mul_f32 v[0:1], v[32:33], v[0:1]
	v_pk_mul_f32 v[2:3], v[34:35], v[2:3]
	v_pk_add_f32 v[48:49], v[48:49], 1.0 op_sel_hi:[1,0]
	v_pk_add_f32 v[50:51], v[50:51], 1.0 op_sel_hi:[1,0]
	v_pk_fma_f32 v[0:1], v[48:49], v[0:1], v[64:65]
	v_pk_fma_f32 v[2:3], v[50:51], v[2:3], v[66:67]
	v_cvt_pk_bf16_f32 v0, v0, v1
	v_cvt_pk_bf16_f32 v1, v2, v3
	global_store_dwordx2 v97, v[0:1], s[100:101] offset:0
	v_pk_mul_f32 v[4:5], v[4:5], v[106:107] op_sel_hi:[1,0]
	v_pk_mul_f32 v[6:7], v[6:7], v[106:107] op_sel_hi:[1,0]
	v_pk_mul_f32 v[4:5], v[36:37], v[4:5]
	v_pk_mul_f32 v[6:7], v[38:39], v[6:7]
	v_pk_add_f32 v[52:53], v[52:53], 1.0 op_sel_hi:[1,0]
	v_pk_add_f32 v[54:55], v[54:55], 1.0 op_sel_hi:[1,0]
	v_pk_fma_f32 v[4:5], v[52:53], v[4:5], v[68:69]
	v_pk_fma_f32 v[6:7], v[54:55], v[6:7], v[70:71]
	v_cvt_pk_bf16_f32 v4, v4, v5
	v_cvt_pk_bf16_f32 v5, v6, v7
	global_store_dwordx2 v97, v[4:5], s[100:101] offset:512
	v_pk_mul_f32 v[8:9], v[8:9], v[106:107] op_sel_hi:[1,0]
	v_pk_mul_f32 v[10:11], v[10:11], v[106:107] op_sel_hi:[1,0]
	v_pk_mul_f32 v[8:9], v[40:41], v[8:9]
	v_pk_mul_f32 v[10:11], v[42:43], v[10:11]
	v_pk_add_f32 v[56:57], v[56:57], 1.0 op_sel_hi:[1,0]
	v_pk_add_f32 v[58:59], v[58:59], 1.0 op_sel_hi:[1,0]
	v_pk_fma_f32 v[8:9], v[56:57], v[8:9], v[72:73]
	v_pk_fma_f32 v[10:11], v[58:59], v[10:11], v[74:75]
	v_cvt_pk_bf16_f32 v8, v8, v9
	v_cvt_pk_bf16_f32 v9, v10, v11
	global_store_dwordx2 v97, v[8:9], s[100:101] offset:1024
	v_pk_mul_f32 v[12:13], v[12:13], v[106:107] op_sel_hi:[1,0]
	v_pk_mul_f32 v[14:15], v[14:15], v[106:107] op_sel_hi:[1,0]
	v_pk_mul_f32 v[12:13], v[44:45], v[12:13]
	v_pk_mul_f32 v[14:15], v[46:47], v[14:15]
	v_pk_add_f32 v[60:61], v[60:61], 1.0 op_sel_hi:[1,0]
	v_pk_add_f32 v[62:63], v[62:63], 1.0 op_sel_hi:[1,0]
	v_pk_fma_f32 v[12:13], v[60:61], v[12:13], v[76:77]
	v_pk_fma_f32 v[14:15], v[62:63], v[14:15], v[78:79]
	v_cvt_pk_bf16_f32 v12, v12, v13
	v_cvt_pk_bf16_f32 v13, v14, v15
	global_store_dwordx2 v97, v[12:13], s[100:101] offset:1536
	s_add_u32 s98, s98, 0x800
	s_sub_u32 s99, s98, 0x2000
	s_lshr_b32 s99, s99, 11
	s_add_u32 s99, s99, 1
	s_cmp_lt_u32 s98, 0x2000
	s_cmov_b32 s99, 0
	s_mul_i32 s99, s99, 0x6000
	s_add_u32 s99, s99, 0x3441000
	s_add_u32 s100, s90, s99
	s_addc_u32 s101, s91, 0
	global_load_dwordx4 v[48:51], v96, s[100:101] offset:0
	global_load_dwordx4 v[52:55], v96, s[100:101] offset:1024
	global_load_dwordx4 v[56:59], v96, s[100:101] offset:2048
	global_load_dwordx4 v[60:63], v96, s[100:101] offset:3072
	s_sub_u32 s99, s98, 0x2000
	s_lshr_b32 s99, s99, 11
	s_add_u32 s99, s99, 1
	s_cmp_lt_u32 s98, 0x2000
	s_cmov_b32 s99, 0
	s_mul_i32 s99, s99, 0x6000
	s_add_u32 s99, s99, 0x3440000
	s_add_u32 s100, s90, s99
	s_addc_u32 s101, s91, 0
	global_load_dwordx4 v[64:67], v96, s[100:101] offset:0
	global_load_dwordx4 v[68:71], v96, s[100:101] offset:1024
	global_load_dwordx4 v[72:75], v96, s[100:101] offset:2048
	global_load_dwordx4 v[76:79], v96, s[100:101] offset:3072
	s_add_u32 s98, s98, 0x800
	s_lshl_b32 s99, s98, 12
	s_sub_u32 vcc_lo, s99, 0x2000000
	s_cmp_lt_u32 s98, 0x2000
	s_cselect_b32 s99, s99, vcc_lo
	s_cselect_b32 s100, s72, s74
	s_cselect_b32 s101, s73, s75
	s_add_u32 s100, s100, s99
	s_addc_u32 s101, s101, 0
	global_load_dwordx4 v[0:3], v96, s[100:101] offset:0
	global_load_dwordx4 v[4:7], v96, s[100:101] offset:1024
	global_load_dwordx4 v[8:11], v96, s[100:101] offset:2048
	global_load_dwordx4 v[12:15], v96, s[100:101] offset:3072
	s_sub_u32 s98, s98, 0x800
	s_waitcnt vmcnt(16)
	v_mul_f32_e32 v80, v17, v17
	v_mul_f32_e32 v81, v21, v21
	v_mul_f32_e32 v82, v25, v25
	v_mul_f32_e32 v83, v29, v29
	v_fmac_f32_e32 v80, v16, v16
	v_fmac_f32_e32 v81, v20, v20
	v_fmac_f32_e32 v82, v24, v24
	v_fmac_f32_e32 v83, v28, v28
	v_fmac_f32_e32 v80, v18, v18
	v_fmac_f32_e32 v81, v22, v22
	v_fmac_f32_e32 v82, v26, v26
	v_fmac_f32_e32 v83, v30, v30
	v_fmac_f32_e32 v80, v19, v19
	v_fmac_f32_e32 v81, v23, v23
	v_fmac_f32_e32 v82, v27, v27
	v_fmac_f32_e32 v83, v31, v31
	v_add_f32_e32 v84, v80, v81
	v_add_f32_e32 v84, v84, v82
	v_add_f32_e32 v84, v84, v83
	v_mov_b32_e32 v85, v84
	s_nop 1
	v_permlane32_swap_b32_e32 v84, v85
	s_nop 1
	v_add_f32_e32 v84, v84, v85
	v_mov_b32_e32 v85, v84
	s_nop 1
	v_permlane16_swap_b32_e32 v84, v85
	s_nop 1
	v_add_f32_e32 v84, v84, v85
	s_nop 1
	v_add_f32_dpp v84, v84, v84 row_mirror row_mask:0xf bank_mask:0xf
	s_nop 1
	v_add_f32_dpp v84, v84, v84 row_half_mirror row_mask:0xf bank_mask:0xf
	s_nop 1
	v_add_f32_dpp v84, v84, v84 quad_perm:[2,3,0,1] row_mask:0xf bank_mask:0xf
	s_nop 1
	v_add_f32_dpp v84, v84, v84 quad_perm:[1,0,3,2] row_mask:0xf bank_mask:0xf
	s_nop 1
	v_fmamk_f32 v84, v84, 0x3a800000, v104
	v_mul_f32_e32 v85, 0x4b800000, v84
	v_cmp_gt_f32_e32 vcc, 0x800000, v84
	s_nop 1
	v_cndmask_b32_e32 v84, v84, v85, vcc
	v_rsq_f32_e32 v84, v84
	s_nop 0
	v_mul_f32_e32 v85, 0x45800000, v84
	v_cndmask_b32_e32 v106, v84, v85, vcc
	s_waitcnt vmcnt(4)
	s_lshl_b32 s99, s98, 11
	s_add_u32 s99, s99, 0xb171900
	s_add_u32 s100, s90, s99
	s_addc_u32 s101, s91, 0
	v_pk_mul_f32 v[16:17], v[16:17], v[106:107] op_sel_hi:[1,0]
	v_pk_mul_f32 v[18:19], v[18:19], v[106:107] op_sel_hi:[1,0]
	v_pk_mul_f32 v[16:17], v[32:33], v[16:17]
	v_pk_mul_f32 v[18:19], v[34:35], v[18:19]
	v_pk_add_f32 v[48:49], v[48:49], 1.0 op_sel_hi:[1,0]
	v_pk_add_f32 v[50:51], v[50:51], 1.0 op_sel_hi:[1,0]
	v_pk_fma_f32 v[16:17], v[48:49], v[16:17], v[64:65]
	v_pk_fma_f32 v[18:19], v[50:51], v[18:19], v[66:67]
	v_cvt_pk_bf16_f32 v16, v16, v17
	v_cvt_pk_bf16_f32 v17, v18, v19
	global_store_dwordx2 v97, v[16:17], s[100:101] offset:0
	v_pk_mul_f32 v[20:21], v[20:21], v[106:107] op_sel_hi:[1,0]
	v_pk_mul_f32 v[22:23], v[22:23], v[106:107] op_sel_hi:[1,0]
	v_pk_mul_f32 v[20:21], v[36:37], v[20:21]
	v_pk_mul_f32 v[22:23], v[38:39], v[22:23]
	v_pk_add_f32 v[52:53], v[52:53], 1.0 op_sel_hi:[1,0]
	v_pk_add_f32 v[54:55], v[54:55], 1.0 op_sel_hi:[1,0]
	v_pk_fma_f32 v[20:21], v[52:53], v[20:21], v[68:69]
	v_pk_fma_f32 v[22:23], v[54:55], v[22:23], v[70:71]
	v_cvt_pk_bf16_f32 v20, v20, v21
	v_cvt_pk_bf16_f32 v21, v22, v23
	global_store_dwordx2 v97, v[20:21], s[100:101] offset:512
	v_pk_mul_f32 v[24:25], v[24:25], v[106:107] op_sel_hi:[1,0]
	v_pk_mul_f32 v[26:27], v[26:27], v[106:107] op_sel_hi:[1,0]
	v_pk_mul_f32 v[24:25], v[40:41], v[24:25]
	v_pk_mul_f32 v[26:27], v[42:43], v[26:27]
	v_pk_add_f32 v[56:57], v[56:57], 1.0 op_sel_hi:[1,0]
	v_pk_add_f32 v[58:59], v[58:59], 1.0 op_sel_hi:[1,0]
	v_pk_fma_f32 v[24:25], v[56:57], v[24:25], v[72:73]
	v_pk_fma_f32 v[26:27], v[58:59], v[26:27], v[74:75]
	v_cvt_pk_bf16_f32 v24, v24, v25
	v_cvt_pk_bf16_f32 v25, v26, v27
	global_store_dwordx2 v97, v[24:25], s[100:101] offset:1024
	v_pk_mul_f32 v[28:29], v[28:29], v[106:107] op_sel_hi:[1,0]
	v_pk_mul_f32 v[30:31], v[30:31], v[106:107] op_sel_hi:[1,0]
	v_pk_mul_f32 v[28:29], v[44:45], v[28:29]
	v_pk_mul_f32 v[30:31], v[46:47], v[30:31]
	v_pk_add_f32 v[60:61], v[60:61], 1.0 op_sel_hi:[1,0]
	v_pk_add_f32 v[62:63], v[62:63], 1.0 op_sel_hi:[1,0]
	v_pk_fma_f32 v[28:29], v[60:61], v[28:29], v[76:77]
	v_pk_fma_f32 v[30:31], v[62:63], v[30:31], v[78:79]
	v_cvt_pk_bf16_f32 v28, v28, v29
	v_cvt_pk_bf16_f32 v29, v30, v31
	global_store_dwordx2 v97, v[28:29], s[100:101] offset:1536
	s_add_u32 s98, s98, 0x800
	s_sub_u32 s99, s98, 0x2000
	s_lshr_b32 s99, s99, 11
	s_add_u32 s99, s99, 1
	s_cmp_lt_u32 s98, 0x2000
	s_cmov_b32 s99, 0
	s_mul_i32 s99, s99, 0x6000
	s_add_u32 s99, s99, 0x3441000
	s_add_u32 s100, s90, s99
	s_addc_u32 s101, s91, 0
	global_load_dwordx4 v[48:51], v96, s[100:101] offset:0
	global_load_dwordx4 v[52:55], v96, s[100:101] offset:1024
	global_load_dwordx4 v[56:59], v96, s[100:101] offset:2048
	global_load_dwordx4 v[60:63], v96, s[100:101] offset:3072
	s_sub_u32 s99, s98, 0x2000
	s_lshr_b32 s99, s99, 11
	s_add_u32 s99, s99, 1
	s_cmp_lt_u32 s98, 0x2000
	s_cmov_b32 s99, 0
	s_mul_i32 s99, s99, 0x6000
	s_add_u32 s99, s99, 0x3440000
	s_add_u32 s100, s90, s99
	s_addc_u32 s101, s91, 0
	global_load_dwordx4 v[64:67], v96, s[100:101] offset:0
	global_load_dwordx4 v[68:71], v96, s[100:101] offset:1024
	global_load_dwordx4 v[72:75], v96, s[100:101] offset:2048
	global_load_dwordx4 v[76:79], v96, s[100:101] offset:3072
	s_add_u32 s98, s98, 0x800
	s_lshl_b32 s99, s98, 12
	s_sub_u32 vcc_lo, s99, 0x2000000
	s_cmp_lt_u32 s98, 0x2000
	s_cselect_b32 s99, s99, vcc_lo
	s_cselect_b32 s100, s72, s74
	s_cselect_b32 s101, s73, s75
	s_add_u32 s100, s100, s99
	s_addc_u32 s101, s101, 0
	global_load_dwordx4 v[16:19], v96, s[100:101] offset:0
	global_load_dwordx4 v[20:23], v96, s[100:101] offset:1024
	global_load_dwordx4 v[24:27], v96, s[100:101] offset:2048
	global_load_dwordx4 v[28:31], v96, s[100:101] offset:3072
	s_sub_u32 s98, s98, 0x800
	s_waitcnt vmcnt(16)
	v_mul_f32_e32 v80, v1, v1
	v_mul_f32_e32 v81, v5, v5
	v_mul_f32_e32 v82, v9, v9
	v_mul_f32_e32 v83, v13, v13
	v_fmac_f32_e32 v80, v0, v0
	v_fmac_f32_e32 v81, v4, v4
	v_fmac_f32_e32 v82, v8, v8
	v_fmac_f32_e32 v83, v12, v12
	v_fmac_f32_e32 v80, v2, v2
	v_fmac_f32_e32 v81, v6, v6
	v_fmac_f32_e32 v82, v10, v10
	v_fmac_f32_e32 v83, v14, v14
	v_fmac_f32_e32 v80, v3, v3
	v_fmac_f32_e32 v81, v7, v7
	v_fmac_f32_e32 v82, v11, v11
	v_fmac_f32_e32 v83, v15, v15
	v_add_f32_e32 v84, v80, v81
	v_add_f32_e32 v84, v84, v82
	v_add_f32_e32 v84, v84, v83
	v_mov_b32_e32 v85, v84
	s_nop 1
	v_permlane32_swap_b32_e32 v84, v85
	s_nop 1
	v_add_f32_e32 v84, v84, v85
	v_mov_b32_e32 v85, v84
	s_nop 1
	v_permlane16_swap_b32_e32 v84, v85
	s_nop 1
	v_add_f32_e32 v84, v84, v85
	s_nop 1
	v_add_f32_dpp v84, v84, v84 row_mirror row_mask:0xf bank_mask:0xf
	s_nop 1
	v_add_f32_dpp v84, v84, v84 row_half_mirror row_mask:0xf bank_mask:0xf
	s_nop 1
	v_add_f32_dpp v84, v84, v84 quad_perm:[2,3,0,1] row_mask:0xf bank_mask:0xf
	s_nop 1
	v_add_f32_dpp v84, v84, v84 quad_perm:[1,0,3,2] row_mask:0xf bank_mask:0xf
	s_nop 1
	v_fmamk_f32 v84, v84, 0x3a800000, v104
	v_mul_f32_e32 v85, 0x4b800000, v84
	v_cmp_gt_f32_e32 vcc, 0x800000, v84
	s_nop 1
	v_cndmask_b32_e32 v84, v84, v85, vcc
	v_rsq_f32_e32 v84, v84
	s_nop 0
	v_mul_f32_e32 v85, 0x45800000, v84
	v_cndmask_b32_e32 v106, v84, v85, vcc
	s_waitcnt vmcnt(4)
	s_lshl_b32 s99, s98, 11
	s_add_u32 s99, s99, 0xb171900
	s_add_u32 s100, s90, s99
	s_addc_u32 s101, s91, 0
	v_pk_mul_f32 v[0:1], v[0:1], v[106:107] op_sel_hi:[1,0]
	v_pk_mul_f32 v[2:3], v[2:3], v[106:107] op_sel_hi:[1,0]
	v_pk_mul_f32 v[0:1], v[32:33], v[0:1]
	v_pk_mul_f32 v[2:3], v[34:35], v[2:3]
	v_pk_add_f32 v[48:49], v[48:49], 1.0 op_sel_hi:[1,0]
	v_pk_add_f32 v[50:51], v[50:51], 1.0 op_sel_hi:[1,0]
	v_pk_fma_f32 v[0:1], v[48:49], v[0:1], v[64:65]
	v_pk_fma_f32 v[2:3], v[50:51], v[2:3], v[66:67]
	v_cvt_pk_bf16_f32 v0, v0, v1
	v_cvt_pk_bf16_f32 v1, v2, v3
	global_store_dwordx2 v97, v[0:1], s[100:101] offset:0
	v_pk_mul_f32 v[4:5], v[4:5], v[106:107] op_sel_hi:[1,0]
	v_pk_mul_f32 v[6:7], v[6:7], v[106:107] op_sel_hi:[1,0]
	v_pk_mul_f32 v[4:5], v[36:37], v[4:5]
	v_pk_mul_f32 v[6:7], v[38:39], v[6:7]
	v_pk_add_f32 v[52:53], v[52:53], 1.0 op_sel_hi:[1,0]
	v_pk_add_f32 v[54:55], v[54:55], 1.0 op_sel_hi:[1,0]
	v_pk_fma_f32 v[4:5], v[52:53], v[4:5], v[68:69]
	v_pk_fma_f32 v[6:7], v[54:55], v[6:7], v[70:71]
	v_cvt_pk_bf16_f32 v4, v4, v5
	v_cvt_pk_bf16_f32 v5, v6, v7
	global_store_dwordx2 v97, v[4:5], s[100:101] offset:512
	v_pk_mul_f32 v[8:9], v[8:9], v[106:107] op_sel_hi:[1,0]
	v_pk_mul_f32 v[10:11], v[10:11], v[106:107] op_sel_hi:[1,0]
	v_pk_mul_f32 v[8:9], v[40:41], v[8:9]
	v_pk_mul_f32 v[10:11], v[42:43], v[10:11]
	v_pk_add_f32 v[56:57], v[56:57], 1.0 op_sel_hi:[1,0]
	v_pk_add_f32 v[58:59], v[58:59], 1.0 op_sel_hi:[1,0]
	v_pk_fma_f32 v[8:9], v[56:57], v[8:9], v[72:73]
	v_pk_fma_f32 v[10:11], v[58:59], v[10:11], v[74:75]
	v_cvt_pk_bf16_f32 v8, v8, v9
	v_cvt_pk_bf16_f32 v9, v10, v11
	global_store_dwordx2 v97, v[8:9], s[100:101] offset:1024
	v_pk_mul_f32 v[12:13], v[12:13], v[106:107] op_sel_hi:[1,0]
	v_pk_mul_f32 v[14:15], v[14:15], v[106:107] op_sel_hi:[1,0]
	v_pk_mul_f32 v[12:13], v[44:45], v[12:13]
	v_pk_mul_f32 v[14:15], v[46:47], v[14:15]
	v_pk_add_f32 v[60:61], v[60:61], 1.0 op_sel_hi:[1,0]
	v_pk_add_f32 v[62:63], v[62:63], 1.0 op_sel_hi:[1,0]
	v_pk_fma_f32 v[12:13], v[60:61], v[12:13], v[76:77]
	v_pk_fma_f32 v[14:15], v[62:63], v[14:15], v[78:79]
	v_cvt_pk_bf16_f32 v12, v12, v13
	v_cvt_pk_bf16_f32 v13, v14, v15
	global_store_dwordx2 v97, v[12:13], s[100:101] offset:1536
	s_add_u32 s98, s98, 0x800
	s_sub_u32 s99, s98, 0x2000
	s_lshr_b32 s99, s99, 11
	s_add_u32 s99, s99, 1
	s_cmp_lt_u32 s98, 0x2000
	s_cmov_b32 s99, 0
	s_mul_i32 s99, s99, 0x6000
	s_add_u32 s99, s99, 0x3441000
	s_add_u32 s100, s90, s99
	s_addc_u32 s101, s91, 0
	global_load_dwordx4 v[48:51], v96, s[100:101] offset:0
	global_load_dwordx4 v[52:55], v96, s[100:101] offset:1024
	global_load_dwordx4 v[56:59], v96, s[100:101] offset:2048
	global_load_dwordx4 v[60:63], v96, s[100:101] offset:3072
	s_sub_u32 s99, s98, 0x2000
	s_lshr_b32 s99, s99, 11
	s_add_u32 s99, s99, 1
	s_cmp_lt_u32 s98, 0x2000
	s_cmov_b32 s99, 0
	s_mul_i32 s99, s99, 0x6000
	s_add_u32 s99, s99, 0x3440000
	s_add_u32 s100, s90, s99
	s_addc_u32 s101, s91, 0
	global_load_dwordx4 v[64:67], v96, s[100:101] offset:0
	global_load_dwordx4 v[68:71], v96, s[100:101] offset:1024
	global_load_dwordx4 v[72:75], v96, s[100:101] offset:2048
	global_load_dwordx4 v[76:79], v96, s[100:101] offset:3072
	s_add_u32 s98, s98, 0x800
	s_lshl_b32 s99, s98, 12
	s_sub_u32 vcc_lo, s99, 0x2000000
	s_cmp_lt_u32 s98, 0x2000
	s_cselect_b32 s99, s99, vcc_lo
	s_cselect_b32 s100, s72, s74
	s_cselect_b32 s101, s73, s75
	s_add_u32 s100, s100, s99
	s_addc_u32 s101, s101, 0
	global_load_dwordx4 v[0:3], v96, s[100:101] offset:0
	global_load_dwordx4 v[4:7], v96, s[100:101] offset:1024
	global_load_dwordx4 v[8:11], v96, s[100:101] offset:2048
	global_load_dwordx4 v[12:15], v96, s[100:101] offset:3072
	s_sub_u32 s98, s98, 0x800
	s_waitcnt vmcnt(16)
	v_mul_f32_e32 v80, v17, v17
	v_mul_f32_e32 v81, v21, v21
	v_mul_f32_e32 v82, v25, v25
	v_mul_f32_e32 v83, v29, v29
	v_fmac_f32_e32 v80, v16, v16
	v_fmac_f32_e32 v81, v20, v20
	v_fmac_f32_e32 v82, v24, v24
	v_fmac_f32_e32 v83, v28, v28
	v_fmac_f32_e32 v80, v18, v18
	v_fmac_f32_e32 v81, v22, v22
	v_fmac_f32_e32 v82, v26, v26
	v_fmac_f32_e32 v83, v30, v30
	v_fmac_f32_e32 v80, v19, v19
	v_fmac_f32_e32 v81, v23, v23
	v_fmac_f32_e32 v82, v27, v27
	v_fmac_f32_e32 v83, v31, v31
	v_add_f32_e32 v84, v80, v81
	v_add_f32_e32 v84, v84, v82
	v_add_f32_e32 v84, v84, v83
	v_mov_b32_e32 v85, v84
	s_nop 1
	v_permlane32_swap_b32_e32 v84, v85
	s_nop 1
	v_add_f32_e32 v84, v84, v85
	v_mov_b32_e32 v85, v84
	s_nop 1
	v_permlane16_swap_b32_e32 v84, v85
	s_nop 1
	v_add_f32_e32 v84, v84, v85
	s_nop 1
	v_add_f32_dpp v84, v84, v84 row_mirror row_mask:0xf bank_mask:0xf
	s_nop 1
	v_add_f32_dpp v84, v84, v84 row_half_mirror row_mask:0xf bank_mask:0xf
	s_nop 1
	v_add_f32_dpp v84, v84, v84 quad_perm:[2,3,0,1] row_mask:0xf bank_mask:0xf
	s_nop 1
	v_add_f32_dpp v84, v84, v84 quad_perm:[1,0,3,2] row_mask:0xf bank_mask:0xf
	s_nop 1
	v_fmamk_f32 v84, v84, 0x3a800000, v104
	v_mul_f32_e32 v85, 0x4b800000, v84
	v_cmp_gt_f32_e32 vcc, 0x800000, v84
	s_nop 1
	v_cndmask_b32_e32 v84, v84, v85, vcc
	v_rsq_f32_e32 v84, v84
	s_nop 0
	v_mul_f32_e32 v85, 0x45800000, v84
	v_cndmask_b32_e32 v106, v84, v85, vcc
	s_waitcnt vmcnt(4)
	s_lshl_b32 s99, s98, 11
	s_add_u32 s99, s99, 0xb171900
	s_add_u32 s100, s90, s99
	s_addc_u32 s101, s91, 0
	v_pk_mul_f32 v[16:17], v[16:17], v[106:107] op_sel_hi:[1,0]
	v_pk_mul_f32 v[18:19], v[18:19], v[106:107] op_sel_hi:[1,0]
	v_pk_mul_f32 v[16:17], v[32:33], v[16:17]
	v_pk_mul_f32 v[18:19], v[34:35], v[18:19]
	v_pk_add_f32 v[48:49], v[48:49], 1.0 op_sel_hi:[1,0]
	v_pk_add_f32 v[50:51], v[50:51], 1.0 op_sel_hi:[1,0]
	v_pk_fma_f32 v[16:17], v[48:49], v[16:17], v[64:65]
	v_pk_fma_f32 v[18:19], v[50:51], v[18:19], v[66:67]
	v_cvt_pk_bf16_f32 v16, v16, v17
	v_cvt_pk_bf16_f32 v17, v18, v19
	global_store_dwordx2 v97, v[16:17], s[100:101] offset:0
	v_pk_mul_f32 v[20:21], v[20:21], v[106:107] op_sel_hi:[1,0]
	v_pk_mul_f32 v[22:23], v[22:23], v[106:107] op_sel_hi:[1,0]
	v_pk_mul_f32 v[20:21], v[36:37], v[20:21]
	v_pk_mul_f32 v[22:23], v[38:39], v[22:23]
	v_pk_add_f32 v[52:53], v[52:53], 1.0 op_sel_hi:[1,0]
	v_pk_add_f32 v[54:55], v[54:55], 1.0 op_sel_hi:[1,0]
	v_pk_fma_f32 v[20:21], v[52:53], v[20:21], v[68:69]
	v_pk_fma_f32 v[22:23], v[54:55], v[22:23], v[70:71]
	v_cvt_pk_bf16_f32 v20, v20, v21
	v_cvt_pk_bf16_f32 v21, v22, v23
	global_store_dwordx2 v97, v[20:21], s[100:101] offset:512
	v_pk_mul_f32 v[24:25], v[24:25], v[106:107] op_sel_hi:[1,0]
	v_pk_mul_f32 v[26:27], v[26:27], v[106:107] op_sel_hi:[1,0]
	v_pk_mul_f32 v[24:25], v[40:41], v[24:25]
	v_pk_mul_f32 v[26:27], v[42:43], v[26:27]
	v_pk_add_f32 v[56:57], v[56:57], 1.0 op_sel_hi:[1,0]
	v_pk_add_f32 v[58:59], v[58:59], 1.0 op_sel_hi:[1,0]
	v_pk_fma_f32 v[24:25], v[56:57], v[24:25], v[72:73]
	v_pk_fma_f32 v[26:27], v[58:59], v[26:27], v[74:75]
	v_cvt_pk_bf16_f32 v24, v24, v25
	v_cvt_pk_bf16_f32 v25, v26, v27
	global_store_dwordx2 v97, v[24:25], s[100:101] offset:1024
	v_pk_mul_f32 v[28:29], v[28:29], v[106:107] op_sel_hi:[1,0]
	v_pk_mul_f32 v[30:31], v[30:31], v[106:107] op_sel_hi:[1,0]
	v_pk_mul_f32 v[28:29], v[44:45], v[28:29]
	v_pk_mul_f32 v[30:31], v[46:47], v[30:31]
	v_pk_add_f32 v[60:61], v[60:61], 1.0 op_sel_hi:[1,0]
	v_pk_add_f32 v[62:63], v[62:63], 1.0 op_sel_hi:[1,0]
	v_pk_fma_f32 v[28:29], v[60:61], v[28:29], v[76:77]
	v_pk_fma_f32 v[30:31], v[62:63], v[30:31], v[78:79]
	v_cvt_pk_bf16_f32 v28, v28, v29
	v_cvt_pk_bf16_f32 v29, v30, v31
	global_store_dwordx2 v97, v[28:29], s[100:101] offset:1536
	s_add_u32 s98, s98, 0x800
	s_sub_u32 s99, s98, 0x2000
	s_lshr_b32 s99, s99, 11
	s_add_u32 s99, s99, 1
	s_cmp_lt_u32 s98, 0x2000
	s_cmov_b32 s99, 0
	s_mul_i32 s99, s99, 0x6000
	s_add_u32 s99, s99, 0x3441000
	s_add_u32 s100, s90, s99
	s_addc_u32 s101, s91, 0
	global_load_dwordx4 v[48:51], v96, s[100:101] offset:0
	global_load_dwordx4 v[52:55], v96, s[100:101] offset:1024
	global_load_dwordx4 v[56:59], v96, s[100:101] offset:2048
	global_load_dwordx4 v[60:63], v96, s[100:101] offset:3072
	s_sub_u32 s99, s98, 0x2000
	s_lshr_b32 s99, s99, 11
	s_add_u32 s99, s99, 1
	s_cmp_lt_u32 s98, 0x2000
	s_cmov_b32 s99, 0
	s_mul_i32 s99, s99, 0x6000
	s_add_u32 s99, s99, 0x3440000
	s_add_u32 s100, s90, s99
	s_addc_u32 s101, s91, 0
	global_load_dwordx4 v[64:67], v96, s[100:101] offset:0
	global_load_dwordx4 v[68:71], v96, s[100:101] offset:1024
	global_load_dwordx4 v[72:75], v96, s[100:101] offset:2048
	global_load_dwordx4 v[76:79], v96, s[100:101] offset:3072
	s_add_u32 s98, s98, 0x800
	s_lshl_b32 s99, s98, 12
	s_sub_u32 vcc_lo, s99, 0x2000000
	s_cmp_lt_u32 s98, 0x2000
	s_cselect_b32 s99, s99, vcc_lo
	s_cselect_b32 s100, s72, s74
	s_cselect_b32 s101, s73, s75
	s_add_u32 s100, s100, s99
	s_addc_u32 s101, s101, 0
	global_load_dwordx4 v[16:19], v96, s[100:101] offset:0
	global_load_dwordx4 v[20:23], v96, s[100:101] offset:1024
	global_load_dwordx4 v[24:27], v96, s[100:101] offset:2048
	global_load_dwordx4 v[28:31], v96, s[100:101] offset:3072
	s_sub_u32 s98, s98, 0x800
	s_waitcnt vmcnt(16)
	v_mul_f32_e32 v80, v1, v1
	v_mul_f32_e32 v81, v5, v5
	v_mul_f32_e32 v82, v9, v9
	v_mul_f32_e32 v83, v13, v13
	v_fmac_f32_e32 v80, v0, v0
	v_fmac_f32_e32 v81, v4, v4
	v_fmac_f32_e32 v82, v8, v8
	v_fmac_f32_e32 v83, v12, v12
	v_fmac_f32_e32 v80, v2, v2
	v_fmac_f32_e32 v81, v6, v6
	v_fmac_f32_e32 v82, v10, v10
	v_fmac_f32_e32 v83, v14, v14
	v_fmac_f32_e32 v80, v3, v3
	v_fmac_f32_e32 v81, v7, v7
	v_fmac_f32_e32 v82, v11, v11
	v_fmac_f32_e32 v83, v15, v15
	v_add_f32_e32 v84, v80, v81
	v_add_f32_e32 v84, v84, v82
	v_add_f32_e32 v84, v84, v83
	v_mov_b32_e32 v85, v84
	s_nop 1
	v_permlane32_swap_b32_e32 v84, v85
	s_nop 1
	v_add_f32_e32 v84, v84, v85
	v_mov_b32_e32 v85, v84
	s_nop 1
	v_permlane16_swap_b32_e32 v84, v85
	s_nop 1
	v_add_f32_e32 v84, v84, v85
	s_nop 1
	v_add_f32_dpp v84, v84, v84 row_mirror row_mask:0xf bank_mask:0xf
	s_nop 1
	v_add_f32_dpp v84, v84, v84 row_half_mirror row_mask:0xf bank_mask:0xf
	s_nop 1
	v_add_f32_dpp v84, v84, v84 quad_perm:[2,3,0,1] row_mask:0xf bank_mask:0xf
	s_nop 1
	v_add_f32_dpp v84, v84, v84 quad_perm:[1,0,3,2] row_mask:0xf bank_mask:0xf
	s_nop 1
	v_fmamk_f32 v84, v84, 0x3a800000, v104
	v_mul_f32_e32 v85, 0x4b800000, v84
	v_cmp_gt_f32_e32 vcc, 0x800000, v84
	s_nop 1
	v_cndmask_b32_e32 v84, v84, v85, vcc
	v_rsq_f32_e32 v84, v84
	s_nop 0
	v_mul_f32_e32 v85, 0x45800000, v84
	v_cndmask_b32_e32 v106, v84, v85, vcc
	s_waitcnt vmcnt(4)
	s_lshl_b32 s99, s98, 11
	s_add_u32 s99, s99, 0xb171900
	s_add_u32 s100, s90, s99
	s_addc_u32 s101, s91, 0
	v_pk_mul_f32 v[0:1], v[0:1], v[106:107] op_sel_hi:[1,0]
	v_pk_mul_f32 v[2:3], v[2:3], v[106:107] op_sel_hi:[1,0]
	v_pk_mul_f32 v[0:1], v[32:33], v[0:1]
	v_pk_mul_f32 v[2:3], v[34:35], v[2:3]
	v_pk_add_f32 v[48:49], v[48:49], 1.0 op_sel_hi:[1,0]
	v_pk_add_f32 v[50:51], v[50:51], 1.0 op_sel_hi:[1,0]
	v_pk_fma_f32 v[0:1], v[48:49], v[0:1], v[64:65]
	v_pk_fma_f32 v[2:3], v[50:51], v[2:3], v[66:67]
	v_cvt_pk_bf16_f32 v0, v0, v1
	v_cvt_pk_bf16_f32 v1, v2, v3
	global_store_dwordx2 v97, v[0:1], s[100:101] offset:0
	v_pk_mul_f32 v[4:5], v[4:5], v[106:107] op_sel_hi:[1,0]
	v_pk_mul_f32 v[6:7], v[6:7], v[106:107] op_sel_hi:[1,0]
	v_pk_mul_f32 v[4:5], v[36:37], v[4:5]
	v_pk_mul_f32 v[6:7], v[38:39], v[6:7]
	v_pk_add_f32 v[52:53], v[52:53], 1.0 op_sel_hi:[1,0]
	v_pk_add_f32 v[54:55], v[54:55], 1.0 op_sel_hi:[1,0]
	v_pk_fma_f32 v[4:5], v[52:53], v[4:5], v[68:69]
	v_pk_fma_f32 v[6:7], v[54:55], v[6:7], v[70:71]
	v_cvt_pk_bf16_f32 v4, v4, v5
	v_cvt_pk_bf16_f32 v5, v6, v7
	global_store_dwordx2 v97, v[4:5], s[100:101] offset:512
	v_pk_mul_f32 v[8:9], v[8:9], v[106:107] op_sel_hi:[1,0]
	v_pk_mul_f32 v[10:11], v[10:11], v[106:107] op_sel_hi:[1,0]
	v_pk_mul_f32 v[8:9], v[40:41], v[8:9]
	v_pk_mul_f32 v[10:11], v[42:43], v[10:11]
	v_pk_add_f32 v[56:57], v[56:57], 1.0 op_sel_hi:[1,0]
	v_pk_add_f32 v[58:59], v[58:59], 1.0 op_sel_hi:[1,0]
	v_pk_fma_f32 v[8:9], v[56:57], v[8:9], v[72:73]
	v_pk_fma_f32 v[10:11], v[58:59], v[10:11], v[74:75]
	v_cvt_pk_bf16_f32 v8, v8, v9
	v_cvt_pk_bf16_f32 v9, v10, v11
	global_store_dwordx2 v97, v[8:9], s[100:101] offset:1024
	v_pk_mul_f32 v[12:13], v[12:13], v[106:107] op_sel_hi:[1,0]
	v_pk_mul_f32 v[14:15], v[14:15], v[106:107] op_sel_hi:[1,0]
	v_pk_mul_f32 v[12:13], v[44:45], v[12:13]
	v_pk_mul_f32 v[14:15], v[46:47], v[14:15]
	v_pk_add_f32 v[60:61], v[60:61], 1.0 op_sel_hi:[1,0]
	v_pk_add_f32 v[62:63], v[62:63], 1.0 op_sel_hi:[1,0]
	v_pk_fma_f32 v[12:13], v[60:61], v[12:13], v[76:77]
	v_pk_fma_f32 v[14:15], v[62:63], v[14:15], v[78:79]
	v_cvt_pk_bf16_f32 v12, v12, v13
	v_cvt_pk_bf16_f32 v13, v14, v15
	global_store_dwordx2 v97, v[12:13], s[100:101] offset:1536
	s_add_u32 s98, s98, 0x800
	s_sub_u32 s99, s98, 0x2000
	s_lshr_b32 s99, s99, 11
	s_add_u32 s99, s99, 1
	s_cmp_lt_u32 s98, 0x2000
	s_cmov_b32 s99, 0
	s_mul_i32 s99, s99, 0x6000
	s_add_u32 s99, s99, 0x3441000
	s_add_u32 s100, s90, s99
	s_addc_u32 s101, s91, 0
	global_load_dwordx4 v[48:51], v96, s[100:101] offset:0
	global_load_dwordx4 v[52:55], v96, s[100:101] offset:1024
	global_load_dwordx4 v[56:59], v96, s[100:101] offset:2048
	global_load_dwordx4 v[60:63], v96, s[100:101] offset:3072
	s_sub_u32 s99, s98, 0x2000
	s_lshr_b32 s99, s99, 11
	s_add_u32 s99, s99, 1
	s_cmp_lt_u32 s98, 0x2000
	s_cmov_b32 s99, 0
	s_mul_i32 s99, s99, 0x6000
	s_add_u32 s99, s99, 0x3440000
	s_add_u32 s100, s90, s99
	s_addc_u32 s101, s91, 0
	global_load_dwordx4 v[64:67], v96, s[100:101] offset:0
	global_load_dwordx4 v[68:71], v96, s[100:101] offset:1024
	global_load_dwordx4 v[72:75], v96, s[100:101] offset:2048
	global_load_dwordx4 v[76:79], v96, s[100:101] offset:3072
	s_waitcnt vmcnt(12)
	v_mul_f32_e32 v80, v17, v17
	v_mul_f32_e32 v81, v21, v21
	v_mul_f32_e32 v82, v25, v25
	v_mul_f32_e32 v83, v29, v29
	v_fmac_f32_e32 v80, v16, v16
	v_fmac_f32_e32 v81, v20, v20
	v_fmac_f32_e32 v82, v24, v24
	v_fmac_f32_e32 v83, v28, v28
	v_fmac_f32_e32 v80, v18, v18
	v_fmac_f32_e32 v81, v22, v22
	v_fmac_f32_e32 v82, v26, v26
	v_fmac_f32_e32 v83, v30, v30
	v_fmac_f32_e32 v80, v19, v19
	v_fmac_f32_e32 v81, v23, v23
	v_fmac_f32_e32 v82, v27, v27
	v_fmac_f32_e32 v83, v31, v31
	v_add_f32_e32 v84, v80, v81
	v_add_f32_e32 v84, v84, v82
	v_add_f32_e32 v84, v84, v83
	v_mov_b32_e32 v85, v84
	s_nop 1
	v_permlane32_swap_b32_e32 v84, v85
	s_nop 1
	v_add_f32_e32 v84, v84, v85
	v_mov_b32_e32 v85, v84
	s_nop 1
	v_permlane16_swap_b32_e32 v84, v85
	s_nop 1
	v_add_f32_e32 v84, v84, v85
	s_nop 1
	v_add_f32_dpp v84, v84, v84 row_mirror row_mask:0xf bank_mask:0xf
	s_nop 1
	v_add_f32_dpp v84, v84, v84 row_half_mirror row_mask:0xf bank_mask:0xf
	s_nop 1
	v_add_f32_dpp v84, v84, v84 quad_perm:[2,3,0,1] row_mask:0xf bank_mask:0xf
	s_nop 1
	v_add_f32_dpp v84, v84, v84 quad_perm:[1,0,3,2] row_mask:0xf bank_mask:0xf
	s_nop 1
	v_fmamk_f32 v84, v84, 0x3a800000, v104
	v_mul_f32_e32 v85, 0x4b800000, v84
	v_cmp_gt_f32_e32 vcc, 0x800000, v84
	s_nop 1
	v_cndmask_b32_e32 v84, v84, v85, vcc
	v_rsq_f32_e32 v84, v84
	s_nop 0
	v_mul_f32_e32 v85, 0x45800000, v84
	v_cndmask_b32_e32 v106, v84, v85, vcc
	s_waitcnt vmcnt(0)
	s_lshl_b32 s99, s98, 11
	s_add_u32 s99, s99, 0xb171900
	s_add_u32 s100, s90, s99
	s_addc_u32 s101, s91, 0
	v_pk_mul_f32 v[16:17], v[16:17], v[106:107] op_sel_hi:[1,0]
	v_pk_mul_f32 v[18:19], v[18:19], v[106:107] op_sel_hi:[1,0]
	v_pk_mul_f32 v[16:17], v[32:33], v[16:17]
	v_pk_mul_f32 v[18:19], v[34:35], v[18:19]
	v_pk_add_f32 v[48:49], v[48:49], 1.0 op_sel_hi:[1,0]
	v_pk_add_f32 v[50:51], v[50:51], 1.0 op_sel_hi:[1,0]
	v_pk_fma_f32 v[16:17], v[48:49], v[16:17], v[64:65]
	v_pk_fma_f32 v[18:19], v[50:51], v[18:19], v[66:67]
	v_cvt_pk_bf16_f32 v16, v16, v17
	v_cvt_pk_bf16_f32 v17, v18, v19
	global_store_dwordx2 v97, v[16:17], s[100:101] offset:0
	v_pk_mul_f32 v[20:21], v[20:21], v[106:107] op_sel_hi:[1,0]
	v_pk_mul_f32 v[22:23], v[22:23], v[106:107] op_sel_hi:[1,0]
	v_pk_mul_f32 v[20:21], v[36:37], v[20:21]
	v_pk_mul_f32 v[22:23], v[38:39], v[22:23]
	v_pk_add_f32 v[52:53], v[52:53], 1.0 op_sel_hi:[1,0]
	v_pk_add_f32 v[54:55], v[54:55], 1.0 op_sel_hi:[1,0]
	v_pk_fma_f32 v[20:21], v[52:53], v[20:21], v[68:69]
	v_pk_fma_f32 v[22:23], v[54:55], v[22:23], v[70:71]
	v_cvt_pk_bf16_f32 v20, v20, v21
	v_cvt_pk_bf16_f32 v21, v22, v23
	global_store_dwordx2 v97, v[20:21], s[100:101] offset:512
	v_pk_mul_f32 v[24:25], v[24:25], v[106:107] op_sel_hi:[1,0]
	v_pk_mul_f32 v[26:27], v[26:27], v[106:107] op_sel_hi:[1,0]
	v_pk_mul_f32 v[24:25], v[40:41], v[24:25]
	v_pk_mul_f32 v[26:27], v[42:43], v[26:27]
	v_pk_add_f32 v[56:57], v[56:57], 1.0 op_sel_hi:[1,0]
	v_pk_add_f32 v[58:59], v[58:59], 1.0 op_sel_hi:[1,0]
	v_pk_fma_f32 v[24:25], v[56:57], v[24:25], v[72:73]
	v_pk_fma_f32 v[26:27], v[58:59], v[26:27], v[74:75]
	v_cvt_pk_bf16_f32 v24, v24, v25
	v_cvt_pk_bf16_f32 v25, v26, v27
	global_store_dwordx2 v97, v[24:25], s[100:101] offset:1024
	v_pk_mul_f32 v[28:29], v[28:29], v[106:107] op_sel_hi:[1,0]
	v_pk_mul_f32 v[30:31], v[30:31], v[106:107] op_sel_hi:[1,0]
	v_pk_mul_f32 v[28:29], v[44:45], v[28:29]
	v_pk_mul_f32 v[30:31], v[46:47], v[30:31]
	v_pk_add_f32 v[60:61], v[60:61], 1.0 op_sel_hi:[1,0]
	v_pk_add_f32 v[62:63], v[62:63], 1.0 op_sel_hi:[1,0]
	v_pk_fma_f32 v[28:29], v[60:61], v[28:29], v[76:77]
	v_pk_fma_f32 v[30:31], v[62:63], v[30:31], v[78:79]
	v_cvt_pk_bf16_f32 v28, v28, v29
	v_cvt_pk_bf16_f32 v29, v30, v31
	global_store_dwordx2 v97, v[28:29], s[100:101] offset:1536

.LBB0_973:
	s_or_b64 exec, exec, s[0:1]
	s_add_u32 s20, s88, 0x2000000
	s_addc_u32 s21, s89, 0
	s_waitcnt lgkmcnt(0)
	s_barrier
	s_and_saveexec_b64 s[2:3], s[78:79]
	s_cbranch_execz .LBB0_980
	v_mbcnt_hi_u32_b32 v0, -1, v182
	v_and_b32_e32 v2, 64, v0
	v_add_u32_e32 v2, 64, v2
	v_xor_b32_e32 v3, 32, v0
	v_cmp_lt_i32_e32 vcc, v3, v2
	s_mov_b64 s[0:1], s[78:79]
	s_mov_b64 s[6:7], s[80:81]
	v_cndmask_b32_e32 v3, v0, v3, vcc
	s_waitcnt vmcnt(1)
	v_lshlrev_b32_e32 v18, 2, v3
	v_xor_b32_e32 v3, 16, v0
	v_cmp_lt_i32_e32 vcc, v3, v2
	v_readlane_b32 s72, v250, 3
	v_and_b32_e32 v6, 0xfc, v149
	v_cndmask_b32_e32 v3, v0, v3, vcc
	v_lshlrev_b32_e32 v19, 2, v3
	v_xor_b32_e32 v3, 8, v0
	v_cmp_lt_i32_e32 vcc, v3, v2
	v_readlane_b32 s78, v250, 9
	v_readlane_b32 s79, v250, 10
	v_cndmask_b32_e32 v3, v0, v3, vcc
	v_lshlrev_b32_e32 v20, 2, v3
	v_xor_b32_e32 v3, 4, v0
	v_cmp_lt_i32_e32 vcc, v3, v2
	v_mov_b32_e32 v1, 0
	v_readlane_b32 s76, v250, 7
	v_cndmask_b32_e32 v3, v0, v3, vcc
	v_lshlrev_b32_e32 v21, 2, v3
	v_xor_b32_e32 v3, 2, v0
	v_cmp_lt_i32_e32 vcc, v3, v2
	v_readlane_b32 s77, v250, 8
	v_readlane_b32 s82, v250, 13
	v_cndmask_b32_e32 v3, v0, v3, vcc
	v_lshlrev_b32_e32 v22, 2, v3
	v_xor_b32_e32 v3, 1, v0
	v_cmp_lt_i32_e32 vcc, v3, v2
	v_readlane_b32 s83, v250, 14
	s_mov_b64 s[78:79], s[0:1]
	v_cndmask_b32_e32 v0, v0, v3, vcc
	v_lshlrev_b32_e32 v23, 2, v0
	v_lshlrev_b32_e32 v0, 2, v6
	v_readlane_b32 s0, v250, 19
	v_readlane_b32 s80, v250, 11
	v_readlane_b32 s81, v250, 12
	v_readlane_b32 s76, v250, 25
	v_lshl_add_u64 v[2:3], s[82:83], 0, v[0:1]
	v_or_b32_e32 v8, 0x100, v6
	v_or_b32_e32 v10, 0x200, v6
	v_or_b32_e32 v12, 0x300, v6
	v_lshlrev_b32_e32 v0, 1, v6
	v_readlane_b32 s1, v250, 20
	s_lshl_b32 s12, s92, 2
	s_mov_b64 s[80:81], s[6:7]
	v_readlane_b32 s77, v250, 26
	v_lshl_add_u64 v[4:5], s[0:1], 0, v[0:1]
	s_mov_b64 s[6:7], 0
	s_movk_i32 s13, 0x2000
	s_movk_i32 s14, 0x1fff
	v_lshlrev_b32_e32 v6, 2, v6
	v_mov_b32_e32 v7, v1
	s_movk_i32 s15, 0x1800
	s_mov_b64 s[8:9], 0x4000
	s_mov_b64 s[10:11], 0x3000
	v_lshlrev_b32_e32 v8, 2, v8
	v_mov_b32_e32 v9, v1
	v_lshlrev_b32_e32 v10, 2, v10
	v_mov_b32_e32 v11, v1
	v_lshlrev_b32_e32 v12, 2, v12
	v_mov_b32_e32 v13, v1
	v_mov_b32_e32 v24, 0x358637bd
	s_mov_b32 s16, 0x800000
	s_movk_i32 s17, 0x2fff
	v_mov_b32_e32 v14, v148
	v_readlane_b32 s73, v250, 4
	v_readlane_b32 s74, v250, 5
	v_readlane_b32 s75, v250, 6
	v_readlane_b32 s84, v250, 15
	v_readlane_b32 s85, v250, 16
	v_readlane_b32 s86, v250, 17
	v_readlane_b32 s87, v250, 18
	v_mbcnt_lo_u32_b32 v80, -1, 0
	v_mbcnt_hi_u32_b32 v80, -1, v80
	v_lshlrev_b32_e32 v96, 4, v80
	v_lshlrev_b32_e32 v97, 3, v80
	v_xor_b32_e32 v98, 32, v80
	v_lshlrev_b32_e32 v98, 2, v98
	v_xor_b32_e32 v99, 16, v80
	v_lshlrev_b32_e32 v99, 2, v99
	v_xor_b32_e32 v100, 8, v80
	v_lshlrev_b32_e32 v100, 2, v100
	v_xor_b32_e32 v101, 4, v80
	v_lshlrev_b32_e32 v101, 2, v101
	v_xor_b32_e32 v102, 2, v80
	v_lshlrev_b32_e32 v102, 2, v102
	v_xor_b32_e32 v103, 1, v80
	v_lshlrev_b32_e32 v103, 2, v103
	v_mov_b32_e32 v104, 0x358637bd
	v_mov_b32_e32 v107, 0
	v_readlane_b32 s100, v250, 13
	v_readlane_b32 s101, v250, 14
	s_nop 5
	global_load_dwordx4 v[32:35], v96, s[100:101] offset:0
	global_load_dwordx4 v[36:39], v96, s[100:101] offset:1024
	global_load_dwordx4 v[40:43], v96, s[100:101] offset:2048
	global_load_dwordx4 v[44:47], v96, s[100:101] offset:3072
	v_readfirstlane_b32 s98, v148
	s_nop 3
	s_lshl_b32 s99, s98, 12
	s_add_u32 s100, s88, s99
	s_addc_u32 s101, s89, 0
	global_load_dwordx4 v[0:3], v96, s[100:101] offset:0
	global_load_dwordx4 v[4:7], v96, s[100:101] offset:1024
	global_load_dwordx4 v[8:11], v96, s[100:101] offset:2048
	global_load_dwordx4 v[12:15], v96, s[100:101] offset:3072
	s_sub_u32 s99, s98, 0x2000
	s_lshr_b32 s99, s99, 11
	s_add_u32 s99, s99, 1
	s_cmp_lt_u32 s98, 0x2000
	s_cmov_b32 s99, 0
	s_mul_i32 s99, s99, 0x6000
	s_add_u32 s99, s99, 0x3444000
	s_add_u32 s100, s90, s99
	s_addc_u32 s101, s91, 0
	global_load_dwordx4 v[48:51], v96, s[100:101] offset:0
	global_load_dwordx4 v[52:55], v96, s[100:101] offset:1024
	global_load_dwordx4 v[56:59], v96, s[100:101] offset:2048
	global_load_dwordx4 v[60:63], v96, s[100:101] offset:3072
	s_sub_u32 s99, s98, 0x2000
	s_lshr_b32 s99, s99, 11
	s_add_u32 s99, s99, 1
	s_cmp_lt_u32 s98, 0x2000
	s_cmov_b32 s99, 0
	s_mul_i32 s99, s99, 0x6000
	s_add_u32 s99, s99, 0x3443000
	s_add_u32 s100, s90, s99
	s_addc_u32 s101, s91, 0
	global_load_dwordx4 v[64:67], v96, s[100:101] offset:0
	global_load_dwordx4 v[68:71], v96, s[100:101] offset:1024
	global_load_dwordx4 v[72:75], v96, s[100:101] offset:2048
	global_load_dwordx4 v[76:79], v96, s[100:101] offset:3072
	s_add_u32 s98, s98, 0x800
	s_lshl_b32 s99, s98, 12
	s_add_u32 s100, s88, s99
	s_addc_u32 s101, s89, 0
	global_load_dwordx4 v[16:19], v96, s[100:101] offset:0
	global_load_dwordx4 v[20:23], v96, s[100:101] offset:1024
	global_load_dwordx4 v[24:27], v96, s[100:101] offset:2048
	global_load_dwordx4 v[28:31], v96, s[100:101] offset:3072
	s_sub_u32 s98, s98, 0x800
	s_waitcnt vmcnt(12)
	v_mul_f32_e32 v80, v1, v1
	v_mul_f32_e32 v81, v5, v5
	v_mul_f32_e32 v82, v9, v9
	v_mul_f32_e32 v83, v13, v13
	v_fmac_f32_e32 v80, v0, v0
	v_fmac_f32_e32 v81, v4, v4
	v_fmac_f32_e32 v82, v8, v8
	v_fmac_f32_e32 v83, v12, v12
	v_fmac_f32_e32 v80, v2, v2
	v_fmac_f32_e32 v81, v6, v6
	v_fmac_f32_e32 v82, v10, v10
	v_fmac_f32_e32 v83, v14, v14
	v_fmac_f32_e32 v80, v3, v3
	v_fmac_f32_e32 v81, v7, v7
	v_fmac_f32_e32 v82, v11, v11
	v_fmac_f32_e32 v83, v15, v15
	v_add_f32_e32 v84, v80, v81
	v_add_f32_e32 v84, v84, v82
	v_add_f32_e32 v84, v84, v83
	v_mov_b32_e32 v85, v84
	s_nop 1
	v_permlane32_swap_b32_e32 v84, v85
	s_nop 1
	v_add_f32_e32 v84, v84, v85
	v_mov_b32_e32 v85, v84
	s_nop 1
	v_permlane16_swap_b32_e32 v84, v85
	s_nop 1
	v_add_f32_e32 v84, v84, v85
	s_nop 1
	v_add_f32_dpp v84, v84, v84 row_mirror row_mask:0xf bank_mask:0xf
	s_nop 1
	v_add_f32_dpp v84, v84, v84 row_half_mirror row_mask:0xf bank_mask:0xf
	s_nop 1
	v_add_f32_dpp v84, v84, v84 quad_perm:[2,3,0,1] row_mask:0xf bank_mask:0xf
	s_nop 1
	v_add_f32_dpp v84, v84, v84 quad_perm:[1,0,3,2] row_mask:0xf bank_mask:0xf
	s_nop 1
	v_fmamk_f32 v84, v84, 0x3a800000, v104
	v_mul_f32_e32 v85, 0x4b800000, v84
	v_cmp_gt_f32_e32 vcc, 0x800000, v84
	s_nop 1
	v_cndmask_b32_e32 v84, v84, v85, vcc
	v_rsq_f32_e32 v84, v84
	s_nop 0
	v_mul_f32_e32 v85, 0x45800000, v84
	v_cndmask_b32_e32 v106, v84, v85, vcc
	s_waitcnt vmcnt(4)
	s_lshl_b32 s99, s98, 11
	s_add_u32 s99, s99, 0xb171900
	s_add_u32 s100, s90, s99
	s_addc_u32 s101, s91, 0
	v_pk_mul_f32 v[0:1], v[0:1], v[106:107] op_sel_hi:[1,0]
	v_pk_mul_f32 v[2:3], v[2:3], v[106:107] op_sel_hi:[1,0]
	v_pk_mul_f32 v[0:1], v[32:33], v[0:1]
	v_pk_mul_f32 v[2:3], v[34:35], v[2:3]
	v_pk_add_f32 v[48:49], v[48:49], 1.0 op_sel_hi:[1,0]
	v_pk_add_f32 v[50:51], v[50:51], 1.0 op_sel_hi:[1,0]
	v_pk_fma_f32 v[0:1], v[48:49], v[0:1], v[64:65]
	v_pk_fma_f32 v[2:3], v[50:51], v[2:3], v[66:67]
	v_cvt_pk_bf16_f32 v0, v0, v1
	v_cvt_pk_bf16_f32 v1, v2, v3
	global_store_dwordx2 v97, v[0:1], s[100:101] offset:0
	v_pk_mul_f32 v[4:5], v[4:5], v[106:107] op_sel_hi:[1,0]
	v_pk_mul_f32 v[6:7], v[6:7], v[106:107] op_sel_hi:[1,0]
	v_pk_mul_f32 v[4:5], v[36:37], v[4:5]
	v_pk_mul_f32 v[6:7], v[38:39], v[6:7]
	v_pk_add_f32 v[52:53], v[52:53], 1.0 op_sel_hi:[1,0]
	v_pk_add_f32 v[54:55], v[54:55], 1.0 op_sel_hi:[1,0]
	v_pk_fma_f32 v[4:5], v[52:53], v[4:5], v[68:69]
	v_pk_fma_f32 v[6:7], v[54:55], v[6:7], v[70:71]
	v_cvt_pk_bf16_f32 v4, v4, v5
	v_cvt_pk_bf16_f32 v5, v6, v7
	global_store_dwordx2 v97, v[4:5], s[100:101] offset:512
	v_pk_mul_f32 v[8:9], v[8:9], v[106:107] op_sel_hi:[1,0]
	v_pk_mul_f32 v[10:11], v[10:11], v[106:107] op_sel_hi:[1,0]
	v_pk_mul_f32 v[8:9], v[40:41], v[8:9]
	v_pk_mul_f32 v[10:11], v[42:43], v[10:11]
	v_pk_add_f32 v[56:57], v[56:57], 1.0 op_sel_hi:[1,0]
	v_pk_add_f32 v[58:59], v[58:59], 1.0 op_sel_hi:[1,0]
	v_pk_fma_f32 v[8:9], v[56:57], v[8:9], v[72:73]
	v_pk_fma_f32 v[10:11], v[58:59], v[10:11], v[74:75]
	v_cvt_pk_bf16_f32 v8, v8, v9
	v_cvt_pk_bf16_f32 v9, v10, v11
	global_store_dwordx2 v97, v[8:9], s[100:101] offset:1024
	v_pk_mul_f32 v[12:13], v[12:13], v[106:107] op_sel_hi:[1,0]
	v_pk_mul_f32 v[14:15], v[14:15], v[106:107] op_sel_hi:[1,0]
	v_pk_mul_f32 v[12:13], v[44:45], v[12:13]
	v_pk_mul_f32 v[14:15], v[46:47], v[14:15]
	v_pk_add_f32 v[60:61], v[60:61], 1.0 op_sel_hi:[1,0]
	v_pk_add_f32 v[62:63], v[62:63], 1.0 op_sel_hi:[1,0]
	v_pk_fma_f32 v[12:13], v[60:61], v[12:13], v[76:77]
	v_pk_fma_f32 v[14:15], v[62:63], v[14:15], v[78:79]
	v_cvt_pk_bf16_f32 v12, v12, v13
	v_cvt_pk_bf16_f32 v13, v14, v15
	global_store_dwordx2 v97, v[12:13], s[100:101] offset:1536
	s_add_u32 s98, s98, 0x800
	s_sub_u32 s99, s98, 0x2000
	s_lshr_b32 s99, s99, 11
	s_add_u32 s99, s99, 1
	s_cmp_lt_u32 s98, 0x2000
	s_cmov_b32 s99, 0
	s_mul_i32 s99, s99, 0x6000
	s_add_u32 s99, s99, 0x3444000
	s_add_u32 s100, s90, s99
	s_addc_u32 s101, s91, 0
	global_load_dwordx4 v[48:51], v96, s[100:101] offset:0
	global_load_dwordx4 v[52:55], v96, s[100:101] offset:1024
	global_load_dwordx4 v[56:59], v96, s[100:101] offset:2048
	global_load_dwordx4 v[60:63], v96, s[100:101] offset:3072
	s_sub_u32 s99, s98, 0x2000
	s_lshr_b32 s99, s99, 11
	s_add_u32 s99, s99, 1
	s_cmp_lt_u32 s98, 0x2000
	s_cmov_b32 s99, 0
	s_mul_i32 s99, s99, 0x6000
	s_add_u32 s99, s99, 0x3443000
	s_add_u32 s100, s90, s99
	s_addc_u32 s101, s91, 0
	global_load_dwordx4 v[64:67], v96, s[100:101] offset:0
	global_load_dwordx4 v[68:71], v96, s[100:101] offset:1024
	global_load_dwordx4 v[72:75], v96, s[100:101] offset:2048
	global_load_dwordx4 v[76:79], v96, s[100:101] offset:3072
	s_add_u32 s98, s98, 0x800
	s_lshl_b32 s99, s98, 12
	s_add_u32 s100, s88, s99
	s_addc_u32 s101, s89, 0
	global_load_dwordx4 v[0:3], v96, s[100:101] offset:0
	global_load_dwordx4 v[4:7], v96, s[100:101] offset:1024
	global_load_dwordx4 v[8:11], v96, s[100:101] offset:2048
	global_load_dwordx4 v[12:15], v96, s[100:101] offset:3072
	s_sub_u32 s98, s98, 0x800
	s_waitcnt vmcnt(16)
	v_mul_f32_e32 v80, v17, v17
	v_mul_f32_e32 v81, v21, v21
	v_mul_f32_e32 v82, v25, v25
	v_mul_f32_e32 v83, v29, v29
	v_fmac_f32_e32 v80, v16, v16
	v_fmac_f32_e32 v81, v20, v20
	v_fmac_f32_e32 v82, v24, v24
	v_fmac_f32_e32 v83, v28, v28
	v_fmac_f32_e32 v80, v18, v18
	v_fmac_f32_e32 v81, v22, v22
	v_fmac_f32_e32 v82, v26, v26
	v_fmac_f32_e32 v83, v30, v30
	v_fmac_f32_e32 v80, v19, v19
	v_fmac_f32_e32 v81, v23, v23
	v_fmac_f32_e32 v82, v27, v27
	v_fmac_f32_e32 v83, v31, v31
	v_add_f32_e32 v84, v80, v81
	v_add_f32_e32 v84, v84, v82
	v_add_f32_e32 v84, v84, v83
	v_mov_b32_e32 v85, v84
	s_nop 1
	v_permlane32_swap_b32_e32 v84, v85
	s_nop 1
	v_add_f32_e32 v84, v84, v85
	v_mov_b32_e32 v85, v84
	s_nop 1
	v_permlane16_swap_b32_e32 v84, v85
	s_nop 1
	v_add_f32_e32 v84, v84, v85
	s_nop 1
	v_add_f32_dpp v84, v84, v84 row_mirror row_mask:0xf bank_mask:0xf
	s_nop 1
	v_add_f32_dpp v84, v84, v84 row_half_mirror row_mask:0xf bank_mask:0xf
	s_nop 1
	v_add_f32_dpp v84, v84, v84 quad_perm:[2,3,0,1] row_mask:0xf bank_mask:0xf
	s_nop 1
	v_add_f32_dpp v84, v84, v84 quad_perm:[1,0,3,2] row_mask:0xf bank_mask:0xf
	s_nop 1
	v_fmamk_f32 v84, v84, 0x3a800000, v104
	v_mul_f32_e32 v85, 0x4b800000, v84
	v_cmp_gt_f32_e32 vcc, 0x800000, v84
	s_nop 1
	v_cndmask_b32_e32 v84, v84, v85, vcc
	v_rsq_f32_e32 v84, v84
	s_nop 0
	v_mul_f32_e32 v85, 0x45800000, v84
	v_cndmask_b32_e32 v106, v84, v85, vcc
	s_waitcnt vmcnt(4)
	s_lshl_b32 s99, s98, 11
	s_add_u32 s99, s99, 0xb171900
	s_add_u32 s100, s90, s99
	s_addc_u32 s101, s91, 0
	v_pk_mul_f32 v[16:17], v[16:17], v[106:107] op_sel_hi:[1,0]
	v_pk_mul_f32 v[18:19], v[18:19], v[106:107] op_sel_hi:[1,0]
	v_pk_mul_f32 v[16:17], v[32:33], v[16:17]
	v_pk_mul_f32 v[18:19], v[34:35], v[18:19]
	v_pk_add_f32 v[48:49], v[48:49], 1.0 op_sel_hi:[1,0]
	v_pk_add_f32 v[50:51], v[50:51], 1.0 op_sel_hi:[1,0]
	v_pk_fma_f32 v[16:17], v[48:49], v[16:17], v[64:65]
	v_pk_fma_f32 v[18:19], v[50:51], v[18:19], v[66:67]
	v_cvt_pk_bf16_f32 v16, v16, v17
	v_cvt_pk_bf16_f32 v17, v18, v19
	global_store_dwordx2 v97, v[16:17], s[100:101] offset:0
	v_pk_mul_f32 v[20:21], v[20:21], v[106:107] op_sel_hi:[1,0]
	v_pk_mul_f32 v[22:23], v[22:23], v[106:107] op_sel_hi:[1,0]
	v_pk_mul_f32 v[20:21], v[36:37], v[20:21]
	v_pk_mul_f32 v[22:23], v[38:39], v[22:23]
	v_pk_add_f32 v[52:53], v[52:53], 1.0 op_sel_hi:[1,0]
	v_pk_add_f32 v[54:55], v[54:55], 1.0 op_sel_hi:[1,0]
	v_pk_fma_f32 v[20:21], v[52:53], v[20:21], v[68:69]
	v_pk_fma_f32 v[22:23], v[54:55], v[22:23], v[70:71]
	v_cvt_pk_bf16_f32 v20, v20, v21
	v_cvt_pk_bf16_f32 v21, v22, v23
	global_store_dwordx2 v97, v[20:21], s[100:101] offset:512
	v_pk_mul_f32 v[24:25], v[24:25], v[106:107] op_sel_hi:[1,0]
	v_pk_mul_f32 v[26:27], v[26:27], v[106:107] op_sel_hi:[1,0]
	v_pk_mul_f32 v[24:25], v[40:41], v[24:25]
	v_pk_mul_f32 v[26:27], v[42:43], v[26:27]
	v_pk_add_f32 v[56:57], v[56:57], 1.0 op_sel_hi:[1,0]
	v_pk_add_f32 v[58:59], v[58:59], 1.0 op_sel_hi:[1,0]
	v_pk_fma_f32 v[24:25], v[56:57], v[24:25], v[72:73]
	v_pk_fma_f32 v[26:27], v[58:59], v[26:27], v[74:75]
	v_cvt_pk_bf16_f32 v24, v24, v25
	v_cvt_pk_bf16_f32 v25, v26, v27
	global_store_dwordx2 v97, v[24:25], s[100:101] offset:1024
	v_pk_mul_f32 v[28:29], v[28:29], v[106:107] op_sel_hi:[1,0]
	v_pk_mul_f32 v[30:31], v[30:31], v[106:107] op_sel_hi:[1,0]
	v_pk_mul_f32 v[28:29], v[44:45], v[28:29]
	v_pk_mul_f32 v[30:31], v[46:47], v[30:31]
	v_pk_add_f32 v[60:61], v[60:61], 1.0 op_sel_hi:[1,0]
	v_pk_add_f32 v[62:63], v[62:63], 1.0 op_sel_hi:[1,0]
	v_pk_fma_f32 v[28:29], v[60:61], v[28:29], v[76:77]
	v_pk_fma_f32 v[30:31], v[62:63], v[30:31], v[78:79]
	v_cvt_pk_bf16_f32 v28, v28, v29
	v_cvt_pk_bf16_f32 v29, v30, v31
	global_store_dwordx2 v97, v[28:29], s[100:101] offset:1536
	s_add_u32 s98, s98, 0x800
	s_sub_u32 s99, s98, 0x2000
	s_lshr_b32 s99, s99, 11
	s_add_u32 s99, s99, 1
	s_cmp_lt_u32 s98, 0x2000
	s_cmov_b32 s99, 0
	s_mul_i32 s99, s99, 0x6000
	s_add_u32 s99, s99, 0x3444000
	s_add_u32 s100, s90, s99
	s_addc_u32 s101, s91, 0
	global_load_dwordx4 v[48:51], v96, s[100:101] offset:0
	global_load_dwordx4 v[52:55], v96, s[100:101] offset:1024
	global_load_dwordx4 v[56:59], v96, s[100:101] offset:2048
	global_load_dwordx4 v[60:63], v96, s[100:101] offset:3072
	s_sub_u32 s99, s98, 0x2000
	s_lshr_b32 s99, s99, 11
	s_add_u32 s99, s99, 1
	s_cmp_lt_u32 s98, 0x2000
	s_cmov_b32 s99, 0
	s_mul_i32 s99, s99, 0x6000
	s_add_u32 s99, s99, 0x3443000
	s_add_u32 s100, s90, s99
	s_addc_u32 s101, s91, 0
	global_load_dwordx4 v[64:67], v96, s[100:101] offset:0
	global_load_dwordx4 v[68:71], v96, s[100:101] offset:1024
	global_load_dwordx4 v[72:75], v96, s[100:101] offset:2048
	global_load_dwordx4 v[76:79], v96, s[100:101] offset:3072
	s_add_u32 s98, s98, 0x800
	s_lshl_b32 s99, s98, 12
	s_add_u32 s100, s88, s99
	s_addc_u32 s101, s89, 0
	global_load_dwordx4 v[16:19], v96, s[100:101] offset:0
	global_load_dwordx4 v[20:23], v96, s[100:101] offset:1024
	global_load_dwordx4 v[24:27], v96, s[100:101] offset:2048
	global_load_dwordx4 v[28:31], v96, s[100:101] offset:3072
	s_sub_u32 s98, s98, 0x800
	s_waitcnt vmcnt(16)
	v_mul_f32_e32 v80, v1, v1
	v_mul_f32_e32 v81, v5, v5
	v_mul_f32_e32 v82, v9, v9
	v_mul_f32_e32 v83, v13, v13
	v_fmac_f32_e32 v80, v0, v0
	v_fmac_f32_e32 v81, v4, v4
	v_fmac_f32_e32 v82, v8, v8
	v_fmac_f32_e32 v83, v12, v12
	v_fmac_f32_e32 v80, v2, v2
	v_fmac_f32_e32 v81, v6, v6
	v_fmac_f32_e32 v82, v10, v10
	v_fmac_f32_e32 v83, v14, v14
	v_fmac_f32_e32 v80, v3, v3
	v_fmac_f32_e32 v81, v7, v7
	v_fmac_f32_e32 v82, v11, v11
	v_fmac_f32_e32 v83, v15, v15
	v_add_f32_e32 v84, v80, v81
	v_add_f32_e32 v84, v84, v82
	v_add_f32_e32 v84, v84, v83
	v_mov_b32_e32 v85, v84
	s_nop 1
	v_permlane32_swap_b32_e32 v84, v85
	s_nop 1
	v_add_f32_e32 v84, v84, v85
	v_mov_b32_e32 v85, v84
	s_nop 1
	v_permlane16_swap_b32_e32 v84, v85
	s_nop 1
	v_add_f32_e32 v84, v84, v85
	s_nop 1
	v_add_f32_dpp v84, v84, v84 row_mirror row_mask:0xf bank_mask:0xf
	s_nop 1
	v_add_f32_dpp v84, v84, v84 row_half_mirror row_mask:0xf bank_mask:0xf
	s_nop 1
	v_add_f32_dpp v84, v84, v84 quad_perm:[2,3,0,1] row_mask:0xf bank_mask:0xf
	s_nop 1
	v_add_f32_dpp v84, v84, v84 quad_perm:[1,0,3,2] row_mask:0xf bank_mask:0xf
	s_nop 1
	v_fmamk_f32 v84, v84, 0x3a800000, v104
	v_mul_f32_e32 v85, 0x4b800000, v84
	v_cmp_gt_f32_e32 vcc, 0x800000, v84
	s_nop 1
	v_cndmask_b32_e32 v84, v84, v85, vcc
	v_rsq_f32_e32 v84, v84
	s_nop 0
	v_mul_f32_e32 v85, 0x45800000, v84
	v_cndmask_b32_e32 v106, v84, v85, vcc
	s_waitcnt vmcnt(4)
	s_lshl_b32 s99, s98, 11
	s_add_u32 s99, s99, 0xb171900
	s_add_u32 s100, s90, s99
	s_addc_u32 s101, s91, 0
	v_pk_mul_f32 v[0:1], v[0:1], v[106:107] op_sel_hi:[1,0]
	v_pk_mul_f32 v[2:3], v[2:3], v[106:107] op_sel_hi:[1,0]
	v_pk_mul_f32 v[0:1], v[32:33], v[0:1]
	v_pk_mul_f32 v[2:3], v[34:35], v[2:3]
	v_pk_add_f32 v[48:49], v[48:49], 1.0 op_sel_hi:[1,0]
	v_pk_add_f32 v[50:51], v[50:51], 1.0 op_sel_hi:[1,0]
	v_pk_fma_f32 v[0:1], v[48:49], v[0:1], v[64:65]
	v_pk_fma_f32 v[2:3], v[50:51], v[2:3], v[66:67]
	v_cvt_pk_bf16_f32 v0, v0, v1
	v_cvt_pk_bf16_f32 v1, v2, v3
	global_store_dwordx2 v97, v[0:1], s[100:101] offset:0
	v_pk_mul_f32 v[4:5], v[4:5], v[106:107] op_sel_hi:[1,0]
	v_pk_mul_f32 v[6:7], v[6:7], v[106:107] op_sel_hi:[1,0]
	v_pk_mul_f32 v[4:5], v[36:37], v[4:5]
	v_pk_mul_f32 v[6:7], v[38:39], v[6:7]
	v_pk_add_f32 v[52:53], v[52:53], 1.0 op_sel_hi:[1,0]
	v_pk_add_f32 v[54:55], v[54:55], 1.0 op_sel_hi:[1,0]
	v_pk_fma_f32 v[4:5], v[52:53], v[4:5], v[68:69]
	v_pk_fma_f32 v[6:7], v[54:55], v[6:7], v[70:71]
	v_cvt_pk_bf16_f32 v4, v4, v5
	v_cvt_pk_bf16_f32 v5, v6, v7
	global_store_dwordx2 v97, v[4:5], s[100:101] offset:512
	v_pk_mul_f32 v[8:9], v[8:9], v[106:107] op_sel_hi:[1,0]
	v_pk_mul_f32 v[10:11], v[10:11], v[106:107] op_sel_hi:[1,0]
	v_pk_mul_f32 v[8:9], v[40:41], v[8:9]
	v_pk_mul_f32 v[10:11], v[42:43], v[10:11]
	v_pk_add_f32 v[56:57], v[56:57], 1.0 op_sel_hi:[1,0]
	v_pk_add_f32 v[58:59], v[58:59], 1.0 op_sel_hi:[1,0]
	v_pk_fma_f32 v[8:9], v[56:57], v[8:9], v[72:73]
	v_pk_fma_f32 v[10:11], v[58:59], v[10:11], v[74:75]
	v_cvt_pk_bf16_f32 v8, v8, v9
	v_cvt_pk_bf16_f32 v9, v10, v11
	global_store_dwordx2 v97, v[8:9], s[100:101] offset:1024
	v_pk_mul_f32 v[12:13], v[12:13], v[106:107] op_sel_hi:[1,0]
	v_pk_mul_f32 v[14:15], v[14:15], v[106:107] op_sel_hi:[1,0]
	v_pk_mul_f32 v[12:13], v[44:45], v[12:13]
	v_pk_mul_f32 v[14:15], v[46:47], v[14:15]
	v_pk_add_f32 v[60:61], v[60:61], 1.0 op_sel_hi:[1,0]
	v_pk_add_f32 v[62:63], v[62:63], 1.0 op_sel_hi:[1,0]
	v_pk_fma_f32 v[12:13], v[60:61], v[12:13], v[76:77]
	v_pk_fma_f32 v[14:15], v[62:63], v[14:15], v[78:79]
	v_cvt_pk_bf16_f32 v12, v12, v13
	v_cvt_pk_bf16_f32 v13, v14, v15
	global_store_dwordx2 v97, v[12:13], s[100:101] offset:1536
	s_add_u32 s98, s98, 0x800
	s_sub_u32 s99, s98, 0x2000
	s_lshr_b32 s99, s99, 11
	s_add_u32 s99, s99, 1
	s_cmp_lt_u32 s98, 0x2000
	s_cmov_b32 s99, 0
	s_mul_i32 s99, s99, 0x6000
	s_add_u32 s99, s99, 0x3444000
	s_add_u32 s100, s90, s99
	s_addc_u32 s101, s91, 0
	global_load_dwordx4 v[48:51], v96, s[100:101] offset:0
	global_load_dwordx4 v[52:55], v96, s[100:101] offset:1024
	global_load_dwordx4 v[56:59], v96, s[100:101] offset:2048
	global_load_dwordx4 v[60:63], v96, s[100:101] offset:3072
	s_sub_u32 s99, s98, 0x2000
	s_lshr_b32 s99, s99, 11
	s_add_u32 s99, s99, 1
	s_cmp_lt_u32 s98, 0x2000
	s_cmov_b32 s99, 0
	s_mul_i32 s99, s99, 0x6000
	s_add_u32 s99, s99, 0x3443000
	s_add_u32 s100, s90, s99
	s_addc_u32 s101, s91, 0
	global_load_dwordx4 v[64:67], v96, s[100:101] offset:0
	global_load_dwordx4 v[68:71], v96, s[100:101] offset:1024
	global_load_dwordx4 v[72:75], v96, s[100:101] offset:2048
	global_load_dwordx4 v[76:79], v96, s[100:101] offset:3072
	s_add_u32 s98, s98, 0x800
	s_lshl_b32 s99, s98, 12
	s_add_u32 s100, s88, s99
	s_addc_u32 s101, s89, 0
	global_load_dwordx4 v[0:3], v96, s[100:101] offset:0
	global_load_dwordx4 v[4:7], v96, s[100:101] offset:1024
	global_load_dwordx4 v[8:11], v96, s[100:101] offset:2048
	global_load_dwordx4 v[12:15], v96, s[100:101] offset:3072
	s_sub_u32 s98, s98, 0x800
	s_waitcnt vmcnt(16)
	v_mul_f32_e32 v80, v17, v17
	v_mul_f32_e32 v81, v21, v21
	v_mul_f32_e32 v82, v25, v25
	v_mul_f32_e32 v83, v29, v29
	v_fmac_f32_e32 v80, v16, v16
	v_fmac_f32_e32 v81, v20, v20
	v_fmac_f32_e32 v82, v24, v24
	v_fmac_f32_e32 v83, v28, v28
	v_fmac_f32_e32 v80, v18, v18
	v_fmac_f32_e32 v81, v22, v22
	v_fmac_f32_e32 v82, v26, v26
	v_fmac_f32_e32 v83, v30, v30
	v_fmac_f32_e32 v80, v19, v19
	v_fmac_f32_e32 v81, v23, v23
	v_fmac_f32_e32 v82, v27, v27
	v_fmac_f32_e32 v83, v31, v31
	v_add_f32_e32 v84, v80, v81
	v_add_f32_e32 v84, v84, v82
	v_add_f32_e32 v84, v84, v83
	v_mov_b32_e32 v85, v84
	s_nop 1
	v_permlane32_swap_b32_e32 v84, v85
	s_nop 1
	v_add_f32_e32 v84, v84, v85
	v_mov_b32_e32 v85, v84
	s_nop 1
	v_permlane16_swap_b32_e32 v84, v85
	s_nop 1
	v_add_f32_e32 v84, v84, v85
	s_nop 1
	v_add_f32_dpp v84, v84, v84 row_mirror row_mask:0xf bank_mask:0xf
	s_nop 1
	v_add_f32_dpp v84, v84, v84 row_half_mirror row_mask:0xf bank_mask:0xf
	s_nop 1
	v_add_f32_dpp v84, v84, v84 quad_perm:[2,3,0,1] row_mask:0xf bank_mask:0xf
	s_nop 1
	v_add_f32_dpp v84, v84, v84 quad_perm:[1,0,3,2] row_mask:0xf bank_mask:0xf
	s_nop 1
	v_fmamk_f32 v84, v84, 0x3a800000, v104
	v_mul_f32_e32 v85, 0x4b800000, v84
	v_cmp_gt_f32_e32 vcc, 0x800000, v84
	s_nop 1
	v_cndmask_b32_e32 v84, v84, v85, vcc
	v_rsq_f32_e32 v84, v84
	s_nop 0
	v_mul_f32_e32 v85, 0x45800000, v84
	v_cndmask_b32_e32 v106, v84, v85, vcc
	s_waitcnt vmcnt(4)
	s_lshl_b32 s99, s98, 11
	s_add_u32 s99, s99, 0xb171900
	s_add_u32 s100, s90, s99
	s_addc_u32 s101, s91, 0
	v_pk_mul_f32 v[16:17], v[16:17], v[106:107] op_sel_hi:[1,0]
	v_pk_mul_f32 v[18:19], v[18:19], v[106:107] op_sel_hi:[1,0]
	v_pk_mul_f32 v[16:17], v[32:33], v[16:17]
	v_pk_mul_f32 v[18:19], v[34:35], v[18:19]
	v_pk_add_f32 v[48:49], v[48:49], 1.0 op_sel_hi:[1,0]
	v_pk_add_f32 v[50:51], v[50:51], 1.0 op_sel_hi:[1,0]
	v_pk_fma_f32 v[16:17], v[48:49], v[16:17], v[64:65]
	v_pk_fma_f32 v[18:19], v[50:51], v[18:19], v[66:67]
	v_cvt_pk_bf16_f32 v16, v16, v17
	v_cvt_pk_bf16_f32 v17, v18, v19
	global_store_dwordx2 v97, v[16:17], s[100:101] offset:0
	v_pk_mul_f32 v[20:21], v[20:21], v[106:107] op_sel_hi:[1,0]
	v_pk_mul_f32 v[22:23], v[22:23], v[106:107] op_sel_hi:[1,0]
	v_pk_mul_f32 v[20:21], v[36:37], v[20:21]
	v_pk_mul_f32 v[22:23], v[38:39], v[22:23]
	v_pk_add_f32 v[52:53], v[52:53], 1.0 op_sel_hi:[1,0]
	v_pk_add_f32 v[54:55], v[54:55], 1.0 op_sel_hi:[1,0]
	v_pk_fma_f32 v[20:21], v[52:53], v[20:21], v[68:69]
	v_pk_fma_f32 v[22:23], v[54:55], v[22:23], v[70:71]
	v_cvt_pk_bf16_f32 v20, v20, v21
	v_cvt_pk_bf16_f32 v21, v22, v23
	global_store_dwordx2 v97, v[20:21], s[100:101] offset:512
	v_pk_mul_f32 v[24:25], v[24:25], v[106:107] op_sel_hi:[1,0]
	v_pk_mul_f32 v[26:27], v[26:27], v[106:107] op_sel_hi:[1,0]
	v_pk_mul_f32 v[24:25], v[40:41], v[24:25]
	v_pk_mul_f32 v[26:27], v[42:43], v[26:27]
	v_pk_add_f32 v[56:57], v[56:57], 1.0 op_sel_hi:[1,0]
	v_pk_add_f32 v[58:59], v[58:59], 1.0 op_sel_hi:[1,0]
	v_pk_fma_f32 v[24:25], v[56:57], v[24:25], v[72:73]
	v_pk_fma_f32 v[26:27], v[58:59], v[26:27], v[74:75]
	v_cvt_pk_bf16_f32 v24, v24, v25
	v_cvt_pk_bf16_f32 v25, v26, v27
	global_store_dwordx2 v97, v[24:25], s[100:101] offset:1024
	v_pk_mul_f32 v[28:29], v[28:29], v[106:107] op_sel_hi:[1,0]
	v_pk_mul_f32 v[30:31], v[30:31], v[106:107] op_sel_hi:[1,0]
	v_pk_mul_f32 v[28:29], v[44:45], v[28:29]
	v_pk_mul_f32 v[30:31], v[46:47], v[30:31]
	v_pk_add_f32 v[60:61], v[60:61], 1.0 op_sel_hi:[1,0]
	v_pk_add_f32 v[62:63], v[62:63], 1.0 op_sel_hi:[1,0]
	v_pk_fma_f32 v[28:29], v[60:61], v[28:29], v[76:77]
	v_pk_fma_f32 v[30:31], v[62:63], v[30:31], v[78:79]
	v_cvt_pk_bf16_f32 v28, v28, v29
	v_cvt_pk_bf16_f32 v29, v30, v31
	global_store_dwordx2 v97, v[28:29], s[100:101] offset:1536
	s_add_u32 s98, s98, 0x800
	s_sub_u32 s99, s98, 0x2000
	s_lshr_b32 s99, s99, 11
	s_add_u32 s99, s99, 1
	s_cmp_lt_u32 s98, 0x2000
	s_cmov_b32 s99, 0
	s_mul_i32 s99, s99, 0x6000
	s_add_u32 s99, s99, 0x3444000
	s_add_u32 s100, s90, s99
	s_addc_u32 s101, s91, 0
	global_load_dwordx4 v[48:51], v96, s[100:101] offset:0
	global_load_dwordx4 v[52:55], v96, s[100:101] offset:1024
	global_load_dwordx4 v[56:59], v96, s[100:101] offset:2048
	global_load_dwordx4 v[60:63], v96, s[100:101] offset:3072
	s_sub_u32 s99, s98, 0x2000
	s_lshr_b32 s99, s99, 11
	s_add_u32 s99, s99, 1
	s_cmp_lt_u32 s98, 0x2000
	s_cmov_b32 s99, 0
	s_mul_i32 s99, s99, 0x6000
	s_add_u32 s99, s99, 0x3443000
	s_add_u32 s100, s90, s99
	s_addc_u32 s101, s91, 0
	global_load_dwordx4 v[64:67], v96, s[100:101] offset:0
	global_load_dwordx4 v[68:71], v96, s[100:101] offset:1024
	global_load_dwordx4 v[72:75], v96, s[100:101] offset:2048
	global_load_dwordx4 v[76:79], v96, s[100:101] offset:3072
	s_add_u32 s98, s98, 0x800
	s_lshl_b32 s99, s98, 12
	s_add_u32 s100, s88, s99
	s_addc_u32 s101, s89, 0
	global_load_dwordx4 v[16:19], v96, s[100:101] offset:0
	global_load_dwordx4 v[20:23], v96, s[100:101] offset:1024
	global_load_dwordx4 v[24:27], v96, s[100:101] offset:2048
	global_load_dwordx4 v[28:31], v96, s[100:101] offset:3072
	s_sub_u32 s98, s98, 0x800
	s_waitcnt vmcnt(16)
	v_mul_f32_e32 v80, v1, v1
	v_mul_f32_e32 v81, v5, v5
	v_mul_f32_e32 v82, v9, v9
	v_mul_f32_e32 v83, v13, v13
	v_fmac_f32_e32 v80, v0, v0
	v_fmac_f32_e32 v81, v4, v4
	v_fmac_f32_e32 v82, v8, v8
	v_fmac_f32_e32 v83, v12, v12
	v_fmac_f32_e32 v80, v2, v2
	v_fmac_f32_e32 v81, v6, v6
	v_fmac_f32_e32 v82, v10, v10
	v_fmac_f32_e32 v83, v14, v14
	v_fmac_f32_e32 v80, v3, v3
	v_fmac_f32_e32 v81, v7, v7
	v_fmac_f32_e32 v82, v11, v11
	v_fmac_f32_e32 v83, v15, v15
	v_add_f32_e32 v84, v80, v81
	v_add_f32_e32 v84, v84, v82
	v_add_f32_e32 v84, v84, v83
	v_mov_b32_e32 v85, v84
	s_nop 1
	v_permlane32_swap_b32_e32 v84, v85
	s_nop 1
	v_add_f32_e32 v84, v84, v85
	v_mov_b32_e32 v85, v84
	s_nop 1
	v_permlane16_swap_b32_e32 v84, v85
	s_nop 1
	v_add_f32_e32 v84, v84, v85
	s_nop 1
	v_add_f32_dpp v84, v84, v84 row_mirror row_mask:0xf bank_mask:0xf
	s_nop 1
	v_add_f32_dpp v84, v84, v84 row_half_mirror row_mask:0xf bank_mask:0xf
	s_nop 1
	v_add_f32_dpp v84, v84, v84 quad_perm:[2,3,0,1] row_mask:0xf bank_mask:0xf
	s_nop 1
	v_add_f32_dpp v84, v84, v84 quad_perm:[1,0,3,2] row_mask:0xf bank_mask:0xf
	s_nop 1
	v_fmamk_f32 v84, v84, 0x3a800000, v104
	v_mul_f32_e32 v85, 0x4b800000, v84
	v_cmp_gt_f32_e32 vcc, 0x800000, v84
	s_nop 1
	v_cndmask_b32_e32 v84, v84, v85, vcc
	v_rsq_f32_e32 v84, v84
	s_nop 0
	v_mul_f32_e32 v85, 0x45800000, v84
	v_cndmask_b32_e32 v106, v84, v85, vcc
	s_waitcnt vmcnt(4)
	s_lshl_b32 s99, s98, 11
	s_add_u32 s99, s99, 0xb171900
	s_add_u32 s100, s90, s99
	s_addc_u32 s101, s91, 0
	v_pk_mul_f32 v[0:1], v[0:1], v[106:107] op_sel_hi:[1,0]
	v_pk_mul_f32 v[2:3], v[2:3], v[106:107] op_sel_hi:[1,0]
	v_pk_mul_f32 v[0:1], v[32:33], v[0:1]
	v_pk_mul_f32 v[2:3], v[34:35], v[2:3]
	v_pk_add_f32 v[48:49], v[48:49], 1.0 op_sel_hi:[1,0]
	v_pk_add_f32 v[50:51], v[50:51], 1.0 op_sel_hi:[1,0]
	v_pk_fma_f32 v[0:1], v[48:49], v[0:1], v[64:65]
	v_pk_fma_f32 v[2:3], v[50:51], v[2:3], v[66:67]
	v_cvt_pk_bf16_f32 v0, v0, v1
	v_cvt_pk_bf16_f32 v1, v2, v3
	global_store_dwordx2 v97, v[0:1], s[100:101] offset:0
	v_pk_mul_f32 v[4:5], v[4:5], v[106:107] op_sel_hi:[1,0]
	v_pk_mul_f32 v[6:7], v[6:7], v[106:107] op_sel_hi:[1,0]
	v_pk_mul_f32 v[4:5], v[36:37], v[4:5]
	v_pk_mul_f32 v[6:7], v[38:39], v[6:7]
	v_pk_add_f32 v[52:53], v[52:53], 1.0 op_sel_hi:[1,0]
	v_pk_add_f32 v[54:55], v[54:55], 1.0 op_sel_hi:[1,0]
	v_pk_fma_f32 v[4:5], v[52:53], v[4:5], v[68:69]
	v_pk_fma_f32 v[6:7], v[54:55], v[6:7], v[70:71]
	v_cvt_pk_bf16_f32 v4, v4, v5
	v_cvt_pk_bf16_f32 v5, v6, v7
	global_store_dwordx2 v97, v[4:5], s[100:101] offset:512
	v_pk_mul_f32 v[8:9], v[8:9], v[106:107] op_sel_hi:[1,0]
	v_pk_mul_f32 v[10:11], v[10:11], v[106:107] op_sel_hi:[1,0]
	v_pk_mul_f32 v[8:9], v[40:41], v[8:9]
	v_pk_mul_f32 v[10:11], v[42:43], v[10:11]
	v_pk_add_f32 v[56:57], v[56:57], 1.0 op_sel_hi:[1,0]
	v_pk_add_f32 v[58:59], v[58:59], 1.0 op_sel_hi:[1,0]
	v_pk_fma_f32 v[8:9], v[56:57], v[8:9], v[72:73]
	v_pk_fma_f32 v[10:11], v[58:59], v[10:11], v[74:75]
	v_cvt_pk_bf16_f32 v8, v8, v9
	v_cvt_pk_bf16_f32 v9, v10, v11
	global_store_dwordx2 v97, v[8:9], s[100:101] offset:1024
	v_pk_mul_f32 v[12:13], v[12:13], v[106:107] op_sel_hi:[1,0]
	v_pk_mul_f32 v[14:15], v[14:15], v[106:107] op_sel_hi:[1,0]
	v_pk_mul_f32 v[12:13], v[44:45], v[12:13]
	v_pk_mul_f32 v[14:15], v[46:47], v[14:15]
	v_pk_add_f32 v[60:61], v[60:61], 1.0 op_sel_hi:[1,0]
	v_pk_add_f32 v[62:63], v[62:63], 1.0 op_sel_hi:[1,0]
	v_pk_fma_f32 v[12:13], v[60:61], v[12:13], v[76:77]
	v_pk_fma_f32 v[14:15], v[62:63], v[14:15], v[78:79]
	v_cvt_pk_bf16_f32 v12, v12, v13
	v_cvt_pk_bf16_f32 v13, v14, v15
	global_store_dwordx2 v97, v[12:13], s[100:101] offset:1536
	s_add_u32 s98, s98, 0x800
	s_sub_u32 s99, s98, 0x2000
	s_lshr_b32 s99, s99, 11
	s_add_u32 s99, s99, 1
	s_cmp_lt_u32 s98, 0x2000
	s_cmov_b32 s99, 0
	s_mul_i32 s99, s99, 0x6000
	s_add_u32 s99, s99, 0x3444000
	s_add_u32 s100, s90, s99
	s_addc_u32 s101, s91, 0
	global_load_dwordx4 v[48:51], v96, s[100:101] offset:0
	global_load_dwordx4 v[52:55], v96, s[100:101] offset:1024
	global_load_dwordx4 v[56:59], v96, s[100:101] offset:2048
	global_load_dwordx4 v[60:63], v96, s[100:101] offset:3072
	s_sub_u32 s99, s98, 0x2000
	s_lshr_b32 s99, s99, 11
	s_add_u32 s99, s99, 1
	s_cmp_lt_u32 s98, 0x2000
	s_cmov_b32 s99, 0
	s_mul_i32 s99, s99, 0x6000
	s_add_u32 s99, s99, 0x3443000
	s_add_u32 s100, s90, s99
	s_addc_u32 s101, s91, 0
	global_load_dwordx4 v[64:67], v96, s[100:101] offset:0
	global_load_dwordx4 v[68:71], v96, s[100:101] offset:1024
	global_load_dwordx4 v[72:75], v96, s[100:101] offset:2048
	global_load_dwordx4 v[76:79], v96, s[100:101] offset:3072
	s_waitcnt vmcnt(12)
	v_mul_f32_e32 v80, v17, v17
	v_mul_f32_e32 v81, v21, v21
	v_mul_f32_e32 v82, v25, v25
	v_mul_f32_e32 v83, v29, v29
	v_fmac_f32_e32 v80, v16, v16
	v_fmac_f32_e32 v81, v20, v20
	v_fmac_f32_e32 v82, v24, v24
	v_fmac_f32_e32 v83, v28, v28
	v_fmac_f32_e32 v80, v18, v18
	v_fmac_f32_e32 v81, v22, v22
	v_fmac_f32_e32 v82, v26, v26
	v_fmac_f32_e32 v83, v30, v30
	v_fmac_f32_e32 v80, v19, v19
	v_fmac_f32_e32 v81, v23, v23
	v_fmac_f32_e32 v82, v27, v27
	v_fmac_f32_e32 v83, v31, v31
	v_add_f32_e32 v84, v80, v81
	v_add_f32_e32 v84, v84, v82
	v_add_f32_e32 v84, v84, v83
	v_mov_b32_e32 v85, v84
	s_nop 1
	v_permlane32_swap_b32_e32 v84, v85
	s_nop 1
	v_add_f32_e32 v84, v84, v85
	v_mov_b32_e32 v85, v84
	s_nop 1
	v_permlane16_swap_b32_e32 v84, v85
	s_nop 1
	v_add_f32_e32 v84, v84, v85
	s_nop 1
	v_add_f32_dpp v84, v84, v84 row_mirror row_mask:0xf bank_mask:0xf
	s_nop 1
	v_add_f32_dpp v84, v84, v84 row_half_mirror row_mask:0xf bank_mask:0xf
	s_nop 1
	v_add_f32_dpp v84, v84, v84 quad_perm:[2,3,0,1] row_mask:0xf bank_mask:0xf
	s_nop 1
	v_add_f32_dpp v84, v84, v84 quad_perm:[1,0,3,2] row_mask:0xf bank_mask:0xf
	s_nop 1
	v_fmamk_f32 v84, v84, 0x3a800000, v104
	v_mul_f32_e32 v85, 0x4b800000, v84
	v_cmp_gt_f32_e32 vcc, 0x800000, v84
	s_nop 1
	v_cndmask_b32_e32 v84, v84, v85, vcc
	v_rsq_f32_e32 v84, v84
	s_nop 0
	v_mul_f32_e32 v85, 0x45800000, v84
	v_cndmask_b32_e32 v106, v84, v85, vcc
	s_waitcnt vmcnt(0)
	s_lshl_b32 s99, s98, 11
	s_add_u32 s99, s99, 0xb171900
	s_add_u32 s100, s90, s99
	s_addc_u32 s101, s91, 0
	v_pk_mul_f32 v[16:17], v[16:17], v[106:107] op_sel_hi:[1,0]
	v_pk_mul_f32 v[18:19], v[18:19], v[106:107] op_sel_hi:[1,0]
	v_pk_mul_f32 v[16:17], v[32:33], v[16:17]
	v_pk_mul_f32 v[18:19], v[34:35], v[18:19]
	v_pk_add_f32 v[48:49], v[48:49], 1.0 op_sel_hi:[1,0]
	v_pk_add_f32 v[50:51], v[50:51], 1.0 op_sel_hi:[1,0]
	v_pk_fma_f32 v[16:17], v[48:49], v[16:17], v[64:65]
	v_pk_fma_f32 v[18:19], v[50:51], v[18:19], v[66:67]
	v_cvt_pk_bf16_f32 v16, v16, v17
	v_cvt_pk_bf16_f32 v17, v18, v19
	global_store_dwordx2 v97, v[16:17], s[100:101] offset:0
	v_pk_mul_f32 v[20:21], v[20:21], v[106:107] op_sel_hi:[1,0]
	v_pk_mul_f32 v[22:23], v[22:23], v[106:107] op_sel_hi:[1,0]
	v_pk_mul_f32 v[20:21], v[36:37], v[20:21]
	v_pk_mul_f32 v[22:23], v[38:39], v[22:23]
	v_pk_add_f32 v[52:53], v[52:53], 1.0 op_sel_hi:[1,0]
	v_pk_add_f32 v[54:55], v[54:55], 1.0 op_sel_hi:[1,0]
	v_pk_fma_f32 v[20:21], v[52:53], v[20:21], v[68:69]
	v_pk_fma_f32 v[22:23], v[54:55], v[22:23], v[70:71]
	v_cvt_pk_bf16_f32 v20, v20, v21
	v_cvt_pk_bf16_f32 v21, v22, v23
	global_store_dwordx2 v97, v[20:21], s[100:101] offset:512
	v_pk_mul_f32 v[24:25], v[24:25], v[106:107] op_sel_hi:[1,0]
	v_pk_mul_f32 v[26:27], v[26:27], v[106:107] op_sel_hi:[1,0]
	v_pk_mul_f32 v[24:25], v[40:41], v[24:25]
	v_pk_mul_f32 v[26:27], v[42:43], v[26:27]
	v_pk_add_f32 v[56:57], v[56:57], 1.0 op_sel_hi:[1,0]
	v_pk_add_f32 v[58:59], v[58:59], 1.0 op_sel_hi:[1,0]
	v_pk_fma_f32 v[24:25], v[56:57], v[24:25], v[72:73]
	v_pk_fma_f32 v[26:27], v[58:59], v[26:27], v[74:75]
	v_cvt_pk_bf16_f32 v24, v24, v25
	v_cvt_pk_bf16_f32 v25, v26, v27
	global_store_dwordx2 v97, v[24:25], s[100:101] offset:1024
	v_pk_mul_f32 v[28:29], v[28:29], v[106:107] op_sel_hi:[1,0]
	v_pk_mul_f32 v[30:31], v[30:31], v[106:107] op_sel_hi:[1,0]
	v_pk_mul_f32 v[28:29], v[44:45], v[28:29]
	v_pk_mul_f32 v[30:31], v[46:47], v[30:31]
	v_pk_add_f32 v[60:61], v[60:61], 1.0 op_sel_hi:[1,0]
	v_pk_add_f32 v[62:63], v[62:63], 1.0 op_sel_hi:[1,0]
	v_pk_fma_f32 v[28:29], v[60:61], v[28:29], v[76:77]
	v_pk_fma_f32 v[30:31], v[62:63], v[30:31], v[78:79]
	v_cvt_pk_bf16_f32 v28, v28, v29
	v_cvt_pk_bf16_f32 v29, v30, v31
	global_store_dwordx2 v97, v[28:29], s[100:101] offset:1536

.LBB0_1448:
	s_or_b64 exec, exec, s[0:1]
	s_add_u32 s24, s90, 0x3452000
	s_addc_u32 s25, s91, 0
	s_waitcnt lgkmcnt(0)
	s_barrier
	s_and_saveexec_b64 s[2:3], s[78:79]
	s_cbranch_execz .LBB0_1455
	v_mbcnt_hi_u32_b32 v0, -1, v182
	v_and_b32_e32 v2, 64, v0
	v_add_u32_e32 v2, 64, v2
	v_xor_b32_e32 v3, 32, v0
	v_cmp_lt_i32_e32 vcc, v3, v2
	v_readlane_b32 s44, v250, 3
	v_readlane_b32 s52, v250, 11
	v_cndmask_b32_e32 v3, v0, v3, vcc
	v_lshlrev_b32_e32 v24, 2, v3
	v_xor_b32_e32 v3, 16, v0
	v_cmp_lt_i32_e32 vcc, v3, v2
	v_readlane_b32 s53, v250, 12
	v_readlane_b32 s54, v250, 13
	v_cndmask_b32_e32 v3, v0, v3, vcc
	v_lshlrev_b32_e32 v25, 2, v3
	v_xor_b32_e32 v3, 8, v0
	v_cmp_lt_i32_e32 vcc, v3, v2
	v_readlane_b32 s55, v250, 14
	s_mov_b64 s[8:9], s[52:53]
	v_cndmask_b32_e32 v3, v0, v3, vcc
	v_lshlrev_b32_e32 v26, 2, v3
	v_xor_b32_e32 v3, 4, v0
	v_cmp_lt_i32_e32 vcc, v3, v2
	s_add_u32 s0, s8, 0x1000
	v_and_b32_e32 v12, 0xfc, v149
	v_cndmask_b32_e32 v3, v0, v3, vcc
	v_lshlrev_b32_e32 v27, 2, v3
	v_xor_b32_e32 v3, 2, v0
	v_cmp_lt_i32_e32 vcc, v3, v2
	s_addc_u32 s1, s9, 0
	v_mov_b32_e32 v1, 0
	v_cndmask_b32_e32 v3, v0, v3, vcc
	v_lshlrev_b32_e32 v28, 2, v3
	v_xor_b32_e32 v3, 1, v0
	v_cmp_lt_i32_e32 vcc, v3, v2
	v_or_b32_e32 v14, 0x100, v12
	v_or_b32_e32 v16, 0x200, v12
	v_cndmask_b32_e32 v0, v0, v3, vcc
	v_lshlrev_b32_e32 v29, 2, v0
	v_lshlrev_b32_e32 v0, 2, v12
	v_lshl_add_u64 v[2:3], s[0:1], 0, v[0:1]
	v_lshlrev_b32_e32 v0, 2, v14
	v_lshl_add_u64 v[4:5], s[0:1], 0, v[0:1]
	v_lshlrev_b32_e32 v0, 2, v16
	s_waitcnt vmcnt(1)
	v_or_b32_e32 v18, 0x300, v12
	v_lshl_add_u64 v[6:7], s[0:1], 0, v[0:1]
	v_lshlrev_b32_e32 v0, 2, v18
	v_lshl_add_u64 v[8:9], s[0:1], 0, v[0:1]
	v_readlane_b32 s0, v250, 19
	s_mov_b64 s[10:11], s[54:55]
	v_lshlrev_b32_e32 v0, 1, v12
	v_readlane_b32 s1, v250, 20
	s_mov_b64 s[6:7], 0x1000
	s_lshl_b32 s10, s92, 2
	v_lshl_add_u64 v[10:11], s[0:1], 0, v[0:1]
	s_mov_b64 s[8:9], 0
	s_movk_i32 s11, 0x2000
	s_movk_i32 s12, 0x1fff
	v_lshlrev_b32_e32 v12, 2, v12
	v_mov_b32_e32 v13, v1
	s_movk_i32 s13, 0x1800
	v_lshlrev_b32_e32 v14, 2, v14
	v_mov_b32_e32 v15, v1
	v_lshlrev_b32_e32 v16, 2, v16
	v_mov_b32_e32 v17, v1
	v_lshlrev_b32_e32 v18, 2, v18
	v_mov_b32_e32 v19, v1
	v_mov_b32_e32 v30, 0x358637bd
	s_mov_b32 s14, 0x800000
	s_movk_i32 s15, 0x2fff
	s_waitcnt vmcnt(0)
	v_mov_b32_e32 v20, v148
	v_readlane_b32 s45, v250, 4
	v_readlane_b32 s46, v250, 5
	v_readlane_b32 s47, v250, 6
	v_readlane_b32 s48, v250, 7
	v_readlane_b32 s49, v250, 8
	v_readlane_b32 s50, v250, 9
	v_readlane_b32 s51, v250, 10
	v_readlane_b32 s56, v250, 15
	v_readlane_b32 s57, v250, 16
	v_readlane_b32 s58, v250, 17
	v_readlane_b32 s59, v250, 18
	v_mbcnt_lo_u32_b32 v80, -1, 0
	v_mbcnt_hi_u32_b32 v80, -1, v80
	v_lshlrev_b32_e32 v96, 4, v80
	v_lshlrev_b32_e32 v97, 3, v80
	v_xor_b32_e32 v98, 32, v80
	v_lshlrev_b32_e32 v98, 2, v98
	v_xor_b32_e32 v99, 16, v80
	v_lshlrev_b32_e32 v99, 2, v99
	v_xor_b32_e32 v100, 8, v80
	v_lshlrev_b32_e32 v100, 2, v100
	v_xor_b32_e32 v101, 4, v80
	v_lshlrev_b32_e32 v101, 2, v101
	v_xor_b32_e32 v102, 2, v80
	v_lshlrev_b32_e32 v102, 2, v102
	v_xor_b32_e32 v103, 1, v80
	v_lshlrev_b32_e32 v103, 2, v103
	v_mov_b32_e32 v104, 0x358637bd
	v_mov_b32_e32 v107, 0
	v_readlane_b32 s100, v250, 11
	v_readlane_b32 s101, v250, 12
	s_nop 5
	s_add_u32 s100, s100, 0x1000
	s_addc_u32 s101, s101, 0
	global_load_dwordx4 v[32:35], v96, s[100:101] offset:0
	global_load_dwordx4 v[36:39], v96, s[100:101] offset:1024
	global_load_dwordx4 v[40:43], v96, s[100:101] offset:2048
	global_load_dwordx4 v[44:47], v96, s[100:101] offset:3072
	v_readfirstlane_b32 s98, v148
	s_nop 3
	s_lshl_b32 s99, s98, 12
	s_add_u32 s100, s88, s99
	s_addc_u32 s101, s89, 0
	global_load_dwordx4 v[0:3], v96, s[100:101] offset:0
	global_load_dwordx4 v[4:7], v96, s[100:101] offset:1024
	global_load_dwordx4 v[8:11], v96, s[100:101] offset:2048
	global_load_dwordx4 v[12:15], v96, s[100:101] offset:3072
	s_sub_u32 s99, s98, 0x2000
	s_lshr_b32 s99, s99, 11
	s_add_u32 s99, s99, 1
	s_cmp_lt_u32 s98, 0x2000
	s_cmov_b32 s99, 0
	s_mul_i32 s99, s99, 0x6000
	s_add_u32 s99, s99, 0x3453000
	s_add_u32 s100, s90, s99
	s_addc_u32 s101, s91, 0
	global_load_dwordx4 v[48:51], v96, s[100:101] offset:0
	global_load_dwordx4 v[52:55], v96, s[100:101] offset:1024
	global_load_dwordx4 v[56:59], v96, s[100:101] offset:2048
	global_load_dwordx4 v[60:63], v96, s[100:101] offset:3072
	s_sub_u32 s99, s98, 0x2000
	s_lshr_b32 s99, s99, 11
	s_add_u32 s99, s99, 1
	s_cmp_lt_u32 s98, 0x2000
	s_cmov_b32 s99, 0
	s_mul_i32 s99, s99, 0x6000
	s_add_u32 s99, s99, 0x3452000
	s_add_u32 s100, s90, s99
	s_addc_u32 s101, s91, 0
	global_load_dwordx4 v[64:67], v96, s[100:101] offset:0
	global_load_dwordx4 v[68:71], v96, s[100:101] offset:1024
	global_load_dwordx4 v[72:75], v96, s[100:101] offset:2048
	global_load_dwordx4 v[76:79], v96, s[100:101] offset:3072
	s_add_u32 s98, s98, 0x800
	s_lshl_b32 s99, s98, 12
	s_add_u32 s100, s88, s99
	s_addc_u32 s101, s89, 0
	global_load_dwordx4 v[16:19], v96, s[100:101] offset:0
	global_load_dwordx4 v[20:23], v96, s[100:101] offset:1024
	global_load_dwordx4 v[24:27], v96, s[100:101] offset:2048
	global_load_dwordx4 v[28:31], v96, s[100:101] offset:3072
	s_sub_u32 s98, s98, 0x800
	s_waitcnt vmcnt(12)
	v_mul_f32_e32 v80, v1, v1
	v_mul_f32_e32 v81, v5, v5
	v_mul_f32_e32 v82, v9, v9
	v_mul_f32_e32 v83, v13, v13
	v_fmac_f32_e32 v80, v0, v0
	v_fmac_f32_e32 v81, v4, v4
	v_fmac_f32_e32 v82, v8, v8
	v_fmac_f32_e32 v83, v12, v12
	v_fmac_f32_e32 v80, v2, v2
	v_fmac_f32_e32 v81, v6, v6
	v_fmac_f32_e32 v82, v10, v10
	v_fmac_f32_e32 v83, v14, v14
	v_fmac_f32_e32 v80, v3, v3
	v_fmac_f32_e32 v81, v7, v7
	v_fmac_f32_e32 v82, v11, v11
	v_fmac_f32_e32 v83, v15, v15
	v_add_f32_e32 v84, v80, v81
	v_add_f32_e32 v84, v84, v82
	v_add_f32_e32 v84, v84, v83
	v_mov_b32_e32 v85, v84
	s_nop 1
	v_permlane32_swap_b32_e32 v84, v85
	s_nop 1
	v_add_f32_e32 v84, v84, v85
	v_mov_b32_e32 v85, v84
	s_nop 1
	v_permlane16_swap_b32_e32 v84, v85
	s_nop 1
	v_add_f32_e32 v84, v84, v85
	s_nop 1
	v_add_f32_dpp v84, v84, v84 row_mirror row_mask:0xf bank_mask:0xf
	s_nop 1
	v_add_f32_dpp v84, v84, v84 row_half_mirror row_mask:0xf bank_mask:0xf
	s_nop 1
	v_add_f32_dpp v84, v84, v84 quad_perm:[2,3,0,1] row_mask:0xf bank_mask:0xf
	s_nop 1
	v_add_f32_dpp v84, v84, v84 quad_perm:[1,0,3,2] row_mask:0xf bank_mask:0xf
	s_nop 1
	v_fmamk_f32 v84, v84, 0x3a800000, v104
	v_mul_f32_e32 v85, 0x4b800000, v84
	v_cmp_gt_f32_e32 vcc, 0x800000, v84
	s_nop 1
	v_cndmask_b32_e32 v84, v84, v85, vcc
	v_rsq_f32_e32 v84, v84
	s_nop 0
	v_mul_f32_e32 v85, 0x45800000, v84
	v_cndmask_b32_e32 v106, v84, v85, vcc
	s_waitcnt vmcnt(4)
	s_lshl_b32 s99, s98, 11
	s_add_u32 s99, s99, 0xb171900
	s_add_u32 s100, s90, s99
	s_addc_u32 s101, s91, 0
	v_pk_mul_f32 v[0:1], v[0:1], v[106:107] op_sel_hi:[1,0]
	v_pk_mul_f32 v[2:3], v[2:3], v[106:107] op_sel_hi:[1,0]
	v_pk_mul_f32 v[0:1], v[32:33], v[0:1]
	v_pk_mul_f32 v[2:3], v[34:35], v[2:3]
	v_pk_add_f32 v[48:49], v[48:49], 1.0 op_sel_hi:[1,0]
	v_pk_add_f32 v[50:51], v[50:51], 1.0 op_sel_hi:[1,0]
	v_pk_fma_f32 v[0:1], v[48:49], v[0:1], v[64:65]
	v_pk_fma_f32 v[2:3], v[50:51], v[2:3], v[66:67]
	v_cvt_pk_bf16_f32 v0, v0, v1
	v_cvt_pk_bf16_f32 v1, v2, v3
	global_store_dwordx2 v97, v[0:1], s[100:101] offset:0
	v_pk_mul_f32 v[4:5], v[4:5], v[106:107] op_sel_hi:[1,0]
	v_pk_mul_f32 v[6:7], v[6:7], v[106:107] op_sel_hi:[1,0]
	v_pk_mul_f32 v[4:5], v[36:37], v[4:5]
	v_pk_mul_f32 v[6:7], v[38:39], v[6:7]
	v_pk_add_f32 v[52:53], v[52:53], 1.0 op_sel_hi:[1,0]
	v_pk_add_f32 v[54:55], v[54:55], 1.0 op_sel_hi:[1,0]
	v_pk_fma_f32 v[4:5], v[52:53], v[4:5], v[68:69]
	v_pk_fma_f32 v[6:7], v[54:55], v[6:7], v[70:71]
	v_cvt_pk_bf16_f32 v4, v4, v5
	v_cvt_pk_bf16_f32 v5, v6, v7
	global_store_dwordx2 v97, v[4:5], s[100:101] offset:512
	v_pk_mul_f32 v[8:9], v[8:9], v[106:107] op_sel_hi:[1,0]
	v_pk_mul_f32 v[10:11], v[10:11], v[106:107] op_sel_hi:[1,0]
	v_pk_mul_f32 v[8:9], v[40:41], v[8:9]
	v_pk_mul_f32 v[10:11], v[42:43], v[10:11]
	v_pk_add_f32 v[56:57], v[56:57], 1.0 op_sel_hi:[1,0]
	v_pk_add_f32 v[58:59], v[58:59], 1.0 op_sel_hi:[1,0]
	v_pk_fma_f32 v[8:9], v[56:57], v[8:9], v[72:73]
	v_pk_fma_f32 v[10:11], v[58:59], v[10:11], v[74:75]
	v_cvt_pk_bf16_f32 v8, v8, v9
	v_cvt_pk_bf16_f32 v9, v10, v11
	global_store_dwordx2 v97, v[8:9], s[100:101] offset:1024
	v_pk_mul_f32 v[12:13], v[12:13], v[106:107] op_sel_hi:[1,0]
	v_pk_mul_f32 v[14:15], v[14:15], v[106:107] op_sel_hi:[1,0]
	v_pk_mul_f32 v[12:13], v[44:45], v[12:13]
	v_pk_mul_f32 v[14:15], v[46:47], v[14:15]
	v_pk_add_f32 v[60:61], v[60:61], 1.0 op_sel_hi:[1,0]
	v_pk_add_f32 v[62:63], v[62:63], 1.0 op_sel_hi:[1,0]
	v_pk_fma_f32 v[12:13], v[60:61], v[12:13], v[76:77]
	v_pk_fma_f32 v[14:15], v[62:63], v[14:15], v[78:79]
	v_cvt_pk_bf16_f32 v12, v12, v13
	v_cvt_pk_bf16_f32 v13, v14, v15
	global_store_dwordx2 v97, v[12:13], s[100:101] offset:1536
	s_add_u32 s98, s98, 0x800
	s_sub_u32 s99, s98, 0x2000
	s_lshr_b32 s99, s99, 11
	s_add_u32 s99, s99, 1
	s_cmp_lt_u32 s98, 0x2000
	s_cmov_b32 s99, 0
	s_mul_i32 s99, s99, 0x6000
	s_add_u32 s99, s99, 0x3453000
	s_add_u32 s100, s90, s99
	s_addc_u32 s101, s91, 0
	global_load_dwordx4 v[48:51], v96, s[100:101] offset:0
	global_load_dwordx4 v[52:55], v96, s[100:101] offset:1024
	global_load_dwordx4 v[56:59], v96, s[100:101] offset:2048
	global_load_dwordx4 v[60:63], v96, s[100:101] offset:3072
	s_sub_u32 s99, s98, 0x2000
	s_lshr_b32 s99, s99, 11
	s_add_u32 s99, s99, 1
	s_cmp_lt_u32 s98, 0x2000
	s_cmov_b32 s99, 0
	s_mul_i32 s99, s99, 0x6000
	s_add_u32 s99, s99, 0x3452000
	s_add_u32 s100, s90, s99
	s_addc_u32 s101, s91, 0
	global_load_dwordx4 v[64:67], v96, s[100:101] offset:0
	global_load_dwordx4 v[68:71], v96, s[100:101] offset:1024
	global_load_dwordx4 v[72:75], v96, s[100:101] offset:2048
	global_load_dwordx4 v[76:79], v96, s[100:101] offset:3072
	s_add_u32 s98, s98, 0x800
	s_lshl_b32 s99, s98, 12
	s_add_u32 s100, s88, s99
	s_addc_u32 s101, s89, 0
	global_load_dwordx4 v[0:3], v96, s[100:101] offset:0
	global_load_dwordx4 v[4:7], v96, s[100:101] offset:1024
	global_load_dwordx4 v[8:11], v96, s[100:101] offset:2048
	global_load_dwordx4 v[12:15], v96, s[100:101] offset:3072
	s_sub_u32 s98, s98, 0x800
	s_waitcnt vmcnt(16)
	v_mul_f32_e32 v80, v17, v17
	v_mul_f32_e32 v81, v21, v21
	v_mul_f32_e32 v82, v25, v25
	v_mul_f32_e32 v83, v29, v29
	v_fmac_f32_e32 v80, v16, v16
	v_fmac_f32_e32 v81, v20, v20
	v_fmac_f32_e32 v82, v24, v24
	v_fmac_f32_e32 v83, v28, v28
	v_fmac_f32_e32 v80, v18, v18
	v_fmac_f32_e32 v81, v22, v22
	v_fmac_f32_e32 v82, v26, v26
	v_fmac_f32_e32 v83, v30, v30
	v_fmac_f32_e32 v80, v19, v19
	v_fmac_f32_e32 v81, v23, v23
	v_fmac_f32_e32 v82, v27, v27
	v_fmac_f32_e32 v83, v31, v31
	v_add_f32_e32 v84, v80, v81
	v_add_f32_e32 v84, v84, v82
	v_add_f32_e32 v84, v84, v83
	v_mov_b32_e32 v85, v84
	s_nop 1
	v_permlane32_swap_b32_e32 v84, v85
	s_nop 1
	v_add_f32_e32 v84, v84, v85
	v_mov_b32_e32 v85, v84
	s_nop 1
	v_permlane16_swap_b32_e32 v84, v85
	s_nop 1
	v_add_f32_e32 v84, v84, v85
	s_nop 1
	v_add_f32_dpp v84, v84, v84 row_mirror row_mask:0xf bank_mask:0xf
	s_nop 1
	v_add_f32_dpp v84, v84, v84 row_half_mirror row_mask:0xf bank_mask:0xf
	s_nop 1
	v_add_f32_dpp v84, v84, v84 quad_perm:[2,3,0,1] row_mask:0xf bank_mask:0xf
	s_nop 1
	v_add_f32_dpp v84, v84, v84 quad_perm:[1,0,3,2] row_mask:0xf bank_mask:0xf
	s_nop 1
	v_fmamk_f32 v84, v84, 0x3a800000, v104
	v_mul_f32_e32 v85, 0x4b800000, v84
	v_cmp_gt_f32_e32 vcc, 0x800000, v84
	s_nop 1
	v_cndmask_b32_e32 v84, v84, v85, vcc
	v_rsq_f32_e32 v84, v84
	s_nop 0
	v_mul_f32_e32 v85, 0x45800000, v84
	v_cndmask_b32_e32 v106, v84, v85, vcc
	s_waitcnt vmcnt(4)
	s_lshl_b32 s99, s98, 11
	s_add_u32 s99, s99, 0xb171900
	s_add_u32 s100, s90, s99
	s_addc_u32 s101, s91, 0
	v_pk_mul_f32 v[16:17], v[16:17], v[106:107] op_sel_hi:[1,0]
	v_pk_mul_f32 v[18:19], v[18:19], v[106:107] op_sel_hi:[1,0]
	v_pk_mul_f32 v[16:17], v[32:33], v[16:17]
	v_pk_mul_f32 v[18:19], v[34:35], v[18:19]
	v_pk_add_f32 v[48:49], v[48:49], 1.0 op_sel_hi:[1,0]
	v_pk_add_f32 v[50:51], v[50:51], 1.0 op_sel_hi:[1,0]
	v_pk_fma_f32 v[16:17], v[48:49], v[16:17], v[64:65]
	v_pk_fma_f32 v[18:19], v[50:51], v[18:19], v[66:67]
	v_cvt_pk_bf16_f32 v16, v16, v17
	v_cvt_pk_bf16_f32 v17, v18, v19
	global_store_dwordx2 v97, v[16:17], s[100:101] offset:0
	v_pk_mul_f32 v[20:21], v[20:21], v[106:107] op_sel_hi:[1,0]
	v_pk_mul_f32 v[22:23], v[22:23], v[106:107] op_sel_hi:[1,0]
	v_pk_mul_f32 v[20:21], v[36:37], v[20:21]
	v_pk_mul_f32 v[22:23], v[38:39], v[22:23]
	v_pk_add_f32 v[52:53], v[52:53], 1.0 op_sel_hi:[1,0]
	v_pk_add_f32 v[54:55], v[54:55], 1.0 op_sel_hi:[1,0]
	v_pk_fma_f32 v[20:21], v[52:53], v[20:21], v[68:69]
	v_pk_fma_f32 v[22:23], v[54:55], v[22:23], v[70:71]
	v_cvt_pk_bf16_f32 v20, v20, v21
	v_cvt_pk_bf16_f32 v21, v22, v23
	global_store_dwordx2 v97, v[20:21], s[100:101] offset:512
	v_pk_mul_f32 v[24:25], v[24:25], v[106:107] op_sel_hi:[1,0]
	v_pk_mul_f32 v[26:27], v[26:27], v[106:107] op_sel_hi:[1,0]
	v_pk_mul_f32 v[24:25], v[40:41], v[24:25]
	v_pk_mul_f32 v[26:27], v[42:43], v[26:27]
	v_pk_add_f32 v[56:57], v[56:57], 1.0 op_sel_hi:[1,0]
	v_pk_add_f32 v[58:59], v[58:59], 1.0 op_sel_hi:[1,0]
	v_pk_fma_f32 v[24:25], v[56:57], v[24:25], v[72:73]
	v_pk_fma_f32 v[26:27], v[58:59], v[26:27], v[74:75]
	v_cvt_pk_bf16_f32 v24, v24, v25
	v_cvt_pk_bf16_f32 v25, v26, v27
	global_store_dwordx2 v97, v[24:25], s[100:101] offset:1024
	v_pk_mul_f32 v[28:29], v[28:29], v[106:107] op_sel_hi:[1,0]
	v_pk_mul_f32 v[30:31], v[30:31], v[106:107] op_sel_hi:[1,0]
	v_pk_mul_f32 v[28:29], v[44:45], v[28:29]
	v_pk_mul_f32 v[30:31], v[46:47], v[30:31]
	v_pk_add_f32 v[60:61], v[60:61], 1.0 op_sel_hi:[1,0]
	v_pk_add_f32 v[62:63], v[62:63], 1.0 op_sel_hi:[1,0]
	v_pk_fma_f32 v[28:29], v[60:61], v[28:29], v[76:77]
	v_pk_fma_f32 v[30:31], v[62:63], v[30:31], v[78:79]
	v_cvt_pk_bf16_f32 v28, v28, v29
	v_cvt_pk_bf16_f32 v29, v30, v31
	global_store_dwordx2 v97, v[28:29], s[100:101] offset:1536
	s_add_u32 s98, s98, 0x800
	s_sub_u32 s99, s98, 0x2000
	s_lshr_b32 s99, s99, 11
	s_add_u32 s99, s99, 1
	s_cmp_lt_u32 s98, 0x2000
	s_cmov_b32 s99, 0
	s_mul_i32 s99, s99, 0x6000
	s_add_u32 s99, s99, 0x3453000
	s_add_u32 s100, s90, s99
	s_addc_u32 s101, s91, 0
	global_load_dwordx4 v[48:51], v96, s[100:101] offset:0
	global_load_dwordx4 v[52:55], v96, s[100:101] offset:1024
	global_load_dwordx4 v[56:59], v96, s[100:101] offset:2048
	global_load_dwordx4 v[60:63], v96, s[100:101] offset:3072
	s_sub_u32 s99, s98, 0x2000
	s_lshr_b32 s99, s99, 11
	s_add_u32 s99, s99, 1
	s_cmp_lt_u32 s98, 0x2000
	s_cmov_b32 s99, 0
	s_mul_i32 s99, s99, 0x6000
	s_add_u32 s99, s99, 0x3452000
	s_add_u32 s100, s90, s99
	s_addc_u32 s101, s91, 0
	global_load_dwordx4 v[64:67], v96, s[100:101] offset:0
	global_load_dwordx4 v[68:71], v96, s[100:101] offset:1024
	global_load_dwordx4 v[72:75], v96, s[100:101] offset:2048
	global_load_dwordx4 v[76:79], v96, s[100:101] offset:3072
	s_add_u32 s98, s98, 0x800
	s_lshl_b32 s99, s98, 12
	s_add_u32 s100, s88, s99
	s_addc_u32 s101, s89, 0
	global_load_dwordx4 v[16:19], v96, s[100:101] offset:0
	global_load_dwordx4 v[20:23], v96, s[100:101] offset:1024
	global_load_dwordx4 v[24:27], v96, s[100:101] offset:2048
	global_load_dwordx4 v[28:31], v96, s[100:101] offset:3072
	s_sub_u32 s98, s98, 0x800
	s_waitcnt vmcnt(16)
	v_mul_f32_e32 v80, v1, v1
	v_mul_f32_e32 v81, v5, v5
	v_mul_f32_e32 v82, v9, v9
	v_mul_f32_e32 v83, v13, v13
	v_fmac_f32_e32 v80, v0, v0
	v_fmac_f32_e32 v81, v4, v4
	v_fmac_f32_e32 v82, v8, v8
	v_fmac_f32_e32 v83, v12, v12
	v_fmac_f32_e32 v80, v2, v2
	v_fmac_f32_e32 v81, v6, v6
	v_fmac_f32_e32 v82, v10, v10
	v_fmac_f32_e32 v83, v14, v14
	v_fmac_f32_e32 v80, v3, v3
	v_fmac_f32_e32 v81, v7, v7
	v_fmac_f32_e32 v82, v11, v11
	v_fmac_f32_e32 v83, v15, v15
	v_add_f32_e32 v84, v80, v81
	v_add_f32_e32 v84, v84, v82
	v_add_f32_e32 v84, v84, v83
	v_mov_b32_e32 v85, v84
	s_nop 1
	v_permlane32_swap_b32_e32 v84, v85
	s_nop 1
	v_add_f32_e32 v84, v84, v85
	v_mov_b32_e32 v85, v84
	s_nop 1
	v_permlane16_swap_b32_e32 v84, v85
	s_nop 1
	v_add_f32_e32 v84, v84, v85
	s_nop 1
	v_add_f32_dpp v84, v84, v84 row_mirror row_mask:0xf bank_mask:0xf
	s_nop 1
	v_add_f32_dpp v84, v84, v84 row_half_mirror row_mask:0xf bank_mask:0xf
	s_nop 1
	v_add_f32_dpp v84, v84, v84 quad_perm:[2,3,0,1] row_mask:0xf bank_mask:0xf
	s_nop 1
	v_add_f32_dpp v84, v84, v84 quad_perm:[1,0,3,2] row_mask:0xf bank_mask:0xf
	s_nop 1
	v_fmamk_f32 v84, v84, 0x3a800000, v104
	v_mul_f32_e32 v85, 0x4b800000, v84
	v_cmp_gt_f32_e32 vcc, 0x800000, v84
	s_nop 1
	v_cndmask_b32_e32 v84, v84, v85, vcc
	v_rsq_f32_e32 v84, v84
	s_nop 0
	v_mul_f32_e32 v85, 0x45800000, v84
	v_cndmask_b32_e32 v106, v84, v85, vcc
	s_waitcnt vmcnt(4)
	s_lshl_b32 s99, s98, 11
	s_add_u32 s99, s99, 0xb171900
	s_add_u32 s100, s90, s99
	s_addc_u32 s101, s91, 0
	v_pk_mul_f32 v[0:1], v[0:1], v[106:107] op_sel_hi:[1,0]
	v_pk_mul_f32 v[2:3], v[2:3], v[106:107] op_sel_hi:[1,0]
	v_pk_mul_f32 v[0:1], v[32:33], v[0:1]
	v_pk_mul_f32 v[2:3], v[34:35], v[2:3]
	v_pk_add_f32 v[48:49], v[48:49], 1.0 op_sel_hi:[1,0]
	v_pk_add_f32 v[50:51], v[50:51], 1.0 op_sel_hi:[1,0]
	v_pk_fma_f32 v[0:1], v[48:49], v[0:1], v[64:65]
	v_pk_fma_f32 v[2:3], v[50:51], v[2:3], v[66:67]
	v_cvt_pk_bf16_f32 v0, v0, v1
	v_cvt_pk_bf16_f32 v1, v2, v3
	global_store_dwordx2 v97, v[0:1], s[100:101] offset:0
	v_pk_mul_f32 v[4:5], v[4:5], v[106:107] op_sel_hi:[1,0]
	v_pk_mul_f32 v[6:7], v[6:7], v[106:107] op_sel_hi:[1,0]
	v_pk_mul_f32 v[4:5], v[36:37], v[4:5]
	v_pk_mul_f32 v[6:7], v[38:39], v[6:7]
	v_pk_add_f32 v[52:53], v[52:53], 1.0 op_sel_hi:[1,0]
	v_pk_add_f32 v[54:55], v[54:55], 1.0 op_sel_hi:[1,0]
	v_pk_fma_f32 v[4:5], v[52:53], v[4:5], v[68:69]
	v_pk_fma_f32 v[6:7], v[54:55], v[6:7], v[70:71]
	v_cvt_pk_bf16_f32 v4, v4, v5
	v_cvt_pk_bf16_f32 v5, v6, v7
	global_store_dwordx2 v97, v[4:5], s[100:101] offset:512
	v_pk_mul_f32 v[8:9], v[8:9], v[106:107] op_sel_hi:[1,0]
	v_pk_mul_f32 v[10:11], v[10:11], v[106:107] op_sel_hi:[1,0]
	v_pk_mul_f32 v[8:9], v[40:41], v[8:9]
	v_pk_mul_f32 v[10:11], v[42:43], v[10:11]
	v_pk_add_f32 v[56:57], v[56:57], 1.0 op_sel_hi:[1,0]
	v_pk_add_f32 v[58:59], v[58:59], 1.0 op_sel_hi:[1,0]
	v_pk_fma_f32 v[8:9], v[56:57], v[8:9], v[72:73]
	v_pk_fma_f32 v[10:11], v[58:59], v[10:11], v[74:75]
	v_cvt_pk_bf16_f32 v8, v8, v9
	v_cvt_pk_bf16_f32 v9, v10, v11
	global_store_dwordx2 v97, v[8:9], s[100:101] offset:1024
	v_pk_mul_f32 v[12:13], v[12:13], v[106:107] op_sel_hi:[1,0]
	v_pk_mul_f32 v[14:15], v[14:15], v[106:107] op_sel_hi:[1,0]
	v_pk_mul_f32 v[12:13], v[44:45], v[12:13]
	v_pk_mul_f32 v[14:15], v[46:47], v[14:15]
	v_pk_add_f32 v[60:61], v[60:61], 1.0 op_sel_hi:[1,0]
	v_pk_add_f32 v[62:63], v[62:63], 1.0 op_sel_hi:[1,0]
	v_pk_fma_f32 v[12:13], v[60:61], v[12:13], v[76:77]
	v_pk_fma_f32 v[14:15], v[62:63], v[14:15], v[78:79]
	v_cvt_pk_bf16_f32 v12, v12, v13
	v_cvt_pk_bf16_f32 v13, v14, v15
	global_store_dwordx2 v97, v[12:13], s[100:101] offset:1536
	s_add_u32 s98, s98, 0x800
	s_sub_u32 s99, s98, 0x2000
	s_lshr_b32 s99, s99, 11
	s_add_u32 s99, s99, 1
	s_cmp_lt_u32 s98, 0x2000
	s_cmov_b32 s99, 0
	s_mul_i32 s99, s99, 0x6000
	s_add_u32 s99, s99, 0x3453000
	s_add_u32 s100, s90, s99
	s_addc_u32 s101, s91, 0
	global_load_dwordx4 v[48:51], v96, s[100:101] offset:0
	global_load_dwordx4 v[52:55], v96, s[100:101] offset:1024
	global_load_dwordx4 v[56:59], v96, s[100:101] offset:2048
	global_load_dwordx4 v[60:63], v96, s[100:101] offset:3072
	s_sub_u32 s99, s98, 0x2000
	s_lshr_b32 s99, s99, 11
	s_add_u32 s99, s99, 1
	s_cmp_lt_u32 s98, 0x2000
	s_cmov_b32 s99, 0
	s_mul_i32 s99, s99, 0x6000
	s_add_u32 s99, s99, 0x3452000
	s_add_u32 s100, s90, s99
	s_addc_u32 s101, s91, 0
	global_load_dwordx4 v[64:67], v96, s[100:101] offset:0
	global_load_dwordx4 v[68:71], v96, s[100:101] offset:1024
	global_load_dwordx4 v[72:75], v96, s[100:101] offset:2048
	global_load_dwordx4 v[76:79], v96, s[100:101] offset:3072
	s_add_u32 s98, s98, 0x800
	s_lshl_b32 s99, s98, 12
	s_add_u32 s100, s88, s99
	s_addc_u32 s101, s89, 0
	global_load_dwordx4 v[0:3], v96, s[100:101] offset:0
	global_load_dwordx4 v[4:7], v96, s[100:101] offset:1024
	global_load_dwordx4 v[8:11], v96, s[100:101] offset:2048
	global_load_dwordx4 v[12:15], v96, s[100:101] offset:3072
	s_sub_u32 s98, s98, 0x800
	s_waitcnt vmcnt(16)
	v_mul_f32_e32 v80, v17, v17
	v_mul_f32_e32 v81, v21, v21
	v_mul_f32_e32 v82, v25, v25
	v_mul_f32_e32 v83, v29, v29
	v_fmac_f32_e32 v80, v16, v16
	v_fmac_f32_e32 v81, v20, v20
	v_fmac_f32_e32 v82, v24, v24
	v_fmac_f32_e32 v83, v28, v28
	v_fmac_f32_e32 v80, v18, v18
	v_fmac_f32_e32 v81, v22, v22
	v_fmac_f32_e32 v82, v26, v26
	v_fmac_f32_e32 v83, v30, v30
	v_fmac_f32_e32 v80, v19, v19
	v_fmac_f32_e32 v81, v23, v23
	v_fmac_f32_e32 v82, v27, v27
	v_fmac_f32_e32 v83, v31, v31
	v_add_f32_e32 v84, v80, v81
	v_add_f32_e32 v84, v84, v82
	v_add_f32_e32 v84, v84, v83
	v_mov_b32_e32 v85, v84
	s_nop 1
	v_permlane32_swap_b32_e32 v84, v85
	s_nop 1
	v_add_f32_e32 v84, v84, v85
	v_mov_b32_e32 v85, v84
	s_nop 1
	v_permlane16_swap_b32_e32 v84, v85
	s_nop 1
	v_add_f32_e32 v84, v84, v85
	s_nop 1
	v_add_f32_dpp v84, v84, v84 row_mirror row_mask:0xf bank_mask:0xf
	s_nop 1
	v_add_f32_dpp v84, v84, v84 row_half_mirror row_mask:0xf bank_mask:0xf
	s_nop 1
	v_add_f32_dpp v84, v84, v84 quad_perm:[2,3,0,1] row_mask:0xf bank_mask:0xf
	s_nop 1
	v_add_f32_dpp v84, v84, v84 quad_perm:[1,0,3,2] row_mask:0xf bank_mask:0xf
	s_nop 1
	v_fmamk_f32 v84, v84, 0x3a800000, v104
	v_mul_f32_e32 v85, 0x4b800000, v84
	v_cmp_gt_f32_e32 vcc, 0x800000, v84
	s_nop 1
	v_cndmask_b32_e32 v84, v84, v85, vcc
	v_rsq_f32_e32 v84, v84
	s_nop 0
	v_mul_f32_e32 v85, 0x45800000, v84
	v_cndmask_b32_e32 v106, v84, v85, vcc
	s_waitcnt vmcnt(4)
	s_lshl_b32 s99, s98, 11
	s_add_u32 s99, s99, 0xb171900
	s_add_u32 s100, s90, s99
	s_addc_u32 s101, s91, 0
	v_pk_mul_f32 v[16:17], v[16:17], v[106:107] op_sel_hi:[1,0]
	v_pk_mul_f32 v[18:19], v[18:19], v[106:107] op_sel_hi:[1,0]
	v_pk_mul_f32 v[16:17], v[32:33], v[16:17]
	v_pk_mul_f32 v[18:19], v[34:35], v[18:19]
	v_pk_add_f32 v[48:49], v[48:49], 1.0 op_sel_hi:[1,0]
	v_pk_add_f32 v[50:51], v[50:51], 1.0 op_sel_hi:[1,0]
	v_pk_fma_f32 v[16:17], v[48:49], v[16:17], v[64:65]
	v_pk_fma_f32 v[18:19], v[50:51], v[18:19], v[66:67]
	v_cvt_pk_bf16_f32 v16, v16, v17
	v_cvt_pk_bf16_f32 v17, v18, v19
	global_store_dwordx2 v97, v[16:17], s[100:101] offset:0
	v_pk_mul_f32 v[20:21], v[20:21], v[106:107] op_sel_hi:[1,0]
	v_pk_mul_f32 v[22:23], v[22:23], v[106:107] op_sel_hi:[1,0]
	v_pk_mul_f32 v[20:21], v[36:37], v[20:21]
	v_pk_mul_f32 v[22:23], v[38:39], v[22:23]
	v_pk_add_f32 v[52:53], v[52:53], 1.0 op_sel_hi:[1,0]
	v_pk_add_f32 v[54:55], v[54:55], 1.0 op_sel_hi:[1,0]
	v_pk_fma_f32 v[20:21], v[52:53], v[20:21], v[68:69]
	v_pk_fma_f32 v[22:23], v[54:55], v[22:23], v[70:71]
	v_cvt_pk_bf16_f32 v20, v20, v21
	v_cvt_pk_bf16_f32 v21, v22, v23
	global_store_dwordx2 v97, v[20:21], s[100:101] offset:512
	v_pk_mul_f32 v[24:25], v[24:25], v[106:107] op_sel_hi:[1,0]
	v_pk_mul_f32 v[26:27], v[26:27], v[106:107] op_sel_hi:[1,0]
	v_pk_mul_f32 v[24:25], v[40:41], v[24:25]
	v_pk_mul_f32 v[26:27], v[42:43], v[26:27]
	v_pk_add_f32 v[56:57], v[56:57], 1.0 op_sel_hi:[1,0]
	v_pk_add_f32 v[58:59], v[58:59], 1.0 op_sel_hi:[1,0]
	v_pk_fma_f32 v[24:25], v[56:57], v[24:25], v[72:73]
	v_pk_fma_f32 v[26:27], v[58:59], v[26:27], v[74:75]
	v_cvt_pk_bf16_f32 v24, v24, v25
	v_cvt_pk_bf16_f32 v25, v26, v27
	global_store_dwordx2 v97, v[24:25], s[100:101] offset:1024
	v_pk_mul_f32 v[28:29], v[28:29], v[106:107] op_sel_hi:[1,0]
	v_pk_mul_f32 v[30:31], v[30:31], v[106:107] op_sel_hi:[1,0]
	v_pk_mul_f32 v[28:29], v[44:45], v[28:29]
	v_pk_mul_f32 v[30:31], v[46:47], v[30:31]
	v_pk_add_f32 v[60:61], v[60:61], 1.0 op_sel_hi:[1,0]
	v_pk_add_f32 v[62:63], v[62:63], 1.0 op_sel_hi:[1,0]
	v_pk_fma_f32 v[28:29], v[60:61], v[28:29], v[76:77]
	v_pk_fma_f32 v[30:31], v[62:63], v[30:31], v[78:79]
	v_cvt_pk_bf16_f32 v28, v28, v29
	v_cvt_pk_bf16_f32 v29, v30, v31
	global_store_dwordx2 v97, v[28:29], s[100:101] offset:1536
	s_add_u32 s98, s98, 0x800
	s_sub_u32 s99, s98, 0x2000
	s_lshr_b32 s99, s99, 11
	s_add_u32 s99, s99, 1
	s_cmp_lt_u32 s98, 0x2000
	s_cmov_b32 s99, 0
	s_mul_i32 s99, s99, 0x6000
	s_add_u32 s99, s99, 0x3453000
	s_add_u32 s100, s90, s99
	s_addc_u32 s101, s91, 0
	global_load_dwordx4 v[48:51], v96, s[100:101] offset:0
	global_load_dwordx4 v[52:55], v96, s[100:101] offset:1024
	global_load_dwordx4 v[56:59], v96, s[100:101] offset:2048
	global_load_dwordx4 v[60:63], v96, s[100:101] offset:3072
	s_sub_u32 s99, s98, 0x2000
	s_lshr_b32 s99, s99, 11
	s_add_u32 s99, s99, 1
	s_cmp_lt_u32 s98, 0x2000
	s_cmov_b32 s99, 0
	s_mul_i32 s99, s99, 0x6000
	s_add_u32 s99, s99, 0x3452000
	s_add_u32 s100, s90, s99
	s_addc_u32 s101, s91, 0
	global_load_dwordx4 v[64:67], v96, s[100:101] offset:0
	global_load_dwordx4 v[68:71], v96, s[100:101] offset:1024
	global_load_dwordx4 v[72:75], v96, s[100:101] offset:2048
	global_load_dwordx4 v[76:79], v96, s[100:101] offset:3072
	s_add_u32 s98, s98, 0x800
	s_lshl_b32 s99, s98, 12
	s_add_u32 s100, s88, s99
	s_addc_u32 s101, s89, 0
	global_load_dwordx4 v[16:19], v96, s[100:101] offset:0
	global_load_dwordx4 v[20:23], v96, s[100:101] offset:1024
	global_load_dwordx4 v[24:27], v96, s[100:101] offset:2048
	global_load_dwordx4 v[28:31], v96, s[100:101] offset:3072
	s_sub_u32 s98, s98, 0x800
	s_waitcnt vmcnt(16)
	v_mul_f32_e32 v80, v1, v1
	v_mul_f32_e32 v81, v5, v5
	v_mul_f32_e32 v82, v9, v9
	v_mul_f32_e32 v83, v13, v13
	v_fmac_f32_e32 v80, v0, v0
	v_fmac_f32_e32 v81, v4, v4
	v_fmac_f32_e32 v82, v8, v8
	v_fmac_f32_e32 v83, v12, v12
	v_fmac_f32_e32 v80, v2, v2
	v_fmac_f32_e32 v81, v6, v6
	v_fmac_f32_e32 v82, v10, v10
	v_fmac_f32_e32 v83, v14, v14
	v_fmac_f32_e32 v80, v3, v3
	v_fmac_f32_e32 v81, v7, v7
	v_fmac_f32_e32 v82, v11, v11
	v_fmac_f32_e32 v83, v15, v15
	v_add_f32_e32 v84, v80, v81
	v_add_f32_e32 v84, v84, v82
	v_add_f32_e32 v84, v84, v83
	v_mov_b32_e32 v85, v84
	s_nop 1
	v_permlane32_swap_b32_e32 v84, v85
	s_nop 1
	v_add_f32_e32 v84, v84, v85
	v_mov_b32_e32 v85, v84
	s_nop 1
	v_permlane16_swap_b32_e32 v84, v85
	s_nop 1
	v_add_f32_e32 v84, v84, v85
	s_nop 1
	v_add_f32_dpp v84, v84, v84 row_mirror row_mask:0xf bank_mask:0xf
	s_nop 1
	v_add_f32_dpp v84, v84, v84 row_half_mirror row_mask:0xf bank_mask:0xf
	s_nop 1
	v_add_f32_dpp v84, v84, v84 quad_perm:[2,3,0,1] row_mask:0xf bank_mask:0xf
	s_nop 1
	v_add_f32_dpp v84, v84, v84 quad_perm:[1,0,3,2] row_mask:0xf bank_mask:0xf
	s_nop 1
	v_fmamk_f32 v84, v84, 0x3a800000, v104
	v_mul_f32_e32 v85, 0x4b800000, v84
	v_cmp_gt_f32_e32 vcc, 0x800000, v84
	s_nop 1
	v_cndmask_b32_e32 v84, v84, v85, vcc
	v_rsq_f32_e32 v84, v84
	s_nop 0
	v_mul_f32_e32 v85, 0x45800000, v84
	v_cndmask_b32_e32 v106, v84, v85, vcc
	s_waitcnt vmcnt(4)
	s_lshl_b32 s99, s98, 11
	s_add_u32 s99, s99, 0xb171900
	s_add_u32 s100, s90, s99
	s_addc_u32 s101, s91, 0
	v_pk_mul_f32 v[0:1], v[0:1], v[106:107] op_sel_hi:[1,0]
	v_pk_mul_f32 v[2:3], v[2:3], v[106:107] op_sel_hi:[1,0]
	v_pk_mul_f32 v[0:1], v[32:33], v[0:1]
	v_pk_mul_f32 v[2:3], v[34:35], v[2:3]
	v_pk_add_f32 v[48:49], v[48:49], 1.0 op_sel_hi:[1,0]
	v_pk_add_f32 v[50:51], v[50:51], 1.0 op_sel_hi:[1,0]
	v_pk_fma_f32 v[0:1], v[48:49], v[0:1], v[64:65]
	v_pk_fma_f32 v[2:3], v[50:51], v[2:3], v[66:67]
	v_cvt_pk_bf16_f32 v0, v0, v1
	v_cvt_pk_bf16_f32 v1, v2, v3
	global_store_dwordx2 v97, v[0:1], s[100:101] offset:0
	v_pk_mul_f32 v[4:5], v[4:5], v[106:107] op_sel_hi:[1,0]
	v_pk_mul_f32 v[6:7], v[6:7], v[106:107] op_sel_hi:[1,0]
	v_pk_mul_f32 v[4:5], v[36:37], v[4:5]
	v_pk_mul_f32 v[6:7], v[38:39], v[6:7]
	v_pk_add_f32 v[52:53], v[52:53], 1.0 op_sel_hi:[1,0]
	v_pk_add_f32 v[54:55], v[54:55], 1.0 op_sel_hi:[1,0]
	v_pk_fma_f32 v[4:5], v[52:53], v[4:5], v[68:69]
	v_pk_fma_f32 v[6:7], v[54:55], v[6:7], v[70:71]
	v_cvt_pk_bf16_f32 v4, v4, v5
	v_cvt_pk_bf16_f32 v5, v6, v7
	global_store_dwordx2 v97, v[4:5], s[100:101] offset:512
	v_pk_mul_f32 v[8:9], v[8:9], v[106:107] op_sel_hi:[1,0]
	v_pk_mul_f32 v[10:11], v[10:11], v[106:107] op_sel_hi:[1,0]
	v_pk_mul_f32 v[8:9], v[40:41], v[8:9]
	v_pk_mul_f32 v[10:11], v[42:43], v[10:11]
	v_pk_add_f32 v[56:57], v[56:57], 1.0 op_sel_hi:[1,0]
	v_pk_add_f32 v[58:59], v[58:59], 1.0 op_sel_hi:[1,0]
	v_pk_fma_f32 v[8:9], v[56:57], v[8:9], v[72:73]
	v_pk_fma_f32 v[10:11], v[58:59], v[10:11], v[74:75]
	v_cvt_pk_bf16_f32 v8, v8, v9
	v_cvt_pk_bf16_f32 v9, v10, v11
	global_store_dwordx2 v97, v[8:9], s[100:101] offset:1024
	v_pk_mul_f32 v[12:13], v[12:13], v[106:107] op_sel_hi:[1,0]
	v_pk_mul_f32 v[14:15], v[14:15], v[106:107] op_sel_hi:[1,0]
	v_pk_mul_f32 v[12:13], v[44:45], v[12:13]
	v_pk_mul_f32 v[14:15], v[46:47], v[14:15]
	v_pk_add_f32 v[60:61], v[60:61], 1.0 op_sel_hi:[1,0]
	v_pk_add_f32 v[62:63], v[62:63], 1.0 op_sel_hi:[1,0]
	v_pk_fma_f32 v[12:13], v[60:61], v[12:13], v[76:77]
	v_pk_fma_f32 v[14:15], v[62:63], v[14:15], v[78:79]
	v_cvt_pk_bf16_f32 v12, v12, v13
	v_cvt_pk_bf16_f32 v13, v14, v15
	global_store_dwordx2 v97, v[12:13], s[100:101] offset:1536
	s_add_u32 s98, s98, 0x800
	s_sub_u32 s99, s98, 0x2000
	s_lshr_b32 s99, s99, 11
	s_add_u32 s99, s99, 1
	s_cmp_lt_u32 s98, 0x2000
	s_cmov_b32 s99, 0
	s_mul_i32 s99, s99, 0x6000
	s_add_u32 s99, s99, 0x3453000
	s_add_u32 s100, s90, s99
	s_addc_u32 s101, s91, 0
	global_load_dwordx4 v[48:51], v96, s[100:101] offset:0
	global_load_dwordx4 v[52:55], v96, s[100:101] offset:1024
	global_load_dwordx4 v[56:59], v96, s[100:101] offset:2048
	global_load_dwordx4 v[60:63], v96, s[100:101] offset:3072
	s_sub_u32 s99, s98, 0x2000
	s_lshr_b32 s99, s99, 11
	s_add_u32 s99, s99, 1
	s_cmp_lt_u32 s98, 0x2000
	s_cmov_b32 s99, 0
	s_mul_i32 s99, s99, 0x6000
	s_add_u32 s99, s99, 0x3452000
	s_add_u32 s100, s90, s99
	s_addc_u32 s101, s91, 0
	global_load_dwordx4 v[64:67], v96, s[100:101] offset:0
	global_load_dwordx4 v[68:71], v96, s[100:101] offset:1024
	global_load_dwordx4 v[72:75], v96, s[100:101] offset:2048
	global_load_dwordx4 v[76:79], v96, s[100:101] offset:3072
	s_waitcnt vmcnt(12)
	v_mul_f32_e32 v80, v17, v17
	v_mul_f32_e32 v81, v21, v21
	v_mul_f32_e32 v82, v25, v25
	v_mul_f32_e32 v83, v29, v29
	v_fmac_f32_e32 v80, v16, v16
	v_fmac_f32_e32 v81, v20, v20
	v_fmac_f32_e32 v82, v24, v24
	v_fmac_f32_e32 v83, v28, v28
	v_fmac_f32_e32 v80, v18, v18
	v_fmac_f32_e32 v81, v22, v22
	v_fmac_f32_e32 v82, v26, v26
	v_fmac_f32_e32 v83, v30, v30
	v_fmac_f32_e32 v80, v19, v19
	v_fmac_f32_e32 v81, v23, v23
	v_fmac_f32_e32 v82, v27, v27
	v_fmac_f32_e32 v83, v31, v31
	v_add_f32_e32 v84, v80, v81
	v_add_f32_e32 v84, v84, v82
	v_add_f32_e32 v84, v84, v83
	v_mov_b32_e32 v85, v84
	s_nop 1
	v_permlane32_swap_b32_e32 v84, v85
	s_nop 1
	v_add_f32_e32 v84, v84, v85
	v_mov_b32_e32 v85, v84
	s_nop 1
	v_permlane16_swap_b32_e32 v84, v85
	s_nop 1
	v_add_f32_e32 v84, v84, v85
	s_nop 1
	v_add_f32_dpp v84, v84, v84 row_mirror row_mask:0xf bank_mask:0xf
	s_nop 1
	v_add_f32_dpp v84, v84, v84 row_half_mirror row_mask:0xf bank_mask:0xf
	s_nop 1
	v_add_f32_dpp v84, v84, v84 quad_perm:[2,3,0,1] row_mask:0xf bank_mask:0xf
	s_nop 1
	v_add_f32_dpp v84, v84, v84 quad_perm:[1,0,3,2] row_mask:0xf bank_mask:0xf
	s_nop 1
	v_fmamk_f32 v84, v84, 0x3a800000, v104
	v_mul_f32_e32 v85, 0x4b800000, v84
	v_cmp_gt_f32_e32 vcc, 0x800000, v84
	s_nop 1
	v_cndmask_b32_e32 v84, v84, v85, vcc
	v_rsq_f32_e32 v84, v84
	s_nop 0
	v_mul_f32_e32 v85, 0x45800000, v84
	v_cndmask_b32_e32 v106, v84, v85, vcc
	s_waitcnt vmcnt(0)
	s_lshl_b32 s99, s98, 11
	s_add_u32 s99, s99, 0xb171900
	s_add_u32 s100, s90, s99
	s_addc_u32 s101, s91, 0
	v_pk_mul_f32 v[16:17], v[16:17], v[106:107] op_sel_hi:[1,0]
	v_pk_mul_f32 v[18:19], v[18:19], v[106:107] op_sel_hi:[1,0]
	v_pk_mul_f32 v[16:17], v[32:33], v[16:17]
	v_pk_mul_f32 v[18:19], v[34:35], v[18:19]
	v_pk_add_f32 v[48:49], v[48:49], 1.0 op_sel_hi:[1,0]
	v_pk_add_f32 v[50:51], v[50:51], 1.0 op_sel_hi:[1,0]
	v_pk_fma_f32 v[16:17], v[48:49], v[16:17], v[64:65]
	v_pk_fma_f32 v[18:19], v[50:51], v[18:19], v[66:67]
	v_cvt_pk_bf16_f32 v16, v16, v17
	v_cvt_pk_bf16_f32 v17, v18, v19
	global_store_dwordx2 v97, v[16:17], s[100:101] offset:0
	v_pk_mul_f32 v[20:21], v[20:21], v[106:107] op_sel_hi:[1,0]
	v_pk_mul_f32 v[22:23], v[22:23], v[106:107] op_sel_hi:[1,0]
	v_pk_mul_f32 v[20:21], v[36:37], v[20:21]
	v_pk_mul_f32 v[22:23], v[38:39], v[22:23]
	v_pk_add_f32 v[52:53], v[52:53], 1.0 op_sel_hi:[1,0]
	v_pk_add_f32 v[54:55], v[54:55], 1.0 op_sel_hi:[1,0]
	v_pk_fma_f32 v[20:21], v[52:53], v[20:21], v[68:69]
	v_pk_fma_f32 v[22:23], v[54:55], v[22:23], v[70:71]
	v_cvt_pk_bf16_f32 v20, v20, v21
	v_cvt_pk_bf16_f32 v21, v22, v23
	global_store_dwordx2 v97, v[20:21], s[100:101] offset:512
	v_pk_mul_f32 v[24:25], v[24:25], v[106:107] op_sel_hi:[1,0]
	v_pk_mul_f32 v[26:27], v[26:27], v[106:107] op_sel_hi:[1,0]
	v_pk_mul_f32 v[24:25], v[40:41], v[24:25]
	v_pk_mul_f32 v[26:27], v[42:43], v[26:27]
	v_pk_add_f32 v[56:57], v[56:57], 1.0 op_sel_hi:[1,0]
	v_pk_add_f32 v[58:59], v[58:59], 1.0 op_sel_hi:[1,0]
	v_pk_fma_f32 v[24:25], v[56:57], v[24:25], v[72:73]
	v_pk_fma_f32 v[26:27], v[58:59], v[26:27], v[74:75]
	v_cvt_pk_bf16_f32 v24, v24, v25
	v_cvt_pk_bf16_f32 v25, v26, v27
	global_store_dwordx2 v97, v[24:25], s[100:101] offset:1024
	v_pk_mul_f32 v[28:29], v[28:29], v[106:107] op_sel_hi:[1,0]
	v_pk_mul_f32 v[30:31], v[30:31], v[106:107] op_sel_hi:[1,0]
	v_pk_mul_f32 v[28:29], v[44:45], v[28:29]
	v_pk_mul_f32 v[30:31], v[46:47], v[30:31]
	v_pk_add_f32 v[60:61], v[60:61], 1.0 op_sel_hi:[1,0]
	v_pk_add_f32 v[62:63], v[62:63], 1.0 op_sel_hi:[1,0]
	v_pk_fma_f32 v[28:29], v[60:61], v[28:29], v[76:77]
	v_pk_fma_f32 v[30:31], v[62:63], v[30:31], v[78:79]
	v_cvt_pk_bf16_f32 v28, v28, v29
	v_cvt_pk_bf16_f32 v29, v30, v31
	global_store_dwordx2 v97, v[28:29], s[100:101] offset:1536

.LBB0_2222:
	s_or_b64 exec, exec, s[0:1]
	s_waitcnt lgkmcnt(0)
	s_barrier
	s_and_saveexec_b64 s[4:5], s[78:79]
	s_cbranch_execz .LBB0_2229
	v_mbcnt_hi_u32_b32 v0, -1, v182
	v_and_b32_e32 v2, 64, v0
	v_add_u32_e32 v2, 64, v2
	v_xor_b32_e32 v3, 32, v0
	v_cmp_lt_i32_e32 vcc, v3, v2
	v_readlane_b32 s36, v250, 3
	v_readlane_b32 s46, v250, 13
	v_cndmask_b32_e32 v3, v0, v3, vcc
	v_lshlrev_b32_e32 v24, 2, v3
	v_xor_b32_e32 v3, 16, v0
	v_cmp_lt_i32_e32 vcc, v3, v2
	v_readlane_b32 s47, v250, 14
	s_mov_b64 s[10:11], s[46:47]
	v_cndmask_b32_e32 v3, v0, v3, vcc
	v_lshlrev_b32_e32 v25, 2, v3
	v_xor_b32_e32 v3, 8, v0
	v_cmp_lt_i32_e32 vcc, v3, v2
	s_add_u32 s0, s10, 0x1000
	v_and_b32_e32 v12, 0xfc, v149
	v_cndmask_b32_e32 v3, v0, v3, vcc
	v_lshlrev_b32_e32 v26, 2, v3
	v_xor_b32_e32 v3, 4, v0
	v_cmp_lt_i32_e32 vcc, v3, v2
	s_addc_u32 s1, s11, 0
	v_mov_b32_e32 v1, 0
	v_cndmask_b32_e32 v3, v0, v3, vcc
	v_lshlrev_b32_e32 v27, 2, v3
	v_xor_b32_e32 v3, 2, v0
	v_cmp_lt_i32_e32 vcc, v3, v2
	v_or_b32_e32 v14, 0x100, v12
	v_or_b32_e32 v16, 0x200, v12
	v_cndmask_b32_e32 v3, v0, v3, vcc
	v_lshlrev_b32_e32 v28, 2, v3
	v_xor_b32_e32 v3, 1, v0
	v_cmp_lt_i32_e32 vcc, v3, v2
	s_waitcnt vmcnt(1)
	v_or_b32_e32 v18, 0x300, v12
	s_lshl_b32 s12, s92, 2
	v_cndmask_b32_e32 v0, v0, v3, vcc
	v_lshlrev_b32_e32 v29, 2, v0
	v_lshlrev_b32_e32 v0, 2, v12
	v_lshl_add_u64 v[2:3], s[0:1], 0, v[0:1]
	v_lshlrev_b32_e32 v0, 2, v14
	v_lshl_add_u64 v[4:5], s[0:1], 0, v[0:1]
	v_lshlrev_b32_e32 v0, 2, v16
	v_lshl_add_u64 v[6:7], s[0:1], 0, v[0:1]
	v_lshlrev_b32_e32 v0, 2, v18
	v_lshl_add_u64 v[8:9], s[0:1], 0, v[0:1]
	v_readlane_b32 s0, v250, 19
	v_lshlrev_b32_e32 v0, 1, v12
	v_readlane_b32 s1, v250, 20
	s_mov_b64 s[6:7], 0
	s_movk_i32 s13, 0x2000
	v_lshl_add_u64 v[10:11], s[0:1], 0, v[0:1]
	s_movk_i32 s14, 0x1fff
	v_lshlrev_b32_e32 v12, 2, v12
	v_mov_b32_e32 v13, v1
	s_movk_i32 s15, 0x1800
	s_mov_b64 s[8:9], 0x4000
	s_mov_b64 s[10:11], 0x3000
	v_lshlrev_b32_e32 v14, 2, v14
	v_mov_b32_e32 v15, v1
	v_lshlrev_b32_e32 v16, 2, v16
	v_mov_b32_e32 v17, v1
	v_lshlrev_b32_e32 v18, 2, v18
	v_mov_b32_e32 v19, v1
	v_mov_b32_e32 v30, 0x358637bd
	s_mov_b32 s16, 0x800000
	s_movk_i32 s17, 0x2fff
	s_waitcnt vmcnt(0)
	v_mov_b32_e32 v20, v148
	v_readlane_b32 s37, v250, 4
	v_readlane_b32 s38, v250, 5
	v_readlane_b32 s39, v250, 6
	v_readlane_b32 s40, v250, 7
	v_readlane_b32 s41, v250, 8
	v_readlane_b32 s42, v250, 9
	v_readlane_b32 s43, v250, 10
	v_readlane_b32 s44, v250, 11
	v_readlane_b32 s45, v250, 12
	v_readlane_b32 s48, v250, 15
	v_readlane_b32 s49, v250, 16
	v_readlane_b32 s50, v250, 17
	v_readlane_b32 s51, v250, 18
	v_mbcnt_lo_u32_b32 v80, -1, 0
	v_mbcnt_hi_u32_b32 v80, -1, v80
	v_lshlrev_b32_e32 v96, 4, v80
	v_lshlrev_b32_e32 v97, 3, v80
	v_xor_b32_e32 v98, 32, v80
	v_lshlrev_b32_e32 v98, 2, v98
	v_xor_b32_e32 v99, 16, v80
	v_lshlrev_b32_e32 v99, 2, v99
	v_xor_b32_e32 v100, 8, v80
	v_lshlrev_b32_e32 v100, 2, v100
	v_xor_b32_e32 v101, 4, v80
	v_lshlrev_b32_e32 v101, 2, v101
	v_xor_b32_e32 v102, 2, v80
	v_lshlrev_b32_e32 v102, 2, v102
	v_xor_b32_e32 v103, 1, v80
	v_lshlrev_b32_e32 v103, 2, v103
	v_mov_b32_e32 v104, 0x358637bd
	v_mov_b32_e32 v107, 0
	v_readlane_b32 s100, v250, 13
	v_readlane_b32 s101, v250, 14
	s_nop 5
	s_add_u32 s100, s100, 0x1000
	s_addc_u32 s101, s101, 0
	global_load_dwordx4 v[32:35], v96, s[100:101] offset:0
	global_load_dwordx4 v[36:39], v96, s[100:101] offset:1024
	global_load_dwordx4 v[40:43], v96, s[100:101] offset:2048
	global_load_dwordx4 v[44:47], v96, s[100:101] offset:3072
	v_readfirstlane_b32 s98, v148
	s_nop 3
	s_lshl_b32 s99, s98, 12
	s_add_u32 s100, s88, s99
	s_addc_u32 s101, s89, 0
	global_load_dwordx4 v[0:3], v96, s[100:101] offset:0
	global_load_dwordx4 v[4:7], v96, s[100:101] offset:1024
	global_load_dwordx4 v[8:11], v96, s[100:101] offset:2048
	global_load_dwordx4 v[12:15], v96, s[100:101] offset:3072
	s_sub_u32 s99, s98, 0x2000
	s_lshr_b32 s99, s99, 11
	s_add_u32 s99, s99, 1
	s_cmp_lt_u32 s98, 0x2000
	s_cmov_b32 s99, 0
	s_mul_i32 s99, s99, 0x6000
	s_add_u32 s99, s99, 0x3456000
	s_add_u32 s100, s90, s99
	s_addc_u32 s101, s91, 0
	global_load_dwordx4 v[48:51], v96, s[100:101] offset:0
	global_load_dwordx4 v[52:55], v96, s[100:101] offset:1024
	global_load_dwordx4 v[56:59], v96, s[100:101] offset:2048
	global_load_dwordx4 v[60:63], v96, s[100:101] offset:3072
	s_sub_u32 s99, s98, 0x2000
	s_lshr_b32 s99, s99, 11
	s_add_u32 s99, s99, 1
	s_cmp_lt_u32 s98, 0x2000
	s_cmov_b32 s99, 0
	s_mul_i32 s99, s99, 0x6000
	s_add_u32 s99, s99, 0x3455000
	s_add_u32 s100, s90, s99
	s_addc_u32 s101, s91, 0
	global_load_dwordx4 v[64:67], v96, s[100:101] offset:0
	global_load_dwordx4 v[68:71], v96, s[100:101] offset:1024
	global_load_dwordx4 v[72:75], v96, s[100:101] offset:2048
	global_load_dwordx4 v[76:79], v96, s[100:101] offset:3072
	s_add_u32 s98, s98, 0x800
	s_lshl_b32 s99, s98, 12
	s_add_u32 s100, s88, s99
	s_addc_u32 s101, s89, 0
	global_load_dwordx4 v[16:19], v96, s[100:101] offset:0
	global_load_dwordx4 v[20:23], v96, s[100:101] offset:1024
	global_load_dwordx4 v[24:27], v96, s[100:101] offset:2048
	global_load_dwordx4 v[28:31], v96, s[100:101] offset:3072
	s_sub_u32 s98, s98, 0x800
	s_waitcnt vmcnt(12)
	v_mul_f32_e32 v80, v1, v1
	v_mul_f32_e32 v81, v5, v5
	v_mul_f32_e32 v82, v9, v9
	v_mul_f32_e32 v83, v13, v13
	v_fmac_f32_e32 v80, v0, v0
	v_fmac_f32_e32 v81, v4, v4
	v_fmac_f32_e32 v82, v8, v8
	v_fmac_f32_e32 v83, v12, v12
	v_fmac_f32_e32 v80, v2, v2
	v_fmac_f32_e32 v81, v6, v6
	v_fmac_f32_e32 v82, v10, v10
	v_fmac_f32_e32 v83, v14, v14
	v_fmac_f32_e32 v80, v3, v3
	v_fmac_f32_e32 v81, v7, v7
	v_fmac_f32_e32 v82, v11, v11
	v_fmac_f32_e32 v83, v15, v15
	v_add_f32_e32 v84, v80, v81
	v_add_f32_e32 v84, v84, v82
	v_add_f32_e32 v84, v84, v83
	v_mov_b32_e32 v85, v84
	s_nop 1
	v_permlane32_swap_b32_e32 v84, v85
	s_nop 1
	v_add_f32_e32 v84, v84, v85
	v_mov_b32_e32 v85, v84
	s_nop 1
	v_permlane16_swap_b32_e32 v84, v85
	s_nop 1
	v_add_f32_e32 v84, v84, v85
	s_nop 1
	v_add_f32_dpp v84, v84, v84 row_mirror row_mask:0xf bank_mask:0xf
	s_nop 1
	v_add_f32_dpp v84, v84, v84 row_half_mirror row_mask:0xf bank_mask:0xf
	s_nop 1
	v_add_f32_dpp v84, v84, v84 quad_perm:[2,3,0,1] row_mask:0xf bank_mask:0xf
	s_nop 1
	v_add_f32_dpp v84, v84, v84 quad_perm:[1,0,3,2] row_mask:0xf bank_mask:0xf
	s_nop 1
	v_fmamk_f32 v84, v84, 0x3a800000, v104
	v_mul_f32_e32 v85, 0x4b800000, v84
	v_cmp_gt_f32_e32 vcc, 0x800000, v84
	s_nop 1
	v_cndmask_b32_e32 v84, v84, v85, vcc
	v_rsq_f32_e32 v84, v84
	s_nop 0
	v_mul_f32_e32 v85, 0x45800000, v84
	v_cndmask_b32_e32 v106, v84, v85, vcc
	s_waitcnt vmcnt(4)
	s_lshl_b32 s99, s98, 11
	s_add_u32 s99, s99, 0xb171900
	s_add_u32 s100, s90, s99
	s_addc_u32 s101, s91, 0
	v_pk_mul_f32 v[0:1], v[0:1], v[106:107] op_sel_hi:[1,0]
	v_pk_mul_f32 v[2:3], v[2:3], v[106:107] op_sel_hi:[1,0]
	v_pk_mul_f32 v[0:1], v[32:33], v[0:1]
	v_pk_mul_f32 v[2:3], v[34:35], v[2:3]
	v_pk_add_f32 v[48:49], v[48:49], 1.0 op_sel_hi:[1,0]
	v_pk_add_f32 v[50:51], v[50:51], 1.0 op_sel_hi:[1,0]
	v_pk_fma_f32 v[0:1], v[48:49], v[0:1], v[64:65]
	v_pk_fma_f32 v[2:3], v[50:51], v[2:3], v[66:67]
	v_cvt_pk_bf16_f32 v0, v0, v1
	v_cvt_pk_bf16_f32 v1, v2, v3
	global_store_dwordx2 v97, v[0:1], s[100:101] offset:0
	v_pk_mul_f32 v[4:5], v[4:5], v[106:107] op_sel_hi:[1,0]
	v_pk_mul_f32 v[6:7], v[6:7], v[106:107] op_sel_hi:[1,0]
	v_pk_mul_f32 v[4:5], v[36:37], v[4:5]
	v_pk_mul_f32 v[6:7], v[38:39], v[6:7]
	v_pk_add_f32 v[52:53], v[52:53], 1.0 op_sel_hi:[1,0]
	v_pk_add_f32 v[54:55], v[54:55], 1.0 op_sel_hi:[1,0]
	v_pk_fma_f32 v[4:5], v[52:53], v[4:5], v[68:69]
	v_pk_fma_f32 v[6:7], v[54:55], v[6:7], v[70:71]
	v_cvt_pk_bf16_f32 v4, v4, v5
	v_cvt_pk_bf16_f32 v5, v6, v7
	global_store_dwordx2 v97, v[4:5], s[100:101] offset:512
	v_pk_mul_f32 v[8:9], v[8:9], v[106:107] op_sel_hi:[1,0]
	v_pk_mul_f32 v[10:11], v[10:11], v[106:107] op_sel_hi:[1,0]
	v_pk_mul_f32 v[8:9], v[40:41], v[8:9]
	v_pk_mul_f32 v[10:11], v[42:43], v[10:11]
	v_pk_add_f32 v[56:57], v[56:57], 1.0 op_sel_hi:[1,0]
	v_pk_add_f32 v[58:59], v[58:59], 1.0 op_sel_hi:[1,0]
	v_pk_fma_f32 v[8:9], v[56:57], v[8:9], v[72:73]
	v_pk_fma_f32 v[10:11], v[58:59], v[10:11], v[74:75]
	v_cvt_pk_bf16_f32 v8, v8, v9
	v_cvt_pk_bf16_f32 v9, v10, v11
	global_store_dwordx2 v97, v[8:9], s[100:101] offset:1024
	v_pk_mul_f32 v[12:13], v[12:13], v[106:107] op_sel_hi:[1,0]
	v_pk_mul_f32 v[14:15], v[14:15], v[106:107] op_sel_hi:[1,0]
	v_pk_mul_f32 v[12:13], v[44:45], v[12:13]
	v_pk_mul_f32 v[14:15], v[46:47], v[14:15]
	v_pk_add_f32 v[60:61], v[60:61], 1.0 op_sel_hi:[1,0]
	v_pk_add_f32 v[62:63], v[62:63], 1.0 op_sel_hi:[1,0]
	v_pk_fma_f32 v[12:13], v[60:61], v[12:13], v[76:77]
	v_pk_fma_f32 v[14:15], v[62:63], v[14:15], v[78:79]
	v_cvt_pk_bf16_f32 v12, v12, v13
	v_cvt_pk_bf16_f32 v13, v14, v15
	global_store_dwordx2 v97, v[12:13], s[100:101] offset:1536
	s_add_u32 s98, s98, 0x800
	s_sub_u32 s99, s98, 0x2000
	s_lshr_b32 s99, s99, 11
	s_add_u32 s99, s99, 1
	s_cmp_lt_u32 s98, 0x2000
	s_cmov_b32 s99, 0
	s_mul_i32 s99, s99, 0x6000
	s_add_u32 s99, s99, 0x3456000
	s_add_u32 s100, s90, s99
	s_addc_u32 s101, s91, 0
	global_load_dwordx4 v[48:51], v96, s[100:101] offset:0
	global_load_dwordx4 v[52:55], v96, s[100:101] offset:1024
	global_load_dwordx4 v[56:59], v96, s[100:101] offset:2048
	global_load_dwordx4 v[60:63], v96, s[100:101] offset:3072
	s_sub_u32 s99, s98, 0x2000
	s_lshr_b32 s99, s99, 11
	s_add_u32 s99, s99, 1
	s_cmp_lt_u32 s98, 0x2000
	s_cmov_b32 s99, 0
	s_mul_i32 s99, s99, 0x6000
	s_add_u32 s99, s99, 0x3455000
	s_add_u32 s100, s90, s99
	s_addc_u32 s101, s91, 0
	global_load_dwordx4 v[64:67], v96, s[100:101] offset:0
	global_load_dwordx4 v[68:71], v96, s[100:101] offset:1024
	global_load_dwordx4 v[72:75], v96, s[100:101] offset:2048
	global_load_dwordx4 v[76:79], v96, s[100:101] offset:3072
	s_add_u32 s98, s98, 0x800
	s_lshl_b32 s99, s98, 12
	s_add_u32 s100, s88, s99
	s_addc_u32 s101, s89, 0
	global_load_dwordx4 v[0:3], v96, s[100:101] offset:0
	global_load_dwordx4 v[4:7], v96, s[100:101] offset:1024
	global_load_dwordx4 v[8:11], v96, s[100:101] offset:2048
	global_load_dwordx4 v[12:15], v96, s[100:101] offset:3072
	s_sub_u32 s98, s98, 0x800
	s_waitcnt vmcnt(16)
	v_mul_f32_e32 v80, v17, v17
	v_mul_f32_e32 v81, v21, v21
	v_mul_f32_e32 v82, v25, v25
	v_mul_f32_e32 v83, v29, v29
	v_fmac_f32_e32 v80, v16, v16
	v_fmac_f32_e32 v81, v20, v20
	v_fmac_f32_e32 v82, v24, v24
	v_fmac_f32_e32 v83, v28, v28
	v_fmac_f32_e32 v80, v18, v18
	v_fmac_f32_e32 v81, v22, v22
	v_fmac_f32_e32 v82, v26, v26
	v_fmac_f32_e32 v83, v30, v30
	v_fmac_f32_e32 v80, v19, v19
	v_fmac_f32_e32 v81, v23, v23
	v_fmac_f32_e32 v82, v27, v27
	v_fmac_f32_e32 v83, v31, v31
	v_add_f32_e32 v84, v80, v81
	v_add_f32_e32 v84, v84, v82
	v_add_f32_e32 v84, v84, v83
	v_mov_b32_e32 v85, v84
	s_nop 1
	v_permlane32_swap_b32_e32 v84, v85
	s_nop 1
	v_add_f32_e32 v84, v84, v85
	v_mov_b32_e32 v85, v84
	s_nop 1
	v_permlane16_swap_b32_e32 v84, v85
	s_nop 1
	v_add_f32_e32 v84, v84, v85
	s_nop 1
	v_add_f32_dpp v84, v84, v84 row_mirror row_mask:0xf bank_mask:0xf
	s_nop 1
	v_add_f32_dpp v84, v84, v84 row_half_mirror row_mask:0xf bank_mask:0xf
	s_nop 1
	v_add_f32_dpp v84, v84, v84 quad_perm:[2,3,0,1] row_mask:0xf bank_mask:0xf
	s_nop 1
	v_add_f32_dpp v84, v84, v84 quad_perm:[1,0,3,2] row_mask:0xf bank_mask:0xf
	s_nop 1
	v_fmamk_f32 v84, v84, 0x3a800000, v104
	v_mul_f32_e32 v85, 0x4b800000, v84
	v_cmp_gt_f32_e32 vcc, 0x800000, v84
	s_nop 1
	v_cndmask_b32_e32 v84, v84, v85, vcc
	v_rsq_f32_e32 v84, v84
	s_nop 0
	v_mul_f32_e32 v85, 0x45800000, v84
	v_cndmask_b32_e32 v106, v84, v85, vcc
	s_waitcnt vmcnt(4)
	s_lshl_b32 s99, s98, 11
	s_add_u32 s99, s99, 0xb171900
	s_add_u32 s100, s90, s99
	s_addc_u32 s101, s91, 0
	v_pk_mul_f32 v[16:17], v[16:17], v[106:107] op_sel_hi:[1,0]
	v_pk_mul_f32 v[18:19], v[18:19], v[106:107] op_sel_hi:[1,0]
	v_pk_mul_f32 v[16:17], v[32:33], v[16:17]
	v_pk_mul_f32 v[18:19], v[34:35], v[18:19]
	v_pk_add_f32 v[48:49], v[48:49], 1.0 op_sel_hi:[1,0]
	v_pk_add_f32 v[50:51], v[50:51], 1.0 op_sel_hi:[1,0]
	v_pk_fma_f32 v[16:17], v[48:49], v[16:17], v[64:65]
	v_pk_fma_f32 v[18:19], v[50:51], v[18:19], v[66:67]
	v_cvt_pk_bf16_f32 v16, v16, v17
	v_cvt_pk_bf16_f32 v17, v18, v19
	global_store_dwordx2 v97, v[16:17], s[100:101] offset:0
	v_pk_mul_f32 v[20:21], v[20:21], v[106:107] op_sel_hi:[1,0]
	v_pk_mul_f32 v[22:23], v[22:23], v[106:107] op_sel_hi:[1,0]
	v_pk_mul_f32 v[20:21], v[36:37], v[20:21]
	v_pk_mul_f32 v[22:23], v[38:39], v[22:23]
	v_pk_add_f32 v[52:53], v[52:53], 1.0 op_sel_hi:[1,0]
	v_pk_add_f32 v[54:55], v[54:55], 1.0 op_sel_hi:[1,0]
	v_pk_fma_f32 v[20:21], v[52:53], v[20:21], v[68:69]
	v_pk_fma_f32 v[22:23], v[54:55], v[22:23], v[70:71]
	v_cvt_pk_bf16_f32 v20, v20, v21
	v_cvt_pk_bf16_f32 v21, v22, v23
	global_store_dwordx2 v97, v[20:21], s[100:101] offset:512
	v_pk_mul_f32 v[24:25], v[24:25], v[106:107] op_sel_hi:[1,0]
	v_pk_mul_f32 v[26:27], v[26:27], v[106:107] op_sel_hi:[1,0]
	v_pk_mul_f32 v[24:25], v[40:41], v[24:25]
	v_pk_mul_f32 v[26:27], v[42:43], v[26:27]
	v_pk_add_f32 v[56:57], v[56:57], 1.0 op_sel_hi:[1,0]
	v_pk_add_f32 v[58:59], v[58:59], 1.0 op_sel_hi:[1,0]
	v_pk_fma_f32 v[24:25], v[56:57], v[24:25], v[72:73]
	v_pk_fma_f32 v[26:27], v[58:59], v[26:27], v[74:75]
	v_cvt_pk_bf16_f32 v24, v24, v25
	v_cvt_pk_bf16_f32 v25, v26, v27
	global_store_dwordx2 v97, v[24:25], s[100:101] offset:1024
	v_pk_mul_f32 v[28:29], v[28:29], v[106:107] op_sel_hi:[1,0]
	v_pk_mul_f32 v[30:31], v[30:31], v[106:107] op_sel_hi:[1,0]
	v_pk_mul_f32 v[28:29], v[44:45], v[28:29]
	v_pk_mul_f32 v[30:31], v[46:47], v[30:31]
	v_pk_add_f32 v[60:61], v[60:61], 1.0 op_sel_hi:[1,0]
	v_pk_add_f32 v[62:63], v[62:63], 1.0 op_sel_hi:[1,0]
	v_pk_fma_f32 v[28:29], v[60:61], v[28:29], v[76:77]
	v_pk_fma_f32 v[30:31], v[62:63], v[30:31], v[78:79]
	v_cvt_pk_bf16_f32 v28, v28, v29
	v_cvt_pk_bf16_f32 v29, v30, v31
	global_store_dwordx2 v97, v[28:29], s[100:101] offset:1536
	s_add_u32 s98, s98, 0x800
	s_sub_u32 s99, s98, 0x2000
	s_lshr_b32 s99, s99, 11
	s_add_u32 s99, s99, 1
	s_cmp_lt_u32 s98, 0x2000
	s_cmov_b32 s99, 0
	s_mul_i32 s99, s99, 0x6000
	s_add_u32 s99, s99, 0x3456000
	s_add_u32 s100, s90, s99
	s_addc_u32 s101, s91, 0
	global_load_dwordx4 v[48:51], v96, s[100:101] offset:0
	global_load_dwordx4 v[52:55], v96, s[100:101] offset:1024
	global_load_dwordx4 v[56:59], v96, s[100:101] offset:2048
	global_load_dwordx4 v[60:63], v96, s[100:101] offset:3072
	s_sub_u32 s99, s98, 0x2000
	s_lshr_b32 s99, s99, 11
	s_add_u32 s99, s99, 1
	s_cmp_lt_u32 s98, 0x2000
	s_cmov_b32 s99, 0
	s_mul_i32 s99, s99, 0x6000
	s_add_u32 s99, s99, 0x3455000
	s_add_u32 s100, s90, s99
	s_addc_u32 s101, s91, 0
	global_load_dwordx4 v[64:67], v96, s[100:101] offset:0
	global_load_dwordx4 v[68:71], v96, s[100:101] offset:1024
	global_load_dwordx4 v[72:75], v96, s[100:101] offset:2048
	global_load_dwordx4 v[76:79], v96, s[100:101] offset:3072
	s_add_u32 s98, s98, 0x800
	s_lshl_b32 s99, s98, 12
	s_add_u32 s100, s88, s99
	s_addc_u32 s101, s89, 0
	global_load_dwordx4 v[16:19], v96, s[100:101] offset:0
	global_load_dwordx4 v[20:23], v96, s[100:101] offset:1024
	global_load_dwordx4 v[24:27], v96, s[100:101] offset:2048
	global_load_dwordx4 v[28:31], v96, s[100:101] offset:3072
	s_sub_u32 s98, s98, 0x800
	s_waitcnt vmcnt(16)
	v_mul_f32_e32 v80, v1, v1
	v_mul_f32_e32 v81, v5, v5
	v_mul_f32_e32 v82, v9, v9
	v_mul_f32_e32 v83, v13, v13
	v_fmac_f32_e32 v80, v0, v0
	v_fmac_f32_e32 v81, v4, v4
	v_fmac_f32_e32 v82, v8, v8
	v_fmac_f32_e32 v83, v12, v12
	v_fmac_f32_e32 v80, v2, v2
	v_fmac_f32_e32 v81, v6, v6
	v_fmac_f32_e32 v82, v10, v10
	v_fmac_f32_e32 v83, v14, v14
	v_fmac_f32_e32 v80, v3, v3
	v_fmac_f32_e32 v81, v7, v7
	v_fmac_f32_e32 v82, v11, v11
	v_fmac_f32_e32 v83, v15, v15
	v_add_f32_e32 v84, v80, v81
	v_add_f32_e32 v84, v84, v82
	v_add_f32_e32 v84, v84, v83
	v_mov_b32_e32 v85, v84
	s_nop 1
	v_permlane32_swap_b32_e32 v84, v85
	s_nop 1
	v_add_f32_e32 v84, v84, v85
	v_mov_b32_e32 v85, v84
	s_nop 1
	v_permlane16_swap_b32_e32 v84, v85
	s_nop 1
	v_add_f32_e32 v84, v84, v85
	s_nop 1
	v_add_f32_dpp v84, v84, v84 row_mirror row_mask:0xf bank_mask:0xf
	s_nop 1
	v_add_f32_dpp v84, v84, v84 row_half_mirror row_mask:0xf bank_mask:0xf
	s_nop 1
	v_add_f32_dpp v84, v84, v84 quad_perm:[2,3,0,1] row_mask:0xf bank_mask:0xf
	s_nop 1
	v_add_f32_dpp v84, v84, v84 quad_perm:[1,0,3,2] row_mask:0xf bank_mask:0xf
	s_nop 1
	v_fmamk_f32 v84, v84, 0x3a800000, v104
	v_mul_f32_e32 v85, 0x4b800000, v84
	v_cmp_gt_f32_e32 vcc, 0x800000, v84
	s_nop 1
	v_cndmask_b32_e32 v84, v84, v85, vcc
	v_rsq_f32_e32 v84, v84
	s_nop 0
	v_mul_f32_e32 v85, 0x45800000, v84
	v_cndmask_b32_e32 v106, v84, v85, vcc
	s_waitcnt vmcnt(4)
	s_lshl_b32 s99, s98, 11
	s_add_u32 s99, s99, 0xb171900
	s_add_u32 s100, s90, s99
	s_addc_u32 s101, s91, 0
	v_pk_mul_f32 v[0:1], v[0:1], v[106:107] op_sel_hi:[1,0]
	v_pk_mul_f32 v[2:3], v[2:3], v[106:107] op_sel_hi:[1,0]
	v_pk_mul_f32 v[0:1], v[32:33], v[0:1]
	v_pk_mul_f32 v[2:3], v[34:35], v[2:3]
	v_pk_add_f32 v[48:49], v[48:49], 1.0 op_sel_hi:[1,0]
	v_pk_add_f32 v[50:51], v[50:51], 1.0 op_sel_hi:[1,0]
	v_pk_fma_f32 v[0:1], v[48:49], v[0:1], v[64:65]
	v_pk_fma_f32 v[2:3], v[50:51], v[2:3], v[66:67]
	v_cvt_pk_bf16_f32 v0, v0, v1
	v_cvt_pk_bf16_f32 v1, v2, v3
	global_store_dwordx2 v97, v[0:1], s[100:101] offset:0
	v_pk_mul_f32 v[4:5], v[4:5], v[106:107] op_sel_hi:[1,0]
	v_pk_mul_f32 v[6:7], v[6:7], v[106:107] op_sel_hi:[1,0]
	v_pk_mul_f32 v[4:5], v[36:37], v[4:5]
	v_pk_mul_f32 v[6:7], v[38:39], v[6:7]
	v_pk_add_f32 v[52:53], v[52:53], 1.0 op_sel_hi:[1,0]
	v_pk_add_f32 v[54:55], v[54:55], 1.0 op_sel_hi:[1,0]
	v_pk_fma_f32 v[4:5], v[52:53], v[4:5], v[68:69]
	v_pk_fma_f32 v[6:7], v[54:55], v[6:7], v[70:71]
	v_cvt_pk_bf16_f32 v4, v4, v5
	v_cvt_pk_bf16_f32 v5, v6, v7
	global_store_dwordx2 v97, v[4:5], s[100:101] offset:512
	v_pk_mul_f32 v[8:9], v[8:9], v[106:107] op_sel_hi:[1,0]
	v_pk_mul_f32 v[10:11], v[10:11], v[106:107] op_sel_hi:[1,0]
	v_pk_mul_f32 v[8:9], v[40:41], v[8:9]
	v_pk_mul_f32 v[10:11], v[42:43], v[10:11]
	v_pk_add_f32 v[56:57], v[56:57], 1.0 op_sel_hi:[1,0]
	v_pk_add_f32 v[58:59], v[58:59], 1.0 op_sel_hi:[1,0]
	v_pk_fma_f32 v[8:9], v[56:57], v[8:9], v[72:73]
	v_pk_fma_f32 v[10:11], v[58:59], v[10:11], v[74:75]
	v_cvt_pk_bf16_f32 v8, v8, v9
	v_cvt_pk_bf16_f32 v9, v10, v11
	global_store_dwordx2 v97, v[8:9], s[100:101] offset:1024
	v_pk_mul_f32 v[12:13], v[12:13], v[106:107] op_sel_hi:[1,0]
	v_pk_mul_f32 v[14:15], v[14:15], v[106:107] op_sel_hi:[1,0]
	v_pk_mul_f32 v[12:13], v[44:45], v[12:13]
	v_pk_mul_f32 v[14:15], v[46:47], v[14:15]
	v_pk_add_f32 v[60:61], v[60:61], 1.0 op_sel_hi:[1,0]
	v_pk_add_f32 v[62:63], v[62:63], 1.0 op_sel_hi:[1,0]
	v_pk_fma_f32 v[12:13], v[60:61], v[12:13], v[76:77]
	v_pk_fma_f32 v[14:15], v[62:63], v[14:15], v[78:79]
	v_cvt_pk_bf16_f32 v12, v12, v13
	v_cvt_pk_bf16_f32 v13, v14, v15
	global_store_dwordx2 v97, v[12:13], s[100:101] offset:1536
	s_add_u32 s98, s98, 0x800
	s_sub_u32 s99, s98, 0x2000
	s_lshr_b32 s99, s99, 11
	s_add_u32 s99, s99, 1
	s_cmp_lt_u32 s98, 0x2000
	s_cmov_b32 s99, 0
	s_mul_i32 s99, s99, 0x6000
	s_add_u32 s99, s99, 0x3456000
	s_add_u32 s100, s90, s99
	s_addc_u32 s101, s91, 0
	global_load_dwordx4 v[48:51], v96, s[100:101] offset:0
	global_load_dwordx4 v[52:55], v96, s[100:101] offset:1024
	global_load_dwordx4 v[56:59], v96, s[100:101] offset:2048
	global_load_dwordx4 v[60:63], v96, s[100:101] offset:3072
	s_sub_u32 s99, s98, 0x2000
	s_lshr_b32 s99, s99, 11
	s_add_u32 s99, s99, 1
	s_cmp_lt_u32 s98, 0x2000
	s_cmov_b32 s99, 0
	s_mul_i32 s99, s99, 0x6000
	s_add_u32 s99, s99, 0x3455000
	s_add_u32 s100, s90, s99
	s_addc_u32 s101, s91, 0
	global_load_dwordx4 v[64:67], v96, s[100:101] offset:0
	global_load_dwordx4 v[68:71], v96, s[100:101] offset:1024
	global_load_dwordx4 v[72:75], v96, s[100:101] offset:2048
	global_load_dwordx4 v[76:79], v96, s[100:101] offset:3072
	s_add_u32 s98, s98, 0x800
	s_lshl_b32 s99, s98, 12
	s_add_u32 s100, s88, s99
	s_addc_u32 s101, s89, 0
	global_load_dwordx4 v[0:3], v96, s[100:101] offset:0
	global_load_dwordx4 v[4:7], v96, s[100:101] offset:1024
	global_load_dwordx4 v[8:11], v96, s[100:101] offset:2048
	global_load_dwordx4 v[12:15], v96, s[100:101] offset:3072
	s_sub_u32 s98, s98, 0x800
	s_waitcnt vmcnt(16)
	v_mul_f32_e32 v80, v17, v17
	v_mul_f32_e32 v81, v21, v21
	v_mul_f32_e32 v82, v25, v25
	v_mul_f32_e32 v83, v29, v29
	v_fmac_f32_e32 v80, v16, v16
	v_fmac_f32_e32 v81, v20, v20
	v_fmac_f32_e32 v82, v24, v24
	v_fmac_f32_e32 v83, v28, v28
	v_fmac_f32_e32 v80, v18, v18
	v_fmac_f32_e32 v81, v22, v22
	v_fmac_f32_e32 v82, v26, v26
	v_fmac_f32_e32 v83, v30, v30
	v_fmac_f32_e32 v80, v19, v19
	v_fmac_f32_e32 v81, v23, v23
	v_fmac_f32_e32 v82, v27, v27
	v_fmac_f32_e32 v83, v31, v31
	v_add_f32_e32 v84, v80, v81
	v_add_f32_e32 v84, v84, v82
	v_add_f32_e32 v84, v84, v83
	v_mov_b32_e32 v85, v84
	s_nop 1
	v_permlane32_swap_b32_e32 v84, v85
	s_nop 1
	v_add_f32_e32 v84, v84, v85
	v_mov_b32_e32 v85, v84
	s_nop 1
	v_permlane16_swap_b32_e32 v84, v85
	s_nop 1
	v_add_f32_e32 v84, v84, v85
	s_nop 1
	v_add_f32_dpp v84, v84, v84 row_mirror row_mask:0xf bank_mask:0xf
	s_nop 1
	v_add_f32_dpp v84, v84, v84 row_half_mirror row_mask:0xf bank_mask:0xf
	s_nop 1
	v_add_f32_dpp v84, v84, v84 quad_perm:[2,3,0,1] row_mask:0xf bank_mask:0xf
	s_nop 1
	v_add_f32_dpp v84, v84, v84 quad_perm:[1,0,3,2] row_mask:0xf bank_mask:0xf
	s_nop 1
	v_fmamk_f32 v84, v84, 0x3a800000, v104
	v_mul_f32_e32 v85, 0x4b800000, v84
	v_cmp_gt_f32_e32 vcc, 0x800000, v84
	s_nop 1
	v_cndmask_b32_e32 v84, v84, v85, vcc
	v_rsq_f32_e32 v84, v84
	s_nop 0
	v_mul_f32_e32 v85, 0x45800000, v84
	v_cndmask_b32_e32 v106, v84, v85, vcc
	s_waitcnt vmcnt(4)
	s_lshl_b32 s99, s98, 11
	s_add_u32 s99, s99, 0xb171900
	s_add_u32 s100, s90, s99
	s_addc_u32 s101, s91, 0
	v_pk_mul_f32 v[16:17], v[16:17], v[106:107] op_sel_hi:[1,0]
	v_pk_mul_f32 v[18:19], v[18:19], v[106:107] op_sel_hi:[1,0]
	v_pk_mul_f32 v[16:17], v[32:33], v[16:17]
	v_pk_mul_f32 v[18:19], v[34:35], v[18:19]
	v_pk_add_f32 v[48:49], v[48:49], 1.0 op_sel_hi:[1,0]
	v_pk_add_f32 v[50:51], v[50:51], 1.0 op_sel_hi:[1,0]
	v_pk_fma_f32 v[16:17], v[48:49], v[16:17], v[64:65]
	v_pk_fma_f32 v[18:19], v[50:51], v[18:19], v[66:67]
	v_cvt_pk_bf16_f32 v16, v16, v17
	v_cvt_pk_bf16_f32 v17, v18, v19
	global_store_dwordx2 v97, v[16:17], s[100:101] offset:0
	v_pk_mul_f32 v[20:21], v[20:21], v[106:107] op_sel_hi:[1,0]
	v_pk_mul_f32 v[22:23], v[22:23], v[106:107] op_sel_hi:[1,0]
	v_pk_mul_f32 v[20:21], v[36:37], v[20:21]
	v_pk_mul_f32 v[22:23], v[38:39], v[22:23]
	v_pk_add_f32 v[52:53], v[52:53], 1.0 op_sel_hi:[1,0]
	v_pk_add_f32 v[54:55], v[54:55], 1.0 op_sel_hi:[1,0]
	v_pk_fma_f32 v[20:21], v[52:53], v[20:21], v[68:69]
	v_pk_fma_f32 v[22:23], v[54:55], v[22:23], v[70:71]
	v_cvt_pk_bf16_f32 v20, v20, v21
	v_cvt_pk_bf16_f32 v21, v22, v23
	global_store_dwordx2 v97, v[20:21], s[100:101] offset:512
	v_pk_mul_f32 v[24:25], v[24:25], v[106:107] op_sel_hi:[1,0]
	v_pk_mul_f32 v[26:27], v[26:27], v[106:107] op_sel_hi:[1,0]
	v_pk_mul_f32 v[24:25], v[40:41], v[24:25]
	v_pk_mul_f32 v[26:27], v[42:43], v[26:27]
	v_pk_add_f32 v[56:57], v[56:57], 1.0 op_sel_hi:[1,0]
	v_pk_add_f32 v[58:59], v[58:59], 1.0 op_sel_hi:[1,0]
	v_pk_fma_f32 v[24:25], v[56:57], v[24:25], v[72:73]
	v_pk_fma_f32 v[26:27], v[58:59], v[26:27], v[74:75]
	v_cvt_pk_bf16_f32 v24, v24, v25
	v_cvt_pk_bf16_f32 v25, v26, v27
	global_store_dwordx2 v97, v[24:25], s[100:101] offset:1024
	v_pk_mul_f32 v[28:29], v[28:29], v[106:107] op_sel_hi:[1,0]
	v_pk_mul_f32 v[30:31], v[30:31], v[106:107] op_sel_hi:[1,0]
	v_pk_mul_f32 v[28:29], v[44:45], v[28:29]
	v_pk_mul_f32 v[30:31], v[46:47], v[30:31]
	v_pk_add_f32 v[60:61], v[60:61], 1.0 op_sel_hi:[1,0]
	v_pk_add_f32 v[62:63], v[62:63], 1.0 op_sel_hi:[1,0]
	v_pk_fma_f32 v[28:29], v[60:61], v[28:29], v[76:77]
	v_pk_fma_f32 v[30:31], v[62:63], v[30:31], v[78:79]
	v_cvt_pk_bf16_f32 v28, v28, v29
	v_cvt_pk_bf16_f32 v29, v30, v31
	global_store_dwordx2 v97, v[28:29], s[100:101] offset:1536
	s_add_u32 s98, s98, 0x800
	s_sub_u32 s99, s98, 0x2000
	s_lshr_b32 s99, s99, 11
	s_add_u32 s99, s99, 1
	s_cmp_lt_u32 s98, 0x2000
	s_cmov_b32 s99, 0
	s_mul_i32 s99, s99, 0x6000
	s_add_u32 s99, s99, 0x3456000
	s_add_u32 s100, s90, s99
	s_addc_u32 s101, s91, 0
	global_load_dwordx4 v[48:51], v96, s[100:101] offset:0
	global_load_dwordx4 v[52:55], v96, s[100:101] offset:1024
	global_load_dwordx4 v[56:59], v96, s[100:101] offset:2048
	global_load_dwordx4 v[60:63], v96, s[100:101] offset:3072
	s_sub_u32 s99, s98, 0x2000
	s_lshr_b32 s99, s99, 11
	s_add_u32 s99, s99, 1
	s_cmp_lt_u32 s98, 0x2000
	s_cmov_b32 s99, 0
	s_mul_i32 s99, s99, 0x6000
	s_add_u32 s99, s99, 0x3455000
	s_add_u32 s100, s90, s99
	s_addc_u32 s101, s91, 0
	global_load_dwordx4 v[64:67], v96, s[100:101] offset:0
	global_load_dwordx4 v[68:71], v96, s[100:101] offset:1024
	global_load_dwordx4 v[72:75], v96, s[100:101] offset:2048
	global_load_dwordx4 v[76:79], v96, s[100:101] offset:3072
	s_add_u32 s98, s98, 0x800
	s_lshl_b32 s99, s98, 12
	s_add_u32 s100, s88, s99
	s_addc_u32 s101, s89, 0
	global_load_dwordx4 v[16:19], v96, s[100:101] offset:0
	global_load_dwordx4 v[20:23], v96, s[100:101] offset:1024
	global_load_dwordx4 v[24:27], v96, s[100:101] offset:2048
	global_load_dwordx4 v[28:31], v96, s[100:101] offset:3072
	s_sub_u32 s98, s98, 0x800
	s_waitcnt vmcnt(16)
	v_mul_f32_e32 v80, v1, v1
	v_mul_f32_e32 v81, v5, v5
	v_mul_f32_e32 v82, v9, v9
	v_mul_f32_e32 v83, v13, v13
	v_fmac_f32_e32 v80, v0, v0
	v_fmac_f32_e32 v81, v4, v4
	v_fmac_f32_e32 v82, v8, v8
	v_fmac_f32_e32 v83, v12, v12
	v_fmac_f32_e32 v80, v2, v2
	v_fmac_f32_e32 v81, v6, v6
	v_fmac_f32_e32 v82, v10, v10
	v_fmac_f32_e32 v83, v14, v14
	v_fmac_f32_e32 v80, v3, v3
	v_fmac_f32_e32 v81, v7, v7
	v_fmac_f32_e32 v82, v11, v11
	v_fmac_f32_e32 v83, v15, v15
	v_add_f32_e32 v84, v80, v81
	v_add_f32_e32 v84, v84, v82
	v_add_f32_e32 v84, v84, v83
	v_mov_b32_e32 v85, v84
	s_nop 1
	v_permlane32_swap_b32_e32 v84, v85
	s_nop 1
	v_add_f32_e32 v84, v84, v85
	v_mov_b32_e32 v85, v84
	s_nop 1
	v_permlane16_swap_b32_e32 v84, v85
	s_nop 1
	v_add_f32_e32 v84, v84, v85
	s_nop 1
	v_add_f32_dpp v84, v84, v84 row_mirror row_mask:0xf bank_mask:0xf
	s_nop 1
	v_add_f32_dpp v84, v84, v84 row_half_mirror row_mask:0xf bank_mask:0xf
	s_nop 1
	v_add_f32_dpp v84, v84, v84 quad_perm:[2,3,0,1] row_mask:0xf bank_mask:0xf
	s_nop 1
	v_add_f32_dpp v84, v84, v84 quad_perm:[1,0,3,2] row_mask:0xf bank_mask:0xf
	s_nop 1
	v_fmamk_f32 v84, v84, 0x3a800000, v104
	v_mul_f32_e32 v85, 0x4b800000, v84
	v_cmp_gt_f32_e32 vcc, 0x800000, v84
	s_nop 1
	v_cndmask_b32_e32 v84, v84, v85, vcc
	v_rsq_f32_e32 v84, v84
	s_nop 0
	v_mul_f32_e32 v85, 0x45800000, v84
	v_cndmask_b32_e32 v106, v84, v85, vcc
	s_waitcnt vmcnt(4)
	s_lshl_b32 s99, s98, 11
	s_add_u32 s99, s99, 0xb171900
	s_add_u32 s100, s90, s99
	s_addc_u32 s101, s91, 0
	v_pk_mul_f32 v[0:1], v[0:1], v[106:107] op_sel_hi:[1,0]
	v_pk_mul_f32 v[2:3], v[2:3], v[106:107] op_sel_hi:[1,0]
	v_pk_mul_f32 v[0:1], v[32:33], v[0:1]
	v_pk_mul_f32 v[2:3], v[34:35], v[2:3]
	v_pk_add_f32 v[48:49], v[48:49], 1.0 op_sel_hi:[1,0]
	v_pk_add_f32 v[50:51], v[50:51], 1.0 op_sel_hi:[1,0]
	v_pk_fma_f32 v[0:1], v[48:49], v[0:1], v[64:65]
	v_pk_fma_f32 v[2:3], v[50:51], v[2:3], v[66:67]
	v_cvt_pk_bf16_f32 v0, v0, v1
	v_cvt_pk_bf16_f32 v1, v2, v3
	global_store_dwordx2 v97, v[0:1], s[100:101] offset:0
	v_pk_mul_f32 v[4:5], v[4:5], v[106:107] op_sel_hi:[1,0]
	v_pk_mul_f32 v[6:7], v[6:7], v[106:107] op_sel_hi:[1,0]
	v_pk_mul_f32 v[4:5], v[36:37], v[4:5]
	v_pk_mul_f32 v[6:7], v[38:39], v[6:7]
	v_pk_add_f32 v[52:53], v[52:53], 1.0 op_sel_hi:[1,0]
	v_pk_add_f32 v[54:55], v[54:55], 1.0 op_sel_hi:[1,0]
	v_pk_fma_f32 v[4:5], v[52:53], v[4:5], v[68:69]
	v_pk_fma_f32 v[6:7], v[54:55], v[6:7], v[70:71]
	v_cvt_pk_bf16_f32 v4, v4, v5
	v_cvt_pk_bf16_f32 v5, v6, v7
	global_store_dwordx2 v97, v[4:5], s[100:101] offset:512
	v_pk_mul_f32 v[8:9], v[8:9], v[106:107] op_sel_hi:[1,0]
	v_pk_mul_f32 v[10:11], v[10:11], v[106:107] op_sel_hi:[1,0]
	v_pk_mul_f32 v[8:9], v[40:41], v[8:9]
	v_pk_mul_f32 v[10:11], v[42:43], v[10:11]
	v_pk_add_f32 v[56:57], v[56:57], 1.0 op_sel_hi:[1,0]
	v_pk_add_f32 v[58:59], v[58:59], 1.0 op_sel_hi:[1,0]
	v_pk_fma_f32 v[8:9], v[56:57], v[8:9], v[72:73]
	v_pk_fma_f32 v[10:11], v[58:59], v[10:11], v[74:75]
	v_cvt_pk_bf16_f32 v8, v8, v9
	v_cvt_pk_bf16_f32 v9, v10, v11
	global_store_dwordx2 v97, v[8:9], s[100:101] offset:1024
	v_pk_mul_f32 v[12:13], v[12:13], v[106:107] op_sel_hi:[1,0]
	v_pk_mul_f32 v[14:15], v[14:15], v[106:107] op_sel_hi:[1,0]
	v_pk_mul_f32 v[12:13], v[44:45], v[12:13]
	v_pk_mul_f32 v[14:15], v[46:47], v[14:15]
	v_pk_add_f32 v[60:61], v[60:61], 1.0 op_sel_hi:[1,0]
	v_pk_add_f32 v[62:63], v[62:63], 1.0 op_sel_hi:[1,0]
	v_pk_fma_f32 v[12:13], v[60:61], v[12:13], v[76:77]
	v_pk_fma_f32 v[14:15], v[62:63], v[14:15], v[78:79]
	v_cvt_pk_bf16_f32 v12, v12, v13
	v_cvt_pk_bf16_f32 v13, v14, v15
	global_store_dwordx2 v97, v[12:13], s[100:101] offset:1536
	s_add_u32 s98, s98, 0x800
	s_sub_u32 s99, s98, 0x2000
	s_lshr_b32 s99, s99, 11
	s_add_u32 s99, s99, 1
	s_cmp_lt_u32 s98, 0x2000
	s_cmov_b32 s99, 0
	s_mul_i32 s99, s99, 0x6000
	s_add_u32 s99, s99, 0x3456000
	s_add_u32 s100, s90, s99
	s_addc_u32 s101, s91, 0
	global_load_dwordx4 v[48:51], v96, s[100:101] offset:0
	global_load_dwordx4 v[52:55], v96, s[100:101] offset:1024
	global_load_dwordx4 v[56:59], v96, s[100:101] offset:2048
	global_load_dwordx4 v[60:63], v96, s[100:101] offset:3072
	s_sub_u32 s99, s98, 0x2000
	s_lshr_b32 s99, s99, 11
	s_add_u32 s99, s99, 1
	s_cmp_lt_u32 s98, 0x2000
	s_cmov_b32 s99, 0
	s_mul_i32 s99, s99, 0x6000
	s_add_u32 s99, s99, 0x3455000
	s_add_u32 s100, s90, s99
	s_addc_u32 s101, s91, 0
	global_load_dwordx4 v[64:67], v96, s[100:101] offset:0
	global_load_dwordx4 v[68:71], v96, s[100:101] offset:1024
	global_load_dwordx4 v[72:75], v96, s[100:101] offset:2048
	global_load_dwordx4 v[76:79], v96, s[100:101] offset:3072
	s_waitcnt vmcnt(12)
	v_mul_f32_e32 v80, v17, v17
	v_mul_f32_e32 v81, v21, v21
	v_mul_f32_e32 v82, v25, v25
	v_mul_f32_e32 v83, v29, v29
	v_fmac_f32_e32 v80, v16, v16
	v_fmac_f32_e32 v81, v20, v20
	v_fmac_f32_e32 v82, v24, v24
	v_fmac_f32_e32 v83, v28, v28
	v_fmac_f32_e32 v80, v18, v18
	v_fmac_f32_e32 v81, v22, v22
	v_fmac_f32_e32 v82, v26, v26
	v_fmac_f32_e32 v83, v30, v30
	v_fmac_f32_e32 v80, v19, v19
	v_fmac_f32_e32 v81, v23, v23
	v_fmac_f32_e32 v82, v27, v27
	v_fmac_f32_e32 v83, v31, v31
	v_add_f32_e32 v84, v80, v81
	v_add_f32_e32 v84, v84, v82
	v_add_f32_e32 v84, v84, v83
	v_mov_b32_e32 v85, v84
	s_nop 1
	v_permlane32_swap_b32_e32 v84, v85
	s_nop 1
	v_add_f32_e32 v84, v84, v85
	v_mov_b32_e32 v85, v84
	s_nop 1
	v_permlane16_swap_b32_e32 v84, v85
	s_nop 1
	v_add_f32_e32 v84, v84, v85
	s_nop 1
	v_add_f32_dpp v84, v84, v84 row_mirror row_mask:0xf bank_mask:0xf
	s_nop 1
	v_add_f32_dpp v84, v84, v84 row_half_mirror row_mask:0xf bank_mask:0xf
	s_nop 1
	v_add_f32_dpp v84, v84, v84 quad_perm:[2,3,0,1] row_mask:0xf bank_mask:0xf
	s_nop 1
	v_add_f32_dpp v84, v84, v84 quad_perm:[1,0,3,2] row_mask:0xf bank_mask:0xf
	s_nop 1
	v_fmamk_f32 v84, v84, 0x3a800000, v104
	v_mul_f32_e32 v85, 0x4b800000, v84
	v_cmp_gt_f32_e32 vcc, 0x800000, v84
	s_nop 1
	v_cndmask_b32_e32 v84, v84, v85, vcc
	v_rsq_f32_e32 v84, v84
	s_nop 0
	v_mul_f32_e32 v85, 0x45800000, v84
	v_cndmask_b32_e32 v106, v84, v85, vcc
	s_waitcnt vmcnt(0)
	s_lshl_b32 s99, s98, 11
	s_add_u32 s99, s99, 0xb171900
	s_add_u32 s100, s90, s99
	s_addc_u32 s101, s91, 0
	v_pk_mul_f32 v[16:17], v[16:17], v[106:107] op_sel_hi:[1,0]
	v_pk_mul_f32 v[18:19], v[18:19], v[106:107] op_sel_hi:[1,0]
	v_pk_mul_f32 v[16:17], v[32:33], v[16:17]
	v_pk_mul_f32 v[18:19], v[34:35], v[18:19]
	v_pk_add_f32 v[48:49], v[48:49], 1.0 op_sel_hi:[1,0]
	v_pk_add_f32 v[50:51], v[50:51], 1.0 op_sel_hi:[1,0]
	v_pk_fma_f32 v[16:17], v[48:49], v[16:17], v[64:65]
	v_pk_fma_f32 v[18:19], v[50:51], v[18:19], v[66:67]
	v_cvt_pk_bf16_f32 v16, v16, v17
	v_cvt_pk_bf16_f32 v17, v18, v19
	global_store_dwordx2 v97, v[16:17], s[100:101] offset:0
	v_pk_mul_f32 v[20:21], v[20:21], v[106:107] op_sel_hi:[1,0]
	v_pk_mul_f32 v[22:23], v[22:23], v[106:107] op_sel_hi:[1,0]
	v_pk_mul_f32 v[20:21], v[36:37], v[20:21]
	v_pk_mul_f32 v[22:23], v[38:39], v[22:23]
	v_pk_add_f32 v[52:53], v[52:53], 1.0 op_sel_hi:[1,0]
	v_pk_add_f32 v[54:55], v[54:55], 1.0 op_sel_hi:[1,0]
	v_pk_fma_f32 v[20:21], v[52:53], v[20:21], v[68:69]
	v_pk_fma_f32 v[22:23], v[54:55], v[22:23], v[70:71]
	v_cvt_pk_bf16_f32 v20, v20, v21
	v_cvt_pk_bf16_f32 v21, v22, v23
	global_store_dwordx2 v97, v[20:21], s[100:101] offset:512
	v_pk_mul_f32 v[24:25], v[24:25], v[106:107] op_sel_hi:[1,0]
	v_pk_mul_f32 v[26:27], v[26:27], v[106:107] op_sel_hi:[1,0]
	v_pk_mul_f32 v[24:25], v[40:41], v[24:25]
	v_pk_mul_f32 v[26:27], v[42:43], v[26:27]
	v_pk_add_f32 v[56:57], v[56:57], 1.0 op_sel_hi:[1,0]
	v_pk_add_f32 v[58:59], v[58:59], 1.0 op_sel_hi:[1,0]
	v_pk_fma_f32 v[24:25], v[56:57], v[24:25], v[72:73]
	v_pk_fma_f32 v[26:27], v[58:59], v[26:27], v[74:75]
	v_cvt_pk_bf16_f32 v24, v24, v25
	v_cvt_pk_bf16_f32 v25, v26, v27
	global_store_dwordx2 v97, v[24:25], s[100:101] offset:1024
	v_pk_mul_f32 v[28:29], v[28:29], v[106:107] op_sel_hi:[1,0]
	v_pk_mul_f32 v[30:31], v[30:31], v[106:107] op_sel_hi:[1,0]
	v_pk_mul_f32 v[28:29], v[44:45], v[28:29]
	v_pk_mul_f32 v[30:31], v[46:47], v[30:31]
	v_pk_add_f32 v[60:61], v[60:61], 1.0 op_sel_hi:[1,0]
	v_pk_add_f32 v[62:63], v[62:63], 1.0 op_sel_hi:[1,0]
	v_pk_fma_f32 v[28:29], v[60:61], v[28:29], v[76:77]
	v_pk_fma_f32 v[30:31], v[62:63], v[30:31], v[78:79]
	v_cvt_pk_bf16_f32 v28, v28, v29
	v_cvt_pk_bf16_f32 v29, v30, v31
	global_store_dwordx2 v97, v[28:29], s[100:101] offset:1536
